# GEMM load segments slimmed: the two counted waits merged into one s_waitcnt, s_nop fillers between m0 write and LDS-DMA replaced by ds_reads (on top of rebalance/saddr/prio moves)
# baseline (speedup 1.0000x reference)
.LBB0_249:
	ds_read_b128 v[152:155], v146
	ds_read_b128 v[156:159], v146 offset:1024
	ds_read_b128 v[160:163], v146 offset:2048
	ds_read_b128 v[164:167], v146 offset:3072
	ds_read_b128 v[168:171], v147
	ds_read_b128 v[172:175], v147 offset:1024
	ds_read_b128 v[176:179], v147 offset:2048
	ds_read_b128 v[180:183], v147 offset:3072
	s_add_u32 s16, s70, 0xfff00080
	s_addc_u32 s17, s71, -1
	s_cmp_eq_u32 s15, 60
	s_cselect_b32 s75, s47, s17
	s_cselect_b32 s74, s93, s16
	s_cselect_b32 s67, s4, s14
	s_cselect_b32 s66, s94, s57
	s_mov_b32 m0, s78
	ds_read_b128 v[184:187], v148
	ds_read_b128 v[188:191], v148 offset:1024
	ds_read_b128 v[192:195], v148 offset:2048
	ds_read_b128 v[196:199], v148 offset:3072
	ds_read_b128 v[200:203], v148 offset:4096
	ds_read_b128 v[204:207], v148 offset:5120
	ds_read_b128 v[208:211], v148 offset:6144
	global_load_lds_dwordx4 v138, s[70:71]
	s_mov_b32 m0, s79
	ds_read_b128 v[212:215], v148 offset:7168
	global_load_lds_dwordx4 v140, s[70:71]
	s_waitcnt vmcnt(8) lgkmcnt(0)
	s_setprio 1
	s_barrier
	v_mfma_f32_16x16x32_bf16 v[122:125], v[152:155], v[184:187], v[122:125]
	v_mfma_f32_16x16x32_bf16 v[114:117], v[160:163], v[184:187], v[114:117]
	v_mfma_f32_16x16x32_bf16 v[106:109], v[152:155], v[192:195], v[106:109]
	v_mfma_f32_16x16x32_bf16 v[98:101], v[160:163], v[192:195], v[98:101]
	v_mfma_f32_16x16x32_bf16 v[90:93], v[152:155], v[200:203], v[90:93]
	v_mfma_f32_16x16x32_bf16 v[82:85], v[160:163], v[200:203], v[82:85]
	v_mfma_f32_16x16x32_bf16 v[74:77], v[152:155], v[208:211], v[74:77]
	v_mfma_f32_16x16x32_bf16 v[58:61], v[160:163], v[208:211], v[58:61]
	v_mfma_f32_16x16x32_bf16 v[122:125], v[156:159], v[188:191], v[122:125]
	v_mfma_f32_16x16x32_bf16 v[114:117], v[164:167], v[188:191], v[114:117]
	v_mfma_f32_16x16x32_bf16 v[106:109], v[156:159], v[196:199], v[106:109]
	v_mfma_f32_16x16x32_bf16 v[98:101], v[164:167], v[196:199], v[98:101]
	v_mfma_f32_16x16x32_bf16 v[90:93], v[156:159], v[204:207], v[90:93]
	v_mfma_f32_16x16x32_bf16 v[82:85], v[164:167], v[204:207], v[82:85]
	v_mfma_f32_16x16x32_bf16 v[74:77], v[156:159], v[212:215], v[74:77]
	v_mfma_f32_16x16x32_bf16 v[58:61], v[164:167], v[212:215], v[58:61]
	s_setprio 0
	s_setprio 1
	v_mfma_f32_16x16x32_bf16 v[126:129], v[168:171], v[184:187], v[126:129]
	v_mfma_f32_16x16x32_bf16 v[118:121], v[176:179], v[184:187], v[118:121]
	v_mfma_f32_16x16x32_bf16 v[110:113], v[168:171], v[192:195], v[110:113]
	v_mfma_f32_16x16x32_bf16 v[102:105], v[176:179], v[192:195], v[102:105]
	v_mfma_f32_16x16x32_bf16 v[94:97], v[168:171], v[200:203], v[94:97]
	v_mfma_f32_16x16x32_bf16 v[86:89], v[176:179], v[200:203], v[86:89]
	v_mfma_f32_16x16x32_bf16 v[78:81], v[168:171], v[208:211], v[78:81]
	v_mfma_f32_16x16x32_bf16 v[66:69], v[176:179], v[208:211], v[66:69]
	v_mfma_f32_16x16x32_bf16 v[126:129], v[172:175], v[188:191], v[126:129]
	v_mfma_f32_16x16x32_bf16 v[118:121], v[180:183], v[188:191], v[118:121]
	v_mfma_f32_16x16x32_bf16 v[110:113], v[172:175], v[196:199], v[110:113]
	v_mfma_f32_16x16x32_bf16 v[102:105], v[180:183], v[196:199], v[102:105]
	v_mfma_f32_16x16x32_bf16 v[94:97], v[172:175], v[204:207], v[94:97]
	v_mfma_f32_16x16x32_bf16 v[86:89], v[180:183], v[204:207], v[86:89]
	v_mfma_f32_16x16x32_bf16 v[78:81], v[172:175], v[212:215], v[78:81]
	v_mfma_f32_16x16x32_bf16 v[66:69], v[180:183], v[212:215], v[66:69]
	s_barrier
	s_setprio 0
	s_mov_b32 m0, s81
	s_mov_b64 s[98:99], s[66:67]
	s_add_u32 s16, s66, 0x100000
	ds_read_b128 v[184:187], v148 offset:16384
	ds_read_b128 v[188:191], v148 offset:17408
	ds_read_b128 v[192:195], v148 offset:18432
	ds_read_b128 v[196:199], v148 offset:19456
	ds_read_b128 v[200:203], v148 offset:20480
	ds_read_b128 v[204:207], v148 offset:21504
	ds_read_b128 v[208:211], v148 offset:22528
	global_load_lds_dwordx4 v134, s[66:67]
	s_mov_b32 m0, s82
	s_addc_u32 s17, s67, 0
	global_load_lds_dwordx4 v130, s[66:67]
	s_mov_b32 m0, s83
	s_mov_b64 s[100:101], s[74:75]
	global_load_lds_dwordx4 v134, s[16:17]
	s_mov_b32 m0, s86
	ds_read_b128 v[212:215], v148 offset:23552
	global_load_lds_dwordx4 v130, s[16:17]
	s_waitcnt vmcnt(6) lgkmcnt(0)
	s_setprio 1
	s_barrier
	v_mfma_f32_16x16x32_bf16 v[62:65], v[152:155], v[184:187], v[62:65]
	v_mfma_f32_16x16x32_bf16 v[50:53], v[160:163], v[184:187], v[50:53]
	v_mfma_f32_16x16x32_bf16 v[42:45], v[152:155], v[192:195], v[42:45]
	v_mfma_f32_16x16x32_bf16 v[34:37], v[160:163], v[192:195], v[34:37]
	v_mfma_f32_16x16x32_bf16 v[26:29], v[152:155], v[200:203], v[26:29]
	v_mfma_f32_16x16x32_bf16 v[18:21], v[160:163], v[200:203], v[18:21]
	v_mfma_f32_16x16x32_bf16 v[10:13], v[152:155], v[208:211], v[10:13]
	v_mfma_f32_16x16x32_bf16 v[2:5], v[160:163], v[208:211], v[2:5]
	v_mfma_f32_16x16x32_bf16 v[62:65], v[156:159], v[188:191], v[62:65]
	v_mfma_f32_16x16x32_bf16 v[50:53], v[164:167], v[188:191], v[50:53]
	v_mfma_f32_16x16x32_bf16 v[42:45], v[156:159], v[196:199], v[42:45]
	v_mfma_f32_16x16x32_bf16 v[34:37], v[164:167], v[196:199], v[34:37]
	v_mfma_f32_16x16x32_bf16 v[26:29], v[156:159], v[204:207], v[26:29]
	v_mfma_f32_16x16x32_bf16 v[18:21], v[164:167], v[204:207], v[18:21]
	v_mfma_f32_16x16x32_bf16 v[10:13], v[156:159], v[212:215], v[10:13]
	v_mfma_f32_16x16x32_bf16 v[2:5], v[164:167], v[212:215], v[2:5]
	s_setprio 0
	s_setprio 1
	v_mfma_f32_16x16x32_bf16 v[70:73], v[168:171], v[184:187], v[70:73]
	v_mfma_f32_16x16x32_bf16 v[54:57], v[176:179], v[184:187], v[54:57]
	v_mfma_f32_16x16x32_bf16 v[46:49], v[168:171], v[192:195], v[46:49]
	v_mfma_f32_16x16x32_bf16 v[38:41], v[176:179], v[192:195], v[38:41]
	v_mfma_f32_16x16x32_bf16 v[30:33], v[168:171], v[200:203], v[30:33]
	v_mfma_f32_16x16x32_bf16 v[22:25], v[176:179], v[200:203], v[22:25]
	v_mfma_f32_16x16x32_bf16 v[14:17], v[168:171], v[208:211], v[14:17]
	v_mfma_f32_16x16x32_bf16 v[6:9], v[176:179], v[208:211], v[6:9]
	v_mfma_f32_16x16x32_bf16 v[70:73], v[172:175], v[188:191], v[70:73]
	v_mfma_f32_16x16x32_bf16 v[54:57], v[180:183], v[188:191], v[54:57]
	v_mfma_f32_16x16x32_bf16 v[46:49], v[172:175], v[196:199], v[46:49]
	v_mfma_f32_16x16x32_bf16 v[38:41], v[180:183], v[196:199], v[38:41]
	v_mfma_f32_16x16x32_bf16 v[30:33], v[172:175], v[204:207], v[30:33]
	v_mfma_f32_16x16x32_bf16 v[22:25], v[180:183], v[204:207], v[22:25]
	v_mfma_f32_16x16x32_bf16 v[14:17], v[172:175], v[212:215], v[14:17]
	v_mfma_f32_16x16x32_bf16 v[6:9], v[180:183], v[212:215], v[6:9]
	s_barrier
	s_setprio 0
	ds_read_b128 v[152:155], v149
	ds_read_b128 v[156:159], v149 offset:1024
	ds_read_b128 v[160:163], v149 offset:2048
	ds_read_b128 v[164:167], v149 offset:3072
	ds_read_b128 v[168:171], v150
	ds_read_b128 v[172:175], v150 offset:1024
	s_add_u32 s16, s74, 0x100000
	s_addc_u32 s17, s75, 0
	s_mov_b32 m0, s29
	ds_read_b128 v[180:183], v150 offset:3072
	global_load_lds_dwordx4 v136, s[100:101]
	s_mov_b32 m0, s33
	ds_read_b128 v[176:179], v150 offset:2048
	global_load_lds_dwordx4 v132, s[100:101]
	s_mov_b32 m0, s58
	ds_read_b128 v[184:187], v148 offset:32768
	ds_read_b128 v[188:191], v148 offset:33792
	ds_read_b128 v[192:195], v148 offset:34816
	ds_read_b128 v[196:199], v148 offset:35840
	ds_read_b128 v[200:203], v148 offset:36864
	ds_read_b128 v[204:207], v148 offset:37888
	ds_read_b128 v[208:211], v148 offset:38912
	global_load_lds_dwordx4 v136, s[16:17]
	s_mov_b32 m0, s59
	ds_read_b128 v[212:215], v148 offset:39936
	global_load_lds_dwordx4 v132, s[16:17]
	s_waitcnt vmcnt(8) lgkmcnt(0)
	s_setprio 1
	s_barrier
	v_mfma_f32_16x16x32_bf16 v[122:125], v[152:155], v[184:187], v[122:125]
	v_mfma_f32_16x16x32_bf16 v[114:117], v[160:163], v[184:187], v[114:117]
	v_mfma_f32_16x16x32_bf16 v[106:109], v[152:155], v[192:195], v[106:109]
	v_mfma_f32_16x16x32_bf16 v[98:101], v[160:163], v[192:195], v[98:101]
	v_mfma_f32_16x16x32_bf16 v[90:93], v[152:155], v[200:203], v[90:93]
	v_mfma_f32_16x16x32_bf16 v[82:85], v[160:163], v[200:203], v[82:85]
	v_mfma_f32_16x16x32_bf16 v[74:77], v[152:155], v[208:211], v[74:77]
	v_mfma_f32_16x16x32_bf16 v[58:61], v[160:163], v[208:211], v[58:61]
	v_mfma_f32_16x16x32_bf16 v[122:125], v[156:159], v[188:191], v[122:125]
	v_mfma_f32_16x16x32_bf16 v[114:117], v[164:167], v[188:191], v[114:117]
	v_mfma_f32_16x16x32_bf16 v[106:109], v[156:159], v[196:199], v[106:109]
	v_mfma_f32_16x16x32_bf16 v[98:101], v[164:167], v[196:199], v[98:101]
	v_mfma_f32_16x16x32_bf16 v[90:93], v[156:159], v[204:207], v[90:93]
	v_mfma_f32_16x16x32_bf16 v[82:85], v[164:167], v[204:207], v[82:85]
	v_mfma_f32_16x16x32_bf16 v[74:77], v[156:159], v[212:215], v[74:77]
	v_mfma_f32_16x16x32_bf16 v[58:61], v[164:167], v[212:215], v[58:61]
	s_setprio 0
	s_setprio 1
	v_mfma_f32_16x16x32_bf16 v[126:129], v[168:171], v[184:187], v[126:129]
	v_mfma_f32_16x16x32_bf16 v[118:121], v[176:179], v[184:187], v[118:121]
	v_mfma_f32_16x16x32_bf16 v[110:113], v[168:171], v[192:195], v[110:113]
	v_mfma_f32_16x16x32_bf16 v[102:105], v[176:179], v[192:195], v[102:105]
	v_mfma_f32_16x16x32_bf16 v[94:97], v[168:171], v[200:203], v[94:97]
	v_mfma_f32_16x16x32_bf16 v[86:89], v[176:179], v[200:203], v[86:89]
	v_mfma_f32_16x16x32_bf16 v[78:81], v[168:171], v[208:211], v[78:81]
	v_mfma_f32_16x16x32_bf16 v[66:69], v[176:179], v[208:211], v[66:69]
	v_mfma_f32_16x16x32_bf16 v[126:129], v[172:175], v[188:191], v[126:129]
	v_mfma_f32_16x16x32_bf16 v[118:121], v[180:183], v[188:191], v[118:121]
	v_mfma_f32_16x16x32_bf16 v[110:113], v[172:175], v[196:199], v[110:113]
	v_mfma_f32_16x16x32_bf16 v[102:105], v[180:183], v[196:199], v[102:105]
	v_mfma_f32_16x16x32_bf16 v[94:97], v[172:175], v[204:207], v[94:97]
	v_mfma_f32_16x16x32_bf16 v[86:89], v[180:183], v[204:207], v[86:89]
	v_mfma_f32_16x16x32_bf16 v[78:81], v[172:175], v[212:215], v[78:81]
	v_mfma_f32_16x16x32_bf16 v[66:69], v[180:183], v[212:215], v[66:69]
	s_barrier
	s_setprio 0
	s_mov_b32 m0, s87
	s_add_u32 s98, s98, 0x80
	s_addc_u32 s99, s99, 0
	s_add_u32 s100, s100, 0x80
	s_addc_u32 s101, s101, 0
	s_add_u32 s16, s66, 0x100080
	ds_read_b128 v[184:187], v148 offset:49152
	ds_read_b128 v[188:191], v148 offset:50176
	ds_read_b128 v[192:195], v148 offset:51200
	ds_read_b128 v[196:199], v148 offset:52224
	global_load_lds_dwordx4 v134, s[98:99]
	s_mov_b32 m0, s88
	s_addc_u32 s17, s67, 0
	global_load_lds_dwordx4 v130, s[98:99]
	s_mov_b32 m0, s89
	ds_read_b128 v[212:215], v148 offset:56320
	global_load_lds_dwordx4 v134, s[16:17]
	s_mov_b32 m0, s56
	ds_read_b128 v[208:211], v148 offset:55296
	global_load_lds_dwordx4 v130, s[16:17]
	s_mov_b32 m0, s65
	ds_read_b128 v[204:207], v148 offset:54272
	global_load_lds_dwordx4 v136, s[100:101]
	s_mov_b32 m0, s76
	ds_read_b128 v[200:203], v148 offset:53248
	global_load_lds_dwordx4 v132, s[100:101]
	s_waitcnt vmcnt(8) lgkmcnt(0)
	s_setprio 1
	s_barrier
	v_mfma_f32_16x16x32_bf16 v[62:65], v[152:155], v[184:187], v[62:65]
	v_mfma_f32_16x16x32_bf16 v[50:53], v[160:163], v[184:187], v[50:53]
	v_mfma_f32_16x16x32_bf16 v[42:45], v[152:155], v[192:195], v[42:45]
	v_mfma_f32_16x16x32_bf16 v[34:37], v[160:163], v[192:195], v[34:37]
	v_mfma_f32_16x16x32_bf16 v[26:29], v[152:155], v[200:203], v[26:29]
	v_mfma_f32_16x16x32_bf16 v[18:21], v[160:163], v[200:203], v[18:21]
	v_mfma_f32_16x16x32_bf16 v[10:13], v[152:155], v[208:211], v[10:13]
	v_mfma_f32_16x16x32_bf16 v[2:5], v[160:163], v[208:211], v[2:5]
	v_mfma_f32_16x16x32_bf16 v[62:65], v[156:159], v[188:191], v[62:65]
	v_mfma_f32_16x16x32_bf16 v[50:53], v[164:167], v[188:191], v[50:53]
	v_mfma_f32_16x16x32_bf16 v[42:45], v[156:159], v[196:199], v[42:45]
	v_mfma_f32_16x16x32_bf16 v[34:37], v[164:167], v[196:199], v[34:37]
	v_mfma_f32_16x16x32_bf16 v[26:29], v[156:159], v[204:207], v[26:29]
	v_mfma_f32_16x16x32_bf16 v[18:21], v[164:167], v[204:207], v[18:21]
	v_mfma_f32_16x16x32_bf16 v[10:13], v[156:159], v[212:215], v[10:13]
	v_mfma_f32_16x16x32_bf16 v[2:5], v[164:167], v[212:215], v[2:5]
	s_setprio 0
	s_setprio 1
	v_mfma_f32_16x16x32_bf16 v[70:73], v[168:171], v[184:187], v[70:73]
	v_mfma_f32_16x16x32_bf16 v[54:57], v[176:179], v[184:187], v[54:57]
	v_mfma_f32_16x16x32_bf16 v[46:49], v[168:171], v[192:195], v[46:49]
	v_mfma_f32_16x16x32_bf16 v[38:41], v[176:179], v[192:195], v[38:41]
	v_mfma_f32_16x16x32_bf16 v[30:33], v[168:171], v[200:203], v[30:33]
	v_mfma_f32_16x16x32_bf16 v[22:25], v[176:179], v[200:203], v[22:25]
	v_mfma_f32_16x16x32_bf16 v[14:17], v[168:171], v[208:211], v[14:17]
	v_mfma_f32_16x16x32_bf16 v[6:9], v[176:179], v[208:211], v[6:9]
	v_mfma_f32_16x16x32_bf16 v[70:73], v[172:175], v[188:191], v[70:73]
	v_mfma_f32_16x16x32_bf16 v[54:57], v[180:183], v[188:191], v[54:57]
	v_mfma_f32_16x16x32_bf16 v[46:49], v[172:175], v[196:199], v[46:49]
	v_mfma_f32_16x16x32_bf16 v[38:41], v[180:183], v[196:199], v[38:41]
	v_mfma_f32_16x16x32_bf16 v[30:33], v[172:175], v[204:207], v[30:33]
	v_mfma_f32_16x16x32_bf16 v[22:25], v[180:183], v[204:207], v[22:25]
	v_mfma_f32_16x16x32_bf16 v[14:17], v[172:175], v[212:215], v[14:17]
	v_mfma_f32_16x16x32_bf16 v[6:9], v[180:183], v[212:215], v[6:9]
	s_barrier
	s_setprio 0
	s_add_i32 s15, s15, 2
	s_add_u32 s70, s70, 0x100
	s_addc_u32 s71, s71, 0
	s_add_u32 s57, s57, 0x100
	s_addc_u32 s14, s14, 0
	s_cmp_gt_u32 s15, 61
	s_cbranch_scc0 .LBB0_249
	s_and_b64 vcc, exec, s[12:13]
	s_cbranch_vccz .LBB0_252
	s_barrier

.LBB0_331:
	ds_read_b128 v[132:135], v207
	ds_read_b128 v[136:139], v207 offset:1024
	ds_read_b128 v[140:143], v207 offset:2048
	ds_read_b128 v[144:147], v207 offset:3072
	ds_read_b128 v[148:151], v208
	ds_read_b128 v[152:155], v208 offset:1024
	ds_read_b128 v[156:159], v208 offset:2048
	ds_read_b128 v[160:163], v208 offset:3072
	s_add_u32 s16, s66, 0x200
	s_addc_u32 s17, s67, 0
	s_cmpk_eq_i32 s15, 0xa8
	s_cselect_b32 s75, s1, s17
	s_cselect_b32 s74, s0, s16
	s_cselect_b32 s71, s65, s14
	s_cselect_b32 s70, s64, s90
	s_mov_b32 m0, s86
	ds_read_b128 v[164:167], v209
	ds_read_b128 v[168:171], v209 offset:1024
	ds_read_b128 v[172:175], v209 offset:2048
	ds_read_b128 v[194:197], v209 offset:3072
	ds_read_b128 v[198:201], v209 offset:4096
	ds_read_b128 v[202:205], v209 offset:5120
	ds_read_b128 v[210:213], v209 offset:6144
	global_load_lds_dwordx4 v186, s[66:67]
	s_mov_b32 m0, s87
	ds_read_b128 v[214:217], v209 offset:7168
	global_load_lds_dwordx4 v188, s[66:67]
	s_waitcnt vmcnt(8) lgkmcnt(0)
	s_setprio 1
	s_barrier
	v_mfma_f32_16x16x32_bf16 v[122:125], v[132:135], v[164:167], v[122:125]
	v_mfma_f32_16x16x32_bf16 v[118:121], v[140:143], v[164:167], v[118:121]
	v_mfma_f32_16x16x32_bf16 v[110:113], v[132:135], v[172:175], v[110:113]
	v_mfma_f32_16x16x32_bf16 v[106:109], v[140:143], v[172:175], v[106:109]
	v_mfma_f32_16x16x32_bf16 v[94:97], v[132:135], v[198:201], v[94:97]
	v_mfma_f32_16x16x32_bf16 v[90:93], v[140:143], v[198:201], v[90:93]
	v_mfma_f32_16x16x32_bf16 v[78:81], v[132:135], v[210:213], v[78:81]
	v_mfma_f32_16x16x32_bf16 v[74:77], v[140:143], v[210:213], v[74:77]
	v_mfma_f32_16x16x32_bf16 v[122:125], v[136:139], v[168:171], v[122:125]
	v_mfma_f32_16x16x32_bf16 v[118:121], v[144:147], v[168:171], v[118:121]
	v_mfma_f32_16x16x32_bf16 v[110:113], v[136:139], v[194:197], v[110:113]
	v_mfma_f32_16x16x32_bf16 v[106:109], v[144:147], v[194:197], v[106:109]
	v_mfma_f32_16x16x32_bf16 v[94:97], v[136:139], v[202:205], v[94:97]
	v_mfma_f32_16x16x32_bf16 v[90:93], v[144:147], v[202:205], v[90:93]
	v_mfma_f32_16x16x32_bf16 v[78:81], v[136:139], v[214:217], v[78:81]
	v_mfma_f32_16x16x32_bf16 v[74:77], v[144:147], v[214:217], v[74:77]
	s_setprio 0
	s_setprio 1
	v_mfma_f32_16x16x32_bf16 v[126:129], v[148:151], v[164:167], v[126:129]
	v_mfma_f32_16x16x32_bf16 v[114:117], v[156:159], v[164:167], v[114:117]
	v_mfma_f32_16x16x32_bf16 v[102:105], v[148:151], v[172:175], v[102:105]
	v_mfma_f32_16x16x32_bf16 v[98:101], v[156:159], v[172:175], v[98:101]
	v_mfma_f32_16x16x32_bf16 v[86:89], v[148:151], v[198:201], v[86:89]
	v_mfma_f32_16x16x32_bf16 v[82:85], v[156:159], v[198:201], v[82:85]
	v_mfma_f32_16x16x32_bf16 v[70:73], v[148:151], v[210:213], v[70:73]
	v_mfma_f32_16x16x32_bf16 v[66:69], v[156:159], v[210:213], v[66:69]
	v_mfma_f32_16x16x32_bf16 v[126:129], v[152:155], v[168:171], v[126:129]
	v_mfma_f32_16x16x32_bf16 v[114:117], v[160:163], v[168:171], v[114:117]
	v_mfma_f32_16x16x32_bf16 v[102:105], v[152:155], v[194:197], v[102:105]
	v_mfma_f32_16x16x32_bf16 v[98:101], v[160:163], v[194:197], v[98:101]
	v_mfma_f32_16x16x32_bf16 v[86:89], v[152:155], v[202:205], v[86:89]
	v_mfma_f32_16x16x32_bf16 v[82:85], v[160:163], v[202:205], v[82:85]
	v_mfma_f32_16x16x32_bf16 v[70:73], v[152:155], v[214:217], v[70:73]
	v_mfma_f32_16x16x32_bf16 v[66:69], v[160:163], v[214:217], v[66:69]
	s_barrier
	s_setprio 0
	s_mov_b32 m0, s88
	s_mov_b64 s[98:99], s[70:71]
	s_add_u32 s16, s70, 0x2b0000
	ds_read_b128 v[164:167], v209 offset:16384
	ds_read_b128 v[168:171], v209 offset:17408
	ds_read_b128 v[172:175], v209 offset:18432
	ds_read_b128 v[194:197], v209 offset:19456
	ds_read_b128 v[198:201], v209 offset:20480
	ds_read_b128 v[202:205], v209 offset:21504
	ds_read_b128 v[210:213], v209 offset:22528
	global_load_lds_dwordx4 v180, s[70:71]
	s_mov_b32 m0, s84
	s_addc_u32 s17, s71, 0
	global_load_lds_dwordx4 v184, s[70:71]
	s_mov_b32 m0, s85
	s_mov_b64 s[100:101], s[74:75]
	global_load_lds_dwordx4 v180, s[16:17]
	s_mov_b32 m0, s46
	ds_read_b128 v[214:217], v209 offset:23552
	global_load_lds_dwordx4 v184, s[16:17]
	s_waitcnt vmcnt(6) lgkmcnt(0)
	s_setprio 1
	s_barrier
	v_mfma_f32_16x16x32_bf16 v[58:61], v[132:135], v[164:167], v[58:61]
	v_mfma_f32_16x16x32_bf16 v[54:57], v[140:143], v[164:167], v[54:57]
	v_mfma_f32_16x16x32_bf16 v[46:49], v[132:135], v[172:175], v[46:49]
	v_mfma_f32_16x16x32_bf16 v[42:45], v[140:143], v[172:175], v[42:45]
	v_mfma_f32_16x16x32_bf16 v[30:33], v[132:135], v[198:201], v[30:33]
	v_mfma_f32_16x16x32_bf16 v[26:29], v[140:143], v[198:201], v[26:29]
	v_mfma_f32_16x16x32_bf16 v[14:17], v[132:135], v[210:213], v[14:17]
	v_mfma_f32_16x16x32_bf16 v[10:13], v[140:143], v[210:213], v[10:13]
	v_mfma_f32_16x16x32_bf16 v[58:61], v[136:139], v[168:171], v[58:61]
	v_mfma_f32_16x16x32_bf16 v[54:57], v[144:147], v[168:171], v[54:57]
	v_mfma_f32_16x16x32_bf16 v[46:49], v[136:139], v[194:197], v[46:49]
	v_mfma_f32_16x16x32_bf16 v[42:45], v[144:147], v[194:197], v[42:45]
	v_mfma_f32_16x16x32_bf16 v[30:33], v[136:139], v[202:205], v[30:33]
	v_mfma_f32_16x16x32_bf16 v[26:29], v[144:147], v[202:205], v[26:29]
	v_mfma_f32_16x16x32_bf16 v[14:17], v[136:139], v[214:217], v[14:17]
	v_mfma_f32_16x16x32_bf16 v[10:13], v[144:147], v[214:217], v[10:13]
	s_setprio 0
	s_setprio 1
	v_mfma_f32_16x16x32_bf16 v[62:65], v[148:151], v[164:167], v[62:65]
	v_mfma_f32_16x16x32_bf16 v[50:53], v[156:159], v[164:167], v[50:53]
	v_mfma_f32_16x16x32_bf16 v[38:41], v[148:151], v[172:175], v[38:41]
	v_mfma_f32_16x16x32_bf16 v[34:37], v[156:159], v[172:175], v[34:37]
	v_mfma_f32_16x16x32_bf16 v[22:25], v[148:151], v[198:201], v[22:25]
	v_mfma_f32_16x16x32_bf16 v[18:21], v[156:159], v[198:201], v[18:21]
	v_mfma_f32_16x16x32_bf16 v[6:9], v[148:151], v[210:213], v[6:9]
	v_mfma_f32_16x16x32_bf16 v[2:5], v[156:159], v[210:213], v[2:5]
	v_mfma_f32_16x16x32_bf16 v[62:65], v[152:155], v[168:171], v[62:65]
	v_mfma_f32_16x16x32_bf16 v[50:53], v[160:163], v[168:171], v[50:53]
	v_mfma_f32_16x16x32_bf16 v[38:41], v[152:155], v[194:197], v[38:41]
	v_mfma_f32_16x16x32_bf16 v[34:37], v[160:163], v[194:197], v[34:37]
	v_mfma_f32_16x16x32_bf16 v[22:25], v[152:155], v[202:205], v[22:25]
	v_mfma_f32_16x16x32_bf16 v[18:21], v[160:163], v[202:205], v[18:21]
	v_mfma_f32_16x16x32_bf16 v[6:9], v[152:155], v[214:217], v[6:9]
	v_mfma_f32_16x16x32_bf16 v[2:5], v[160:163], v[214:217], v[2:5]
	s_barrier
; #define PG8_BAR __builtin_amdgcn_s_barrier()
;     ...
;         for (int t = 2; t < nt; t += 2) PG8_KITER(t);
;         if constexpr (ALIGN_EPI) { if (wr == 0) PG8_BAR; }
	s_setprio 0
	ds_read_b128 v[132:135], v130
	ds_read_b128 v[136:139], v130 offset:1024
	ds_read_b128 v[140:143], v130 offset:2048
	ds_read_b128 v[144:147], v130 offset:3072
	ds_read_b128 v[148:151], v131
	ds_read_b128 v[152:155], v131 offset:1024
	s_add_u32 s16, s74, 0x2b0000
	s_addc_u32 s17, s75, 0
	s_mov_b32 m0, s11
	ds_read_b128 v[160:163], v131 offset:3072
	global_load_lds_dwordx4 v178, s[100:101]
	s_mov_b32 m0, s12
	ds_read_b128 v[156:159], v131 offset:2048
	global_load_lds_dwordx4 v182, s[100:101]
	s_mov_b32 m0, s13
	ds_read_b128 v[164:167], v209 offset:32768
	ds_read_b128 v[168:171], v209 offset:33792
	ds_read_b128 v[172:175], v209 offset:34816
	ds_read_b128 v[194:197], v209 offset:35840
	ds_read_b128 v[198:201], v209 offset:36864
	ds_read_b128 v[202:205], v209 offset:37888
	ds_read_b128 v[210:213], v209 offset:38912
	global_load_lds_dwordx4 v178, s[16:17]
	s_mov_b32 m0, s29
	ds_read_b128 v[214:217], v209 offset:39936
	global_load_lds_dwordx4 v182, s[16:17]
	s_waitcnt vmcnt(8) lgkmcnt(0)
	s_setprio 1
	s_barrier
	v_mfma_f32_16x16x32_bf16 v[122:125], v[132:135], v[164:167], v[122:125]
	v_mfma_f32_16x16x32_bf16 v[118:121], v[140:143], v[164:167], v[118:121]
	v_mfma_f32_16x16x32_bf16 v[110:113], v[132:135], v[172:175], v[110:113]
	v_mfma_f32_16x16x32_bf16 v[106:109], v[140:143], v[172:175], v[106:109]
	v_mfma_f32_16x16x32_bf16 v[94:97], v[132:135], v[198:201], v[94:97]
	v_mfma_f32_16x16x32_bf16 v[90:93], v[140:143], v[198:201], v[90:93]
	v_mfma_f32_16x16x32_bf16 v[78:81], v[132:135], v[210:213], v[78:81]
	v_mfma_f32_16x16x32_bf16 v[74:77], v[140:143], v[210:213], v[74:77]
	v_mfma_f32_16x16x32_bf16 v[122:125], v[136:139], v[168:171], v[122:125]
	v_mfma_f32_16x16x32_bf16 v[118:121], v[144:147], v[168:171], v[118:121]
	v_mfma_f32_16x16x32_bf16 v[110:113], v[136:139], v[194:197], v[110:113]
	v_mfma_f32_16x16x32_bf16 v[106:109], v[144:147], v[194:197], v[106:109]
	v_mfma_f32_16x16x32_bf16 v[94:97], v[136:139], v[202:205], v[94:97]
	v_mfma_f32_16x16x32_bf16 v[90:93], v[144:147], v[202:205], v[90:93]
	v_mfma_f32_16x16x32_bf16 v[78:81], v[136:139], v[214:217], v[78:81]
	v_mfma_f32_16x16x32_bf16 v[74:77], v[144:147], v[214:217], v[74:77]
	s_setprio 0
	s_setprio 1
	v_mfma_f32_16x16x32_bf16 v[126:129], v[148:151], v[164:167], v[126:129]
	v_mfma_f32_16x16x32_bf16 v[114:117], v[156:159], v[164:167], v[114:117]
	v_mfma_f32_16x16x32_bf16 v[102:105], v[148:151], v[172:175], v[102:105]
	v_mfma_f32_16x16x32_bf16 v[98:101], v[156:159], v[172:175], v[98:101]
	v_mfma_f32_16x16x32_bf16 v[86:89], v[148:151], v[198:201], v[86:89]
	v_mfma_f32_16x16x32_bf16 v[82:85], v[156:159], v[198:201], v[82:85]
	v_mfma_f32_16x16x32_bf16 v[70:73], v[148:151], v[210:213], v[70:73]
	v_mfma_f32_16x16x32_bf16 v[66:69], v[156:159], v[210:213], v[66:69]
	v_mfma_f32_16x16x32_bf16 v[126:129], v[152:155], v[168:171], v[126:129]
	v_mfma_f32_16x16x32_bf16 v[114:117], v[160:163], v[168:171], v[114:117]
	v_mfma_f32_16x16x32_bf16 v[102:105], v[152:155], v[194:197], v[102:105]
	v_mfma_f32_16x16x32_bf16 v[98:101], v[160:163], v[194:197], v[98:101]
	v_mfma_f32_16x16x32_bf16 v[86:89], v[152:155], v[202:205], v[86:89]
	v_mfma_f32_16x16x32_bf16 v[82:85], v[160:163], v[202:205], v[82:85]
	v_mfma_f32_16x16x32_bf16 v[70:73], v[152:155], v[214:217], v[70:73]
	v_mfma_f32_16x16x32_bf16 v[66:69], v[160:163], v[214:217], v[66:69]
	s_barrier
	s_setprio 0
	s_mov_b32 m0, s47
	s_add_u32 s98, s98, 0x80
	s_addc_u32 s99, s99, 0
	s_add_u32 s100, s100, 0x80
	s_addc_u32 s101, s101, 0
	s_add_u32 s16, s70, 0x2b0080
	ds_read_b128 v[164:167], v209 offset:49152
	ds_read_b128 v[168:171], v209 offset:50176
	ds_read_b128 v[172:175], v209 offset:51200
	ds_read_b128 v[194:197], v209 offset:52224
	global_load_lds_dwordx4 v180, s[98:99]
	s_mov_b32 m0, s89
	s_addc_u32 s17, s71, 0
	global_load_lds_dwordx4 v184, s[98:99]
	s_mov_b32 m0, s56
	ds_read_b128 v[214:217], v209 offset:56320
	global_load_lds_dwordx4 v180, s[16:17]
	s_mov_b32 m0, s57
	ds_read_b128 v[210:213], v209 offset:55296
	global_load_lds_dwordx4 v184, s[16:17]
	s_mov_b32 m0, s58
	ds_read_b128 v[202:205], v209 offset:54272
	global_load_lds_dwordx4 v178, s[100:101]
	s_mov_b32 m0, s59
	ds_read_b128 v[198:201], v209 offset:53248
	global_load_lds_dwordx4 v182, s[100:101]
	s_waitcnt vmcnt(8) lgkmcnt(0)
	s_setprio 1
	s_barrier
	v_mfma_f32_16x16x32_bf16 v[58:61], v[132:135], v[164:167], v[58:61]
	v_mfma_f32_16x16x32_bf16 v[54:57], v[140:143], v[164:167], v[54:57]
	v_mfma_f32_16x16x32_bf16 v[46:49], v[132:135], v[172:175], v[46:49]
	v_mfma_f32_16x16x32_bf16 v[42:45], v[140:143], v[172:175], v[42:45]
	v_mfma_f32_16x16x32_bf16 v[30:33], v[132:135], v[198:201], v[30:33]
	v_mfma_f32_16x16x32_bf16 v[26:29], v[140:143], v[198:201], v[26:29]
	v_mfma_f32_16x16x32_bf16 v[14:17], v[132:135], v[210:213], v[14:17]
	v_mfma_f32_16x16x32_bf16 v[10:13], v[140:143], v[210:213], v[10:13]
	v_mfma_f32_16x16x32_bf16 v[58:61], v[136:139], v[168:171], v[58:61]
	v_mfma_f32_16x16x32_bf16 v[54:57], v[144:147], v[168:171], v[54:57]
	v_mfma_f32_16x16x32_bf16 v[46:49], v[136:139], v[194:197], v[46:49]
	v_mfma_f32_16x16x32_bf16 v[42:45], v[144:147], v[194:197], v[42:45]
	v_mfma_f32_16x16x32_bf16 v[30:33], v[136:139], v[202:205], v[30:33]
	v_mfma_f32_16x16x32_bf16 v[26:29], v[144:147], v[202:205], v[26:29]
	v_mfma_f32_16x16x32_bf16 v[14:17], v[136:139], v[214:217], v[14:17]
	v_mfma_f32_16x16x32_bf16 v[10:13], v[144:147], v[214:217], v[10:13]
	s_setprio 0
	s_setprio 1
	v_mfma_f32_16x16x32_bf16 v[62:65], v[148:151], v[164:167], v[62:65]
	v_mfma_f32_16x16x32_bf16 v[50:53], v[156:159], v[164:167], v[50:53]
	v_mfma_f32_16x16x32_bf16 v[38:41], v[148:151], v[172:175], v[38:41]
	v_mfma_f32_16x16x32_bf16 v[34:37], v[156:159], v[172:175], v[34:37]
	v_mfma_f32_16x16x32_bf16 v[22:25], v[148:151], v[198:201], v[22:25]
	v_mfma_f32_16x16x32_bf16 v[18:21], v[156:159], v[198:201], v[18:21]
	v_mfma_f32_16x16x32_bf16 v[6:9], v[148:151], v[210:213], v[6:9]
	v_mfma_f32_16x16x32_bf16 v[2:5], v[156:159], v[210:213], v[2:5]
	v_mfma_f32_16x16x32_bf16 v[62:65], v[152:155], v[168:171], v[62:65]
	v_mfma_f32_16x16x32_bf16 v[50:53], v[160:163], v[168:171], v[50:53]
	v_mfma_f32_16x16x32_bf16 v[38:41], v[152:155], v[194:197], v[38:41]
	v_mfma_f32_16x16x32_bf16 v[34:37], v[160:163], v[194:197], v[34:37]
	v_mfma_f32_16x16x32_bf16 v[22:25], v[152:155], v[202:205], v[22:25]
	v_mfma_f32_16x16x32_bf16 v[18:21], v[160:163], v[202:205], v[18:21]
	v_mfma_f32_16x16x32_bf16 v[6:9], v[152:155], v[214:217], v[6:9]
	v_mfma_f32_16x16x32_bf16 v[2:5], v[160:163], v[214:217], v[2:5]
	s_barrier
	s_setprio 0
	s_add_i32 s15, s15, 2
	s_add_u32 s66, s66, 0x100
	s_addc_u32 s67, s67, 0
	s_add_u32 s90, s90, 0x100
	s_addc_u32 s14, s14, 0
	s_cmpk_gt_u32 s15, 0xa9
	s_cbranch_scc0 .LBB0_331
	s_and_b64 vcc, exec, s[30:31]
	s_cbranch_vccz .LBB0_334
	s_barrier

.LBB0_415:
	ds_read_b128 v[150:153], v163
	ds_read_b128 v[154:157], v163 offset:1024
	ds_read_b128 v[158:161], v163 offset:2048
	ds_read_b128 v[168:171], v163 offset:3072
	ds_read_b128 v[172:175], v164
	ds_read_b128 v[176:179], v164 offset:1024
	ds_read_b128 v[180:183], v164 offset:2048
	ds_read_b128 v[184:187], v164 offset:3072
	s_add_u32 s6, s80, 0xfff00080
	s_addc_u32 s7, s81, -1
	s_cmp_eq_u32 s15, 60
	s_cselect_b32 s83, s1, s7
	s_cselect_b32 s82, s75, s6
	s_cselect_b32 s7, s18, s14
	s_cselect_b32 s6, vcc_lo, s30
	s_mov_b32 m0, s89
	ds_read_b128 v[188:191], v165
	ds_read_b128 v[192:195], v165 offset:1024
	ds_read_b128 v[196:199], v165 offset:2048
	ds_read_b128 v[200:203], v165 offset:3072
	ds_read_b128 v[204:207], v165 offset:4096
	ds_read_b128 v[208:211], v165 offset:5120
	ds_read_b128 v[212:215], v165 offset:6144
	global_load_lds_dwordx4 v140, s[80:81]
	s_mov_b32 m0, s92
	ds_read_b128 v[216:219], v165 offset:7168
	global_load_lds_dwordx4 v142, s[80:81]
	s_waitcnt vmcnt(8) lgkmcnt(0)
	s_setprio 1
	s_barrier
	v_mfma_f32_16x16x32_bf16 v[118:121], v[150:153], v[188:191], v[118:121]
	v_mfma_f32_16x16x32_bf16 v[114:117], v[158:161], v[188:191], v[114:117]
	v_mfma_f32_16x16x32_bf16 v[102:105], v[150:153], v[196:199], v[102:105]
	v_mfma_f32_16x16x32_bf16 v[98:101], v[158:161], v[196:199], v[98:101]
	v_mfma_f32_16x16x32_bf16 v[86:89], v[150:153], v[204:207], v[86:89]
	v_mfma_f32_16x16x32_bf16 v[82:85], v[158:161], v[204:207], v[82:85]
	v_mfma_f32_16x16x32_bf16 v[70:73], v[150:153], v[212:215], v[70:73]
	v_mfma_f32_16x16x32_bf16 v[66:69], v[158:161], v[212:215], v[66:69]
	v_mfma_f32_16x16x32_bf16 v[118:121], v[154:157], v[192:195], v[118:121]
	v_mfma_f32_16x16x32_bf16 v[114:117], v[168:171], v[192:195], v[114:117]
	v_mfma_f32_16x16x32_bf16 v[102:105], v[154:157], v[200:203], v[102:105]
	v_mfma_f32_16x16x32_bf16 v[98:101], v[168:171], v[200:203], v[98:101]
	v_mfma_f32_16x16x32_bf16 v[86:89], v[154:157], v[208:211], v[86:89]
	v_mfma_f32_16x16x32_bf16 v[82:85], v[168:171], v[208:211], v[82:85]
	v_mfma_f32_16x16x32_bf16 v[70:73], v[154:157], v[216:219], v[70:73]
	v_mfma_f32_16x16x32_bf16 v[66:69], v[168:171], v[216:219], v[66:69]
	s_setprio 0
	s_setprio 1
	v_mfma_f32_16x16x32_bf16 v[126:129], v[172:175], v[188:191], v[126:129]
	v_mfma_f32_16x16x32_bf16 v[122:125], v[180:183], v[188:191], v[122:125]
	v_mfma_f32_16x16x32_bf16 v[110:113], v[172:175], v[196:199], v[110:113]
	v_mfma_f32_16x16x32_bf16 v[106:109], v[180:183], v[196:199], v[106:109]
	v_mfma_f32_16x16x32_bf16 v[94:97], v[172:175], v[204:207], v[94:97]
	v_mfma_f32_16x16x32_bf16 v[90:93], v[180:183], v[204:207], v[90:93]
	v_mfma_f32_16x16x32_bf16 v[78:81], v[172:175], v[212:215], v[78:81]
	v_mfma_f32_16x16x32_bf16 v[74:77], v[180:183], v[212:215], v[74:77]
	v_mfma_f32_16x16x32_bf16 v[126:129], v[176:179], v[192:195], v[126:129]
	v_mfma_f32_16x16x32_bf16 v[122:125], v[184:187], v[192:195], v[122:125]
	v_mfma_f32_16x16x32_bf16 v[110:113], v[176:179], v[200:203], v[110:113]
	v_mfma_f32_16x16x32_bf16 v[106:109], v[184:187], v[200:203], v[106:109]
	v_mfma_f32_16x16x32_bf16 v[94:97], v[176:179], v[208:211], v[94:97]
	v_mfma_f32_16x16x32_bf16 v[90:93], v[184:187], v[208:211], v[90:93]
	v_mfma_f32_16x16x32_bf16 v[78:81], v[176:179], v[216:219], v[78:81]
	v_mfma_f32_16x16x32_bf16 v[74:77], v[184:187], v[216:219], v[74:77]
	s_barrier
	s_setprio 0
	s_mov_b32 m0, vcc_hi
	s_mov_b64 s[98:99], s[6:7]
	s_add_u32 s16, s6, 0x100000
	ds_read_b128 v[188:191], v165 offset:16384
	ds_read_b128 v[192:195], v165 offset:17408
	ds_read_b128 v[196:199], v165 offset:18432
	ds_read_b128 v[200:203], v165 offset:19456
	ds_read_b128 v[204:207], v165 offset:20480
	ds_read_b128 v[208:211], v165 offset:21504
	ds_read_b128 v[212:215], v165 offset:22528
	global_load_lds_dwordx4 v134, s[6:7]
	s_mov_b32 m0, s84
	s_addc_u32 s17, s7, 0
	global_load_lds_dwordx4 v130, s[6:7]
	s_mov_b32 m0, s85
	s_mov_b64 s[100:101], s[82:83]
	global_load_lds_dwordx4 v134, s[16:17]
	s_mov_b32 m0, s46
	ds_read_b128 v[216:219], v165 offset:23552
	global_load_lds_dwordx4 v130, s[16:17]
	s_waitcnt vmcnt(6) lgkmcnt(0)
	s_setprio 1
	s_barrier
	v_mfma_f32_16x16x32_bf16 v[54:57], v[150:153], v[188:191], v[54:57]
	v_mfma_f32_16x16x32_bf16 v[50:53], v[158:161], v[188:191], v[50:53]
	v_mfma_f32_16x16x32_bf16 v[38:41], v[150:153], v[196:199], v[38:41]
	v_mfma_f32_16x16x32_bf16 v[34:37], v[158:161], v[196:199], v[34:37]
	v_mfma_f32_16x16x32_bf16 v[22:25], v[150:153], v[204:207], v[22:25]
	v_mfma_f32_16x16x32_bf16 v[18:21], v[158:161], v[204:207], v[18:21]
	v_mfma_f32_16x16x32_bf16 v[6:9], v[150:153], v[212:215], v[6:9]
	v_mfma_f32_16x16x32_bf16 v[2:5], v[158:161], v[212:215], v[2:5]
	v_mfma_f32_16x16x32_bf16 v[54:57], v[154:157], v[192:195], v[54:57]
	v_mfma_f32_16x16x32_bf16 v[50:53], v[168:171], v[192:195], v[50:53]
	v_mfma_f32_16x16x32_bf16 v[38:41], v[154:157], v[200:203], v[38:41]
	v_mfma_f32_16x16x32_bf16 v[34:37], v[168:171], v[200:203], v[34:37]
	v_mfma_f32_16x16x32_bf16 v[22:25], v[154:157], v[208:211], v[22:25]
	v_mfma_f32_16x16x32_bf16 v[18:21], v[168:171], v[208:211], v[18:21]
	v_mfma_f32_16x16x32_bf16 v[6:9], v[154:157], v[216:219], v[6:9]
	v_mfma_f32_16x16x32_bf16 v[2:5], v[168:171], v[216:219], v[2:5]
	s_setprio 0
	s_setprio 1
	v_mfma_f32_16x16x32_bf16 v[62:65], v[172:175], v[188:191], v[62:65]
	v_mfma_f32_16x16x32_bf16 v[58:61], v[180:183], v[188:191], v[58:61]
	v_mfma_f32_16x16x32_bf16 v[46:49], v[172:175], v[196:199], v[46:49]
	v_mfma_f32_16x16x32_bf16 v[42:45], v[180:183], v[196:199], v[42:45]
	v_mfma_f32_16x16x32_bf16 v[30:33], v[172:175], v[204:207], v[30:33]
	v_mfma_f32_16x16x32_bf16 v[26:29], v[180:183], v[204:207], v[26:29]
	v_mfma_f32_16x16x32_bf16 v[14:17], v[172:175], v[212:215], v[14:17]
	v_mfma_f32_16x16x32_bf16 v[10:13], v[180:183], v[212:215], v[10:13]
	v_mfma_f32_16x16x32_bf16 v[62:65], v[176:179], v[192:195], v[62:65]
	v_mfma_f32_16x16x32_bf16 v[58:61], v[184:187], v[192:195], v[58:61]
	v_mfma_f32_16x16x32_bf16 v[46:49], v[176:179], v[200:203], v[46:49]
	v_mfma_f32_16x16x32_bf16 v[42:45], v[184:187], v[200:203], v[42:45]
	v_mfma_f32_16x16x32_bf16 v[30:33], v[176:179], v[208:211], v[30:33]
	v_mfma_f32_16x16x32_bf16 v[26:29], v[184:187], v[208:211], v[26:29]
	v_mfma_f32_16x16x32_bf16 v[14:17], v[176:179], v[216:219], v[14:17]
	v_mfma_f32_16x16x32_bf16 v[10:13], v[184:187], v[216:219], v[10:13]
	s_barrier
; #define PG8_BAR __builtin_amdgcn_s_barrier()
;     ...
;         for (int t = 2; t < nt; t += 2) PG8_KITER(t);
;         if constexpr (ALIGN_EPI) { if (wr == 0) PG8_BAR; }
	s_setprio 0
	ds_read_b128 v[150:153], v138
	ds_read_b128 v[154:157], v138 offset:1024
	ds_read_b128 v[158:161], v138 offset:2048
	ds_read_b128 v[168:171], v138 offset:3072
	ds_read_b128 v[172:175], v148
	ds_read_b128 v[176:179], v148 offset:1024
	s_add_u32 s16, s82, 0x100000
	s_addc_u32 s17, s83, 0
	s_mov_b32 m0, s86
	ds_read_b128 v[184:187], v148 offset:3072
	global_load_lds_dwordx4 v136, s[100:101]
	s_mov_b32 m0, s93
	ds_read_b128 v[180:183], v148 offset:2048
	global_load_lds_dwordx4 v132, s[100:101]
	s_mov_b32 m0, s94
	ds_read_b128 v[188:191], v165 offset:32768
	ds_read_b128 v[192:195], v165 offset:33792
	ds_read_b128 v[196:199], v165 offset:34816
	ds_read_b128 v[200:203], v165 offset:35840
	ds_read_b128 v[204:207], v165 offset:36864
	ds_read_b128 v[208:211], v165 offset:37888
	ds_read_b128 v[212:215], v165 offset:38912
	global_load_lds_dwordx4 v136, s[16:17]
	s_mov_b32 m0, s95
	ds_read_b128 v[216:219], v165 offset:39936
	global_load_lds_dwordx4 v132, s[16:17]
	s_waitcnt vmcnt(8) lgkmcnt(0)
	s_setprio 1
	s_barrier
	v_mfma_f32_16x16x32_bf16 v[118:121], v[150:153], v[188:191], v[118:121]
	v_mfma_f32_16x16x32_bf16 v[114:117], v[158:161], v[188:191], v[114:117]
	v_mfma_f32_16x16x32_bf16 v[102:105], v[150:153], v[196:199], v[102:105]
	v_mfma_f32_16x16x32_bf16 v[98:101], v[158:161], v[196:199], v[98:101]
	v_mfma_f32_16x16x32_bf16 v[86:89], v[150:153], v[204:207], v[86:89]
	v_mfma_f32_16x16x32_bf16 v[82:85], v[158:161], v[204:207], v[82:85]
	v_mfma_f32_16x16x32_bf16 v[70:73], v[150:153], v[212:215], v[70:73]
	v_mfma_f32_16x16x32_bf16 v[66:69], v[158:161], v[212:215], v[66:69]
	v_mfma_f32_16x16x32_bf16 v[118:121], v[154:157], v[192:195], v[118:121]
	v_mfma_f32_16x16x32_bf16 v[114:117], v[168:171], v[192:195], v[114:117]
	v_mfma_f32_16x16x32_bf16 v[102:105], v[154:157], v[200:203], v[102:105]
	v_mfma_f32_16x16x32_bf16 v[98:101], v[168:171], v[200:203], v[98:101]
	v_mfma_f32_16x16x32_bf16 v[86:89], v[154:157], v[208:211], v[86:89]
	v_mfma_f32_16x16x32_bf16 v[82:85], v[168:171], v[208:211], v[82:85]
	v_mfma_f32_16x16x32_bf16 v[70:73], v[154:157], v[216:219], v[70:73]
	v_mfma_f32_16x16x32_bf16 v[66:69], v[168:171], v[216:219], v[66:69]
	s_setprio 0
	s_setprio 1
	v_mfma_f32_16x16x32_bf16 v[126:129], v[172:175], v[188:191], v[126:129]
	v_mfma_f32_16x16x32_bf16 v[122:125], v[180:183], v[188:191], v[122:125]
	v_mfma_f32_16x16x32_bf16 v[110:113], v[172:175], v[196:199], v[110:113]
	v_mfma_f32_16x16x32_bf16 v[106:109], v[180:183], v[196:199], v[106:109]
	v_mfma_f32_16x16x32_bf16 v[94:97], v[172:175], v[204:207], v[94:97]
	v_mfma_f32_16x16x32_bf16 v[90:93], v[180:183], v[204:207], v[90:93]
	v_mfma_f32_16x16x32_bf16 v[78:81], v[172:175], v[212:215], v[78:81]
	v_mfma_f32_16x16x32_bf16 v[74:77], v[180:183], v[212:215], v[74:77]
	v_mfma_f32_16x16x32_bf16 v[126:129], v[176:179], v[192:195], v[126:129]
	v_mfma_f32_16x16x32_bf16 v[122:125], v[184:187], v[192:195], v[122:125]
	v_mfma_f32_16x16x32_bf16 v[110:113], v[176:179], v[200:203], v[110:113]
	v_mfma_f32_16x16x32_bf16 v[106:109], v[184:187], v[200:203], v[106:109]
	v_mfma_f32_16x16x32_bf16 v[94:97], v[176:179], v[208:211], v[94:97]
	v_mfma_f32_16x16x32_bf16 v[90:93], v[184:187], v[208:211], v[90:93]
	v_mfma_f32_16x16x32_bf16 v[78:81], v[176:179], v[216:219], v[78:81]
	v_mfma_f32_16x16x32_bf16 v[74:77], v[184:187], v[216:219], v[74:77]
	s_barrier
	s_setprio 0
	s_mov_b32 m0, s47
	s_add_u32 s98, s98, 0x80
	s_addc_u32 s99, s99, 0
	s_add_u32 s100, s100, 0x80
	s_addc_u32 s101, s101, 0
	s_add_u32 s6, s6, 0x100080
	ds_read_b128 v[188:191], v165 offset:49152
	ds_read_b128 v[192:195], v165 offset:50176
	ds_read_b128 v[196:199], v165 offset:51200
	ds_read_b128 v[200:203], v165 offset:52224
	global_load_lds_dwordx4 v134, s[98:99]
	s_mov_b32 m0, s91
	s_addc_u32 s7, s7, 0
	global_load_lds_dwordx4 v130, s[98:99]
	s_mov_b32 m0, s56
	ds_read_b128 v[216:219], v165 offset:56320
	global_load_lds_dwordx4 v134, s[6:7]
	s_mov_b32 m0, s57
	ds_read_b128 v[212:215], v165 offset:55296
	global_load_lds_dwordx4 v130, s[6:7]
	s_mov_b32 m0, s96
	ds_read_b128 v[208:211], v165 offset:54272
	global_load_lds_dwordx4 v136, s[100:101]
	s_mov_b32 m0, s97
	ds_read_b128 v[204:207], v165 offset:53248
	global_load_lds_dwordx4 v132, s[100:101]
	s_waitcnt vmcnt(8) lgkmcnt(0)
	s_setprio 1
	s_barrier
	v_mfma_f32_16x16x32_bf16 v[54:57], v[150:153], v[188:191], v[54:57]
	v_mfma_f32_16x16x32_bf16 v[50:53], v[158:161], v[188:191], v[50:53]
	v_mfma_f32_16x16x32_bf16 v[38:41], v[150:153], v[196:199], v[38:41]
	v_mfma_f32_16x16x32_bf16 v[34:37], v[158:161], v[196:199], v[34:37]
	v_mfma_f32_16x16x32_bf16 v[22:25], v[150:153], v[204:207], v[22:25]
	v_mfma_f32_16x16x32_bf16 v[18:21], v[158:161], v[204:207], v[18:21]
	v_mfma_f32_16x16x32_bf16 v[6:9], v[150:153], v[212:215], v[6:9]
	v_mfma_f32_16x16x32_bf16 v[2:5], v[158:161], v[212:215], v[2:5]
	v_mfma_f32_16x16x32_bf16 v[54:57], v[154:157], v[192:195], v[54:57]
	v_mfma_f32_16x16x32_bf16 v[50:53], v[168:171], v[192:195], v[50:53]
	v_mfma_f32_16x16x32_bf16 v[38:41], v[154:157], v[200:203], v[38:41]
	v_mfma_f32_16x16x32_bf16 v[34:37], v[168:171], v[200:203], v[34:37]
	v_mfma_f32_16x16x32_bf16 v[22:25], v[154:157], v[208:211], v[22:25]
	v_mfma_f32_16x16x32_bf16 v[18:21], v[168:171], v[208:211], v[18:21]
	v_mfma_f32_16x16x32_bf16 v[6:9], v[154:157], v[216:219], v[6:9]
	v_mfma_f32_16x16x32_bf16 v[2:5], v[168:171], v[216:219], v[2:5]
	s_setprio 0
	s_setprio 1
	v_mfma_f32_16x16x32_bf16 v[62:65], v[172:175], v[188:191], v[62:65]
	v_mfma_f32_16x16x32_bf16 v[58:61], v[180:183], v[188:191], v[58:61]
	v_mfma_f32_16x16x32_bf16 v[46:49], v[172:175], v[196:199], v[46:49]
	v_mfma_f32_16x16x32_bf16 v[42:45], v[180:183], v[196:199], v[42:45]
	v_mfma_f32_16x16x32_bf16 v[30:33], v[172:175], v[204:207], v[30:33]
	v_mfma_f32_16x16x32_bf16 v[26:29], v[180:183], v[204:207], v[26:29]
	v_mfma_f32_16x16x32_bf16 v[14:17], v[172:175], v[212:215], v[14:17]
	v_mfma_f32_16x16x32_bf16 v[10:13], v[180:183], v[212:215], v[10:13]
	v_mfma_f32_16x16x32_bf16 v[62:65], v[176:179], v[192:195], v[62:65]
	v_mfma_f32_16x16x32_bf16 v[58:61], v[184:187], v[192:195], v[58:61]
	v_mfma_f32_16x16x32_bf16 v[46:49], v[176:179], v[200:203], v[46:49]
	v_mfma_f32_16x16x32_bf16 v[42:45], v[184:187], v[200:203], v[42:45]
	v_mfma_f32_16x16x32_bf16 v[30:33], v[176:179], v[208:211], v[30:33]
	v_mfma_f32_16x16x32_bf16 v[26:29], v[184:187], v[208:211], v[26:29]
	v_mfma_f32_16x16x32_bf16 v[14:17], v[176:179], v[216:219], v[14:17]
	v_mfma_f32_16x16x32_bf16 v[10:13], v[184:187], v[216:219], v[10:13]
	s_barrier
	s_setprio 0
	s_add_i32 s15, s15, 2
	s_add_u32 s80, s80, 0x100
	s_addc_u32 s81, s81, 0
	s_add_u32 s30, s30, 0x100
	s_addc_u32 s14, s14, 0
	s_cmp_gt_u32 s15, 61
	s_cbranch_scc0 .LBB0_415
	s_and_b64 vcc, exec, s[64:65]
	s_cbranch_vccz .LBB0_418
	s_barrier

.LBB0_435:
	ds_read_b128 v[146:149], v141
	ds_read_b128 v[150:153], v141 offset:1024
	ds_read_b128 v[154:157], v141 offset:2048
	ds_read_b128 v[158:161], v141 offset:3072
	ds_read_b128 v[162:165], v142
	ds_read_b128 v[166:169], v142 offset:1024
	ds_read_b128 v[170:173], v142 offset:2048
	ds_read_b128 v[174:177], v142 offset:3072
	s_add_u32 s17, s78, 0xfff00080
	s_addc_u32 s20, s79, -1
	s_cmp_eq_u32 s16, 60
	s_cselect_b32 s81, s9, s20
	s_cselect_b32 s80, s67, s17
	s_cselect_b32 s77, s18, s15
	s_cselect_b32 s76, s95, s14
	s_mov_b32 m0, s96
	ds_read_b128 v[178:181], v143
	ds_read_b128 v[182:185], v143 offset:1024
	ds_read_b128 v[186:189], v143 offset:2048
	ds_read_b128 v[190:193], v143 offset:3072
	ds_read_b128 v[194:197], v143 offset:4096
	ds_read_b128 v[198:201], v143 offset:5120
	ds_read_b128 v[202:205], v143 offset:6144
	global_load_lds_dwordx4 v136, s[78:79]
	s_mov_b32 m0, s97
	ds_read_b128 v[206:209], v143 offset:7168
	global_load_lds_dwordx4 v138, s[78:79]
	s_waitcnt vmcnt(8) lgkmcnt(0)
	s_setprio 1
	s_barrier
	v_mfma_f32_16x16x32_bf16 v[34:37], v[146:149], v[178:181], v[34:37]
	v_mfma_f32_16x16x32_bf16 v[38:41], v[154:157], v[178:181], v[38:41]
	v_mfma_f32_16x16x32_bf16 v[18:21], v[146:149], v[186:189], v[18:21]
	v_mfma_f32_16x16x32_bf16 v[22:25], v[154:157], v[186:189], v[22:25]
	v_mfma_f32_16x16x32_bf16 v[10:13], v[146:149], v[194:197], v[10:13]
	v_mfma_f32_16x16x32_bf16 v[14:17], v[154:157], v[194:197], v[14:17]
	v_mfma_f32_16x16x32_bf16 v[2:5], v[146:149], v[202:205], v[2:5]
	v_mfma_f32_16x16x32_bf16 v[6:9], v[154:157], v[202:205], v[6:9]
	v_mfma_f32_16x16x32_bf16 v[34:37], v[150:153], v[182:185], v[34:37]
	v_mfma_f32_16x16x32_bf16 v[38:41], v[158:161], v[182:185], v[38:41]
	v_mfma_f32_16x16x32_bf16 v[18:21], v[150:153], v[190:193], v[18:21]
	v_mfma_f32_16x16x32_bf16 v[22:25], v[158:161], v[190:193], v[22:25]
	v_mfma_f32_16x16x32_bf16 v[10:13], v[150:153], v[198:201], v[10:13]
	v_mfma_f32_16x16x32_bf16 v[14:17], v[158:161], v[198:201], v[14:17]
	v_mfma_f32_16x16x32_bf16 v[2:5], v[150:153], v[206:209], v[2:5]
	v_mfma_f32_16x16x32_bf16 v[6:9], v[158:161], v[206:209], v[6:9]
	s_setprio 0
	s_setprio 1
	v_mfma_f32_16x16x32_bf16 v[66:69], v[162:165], v[178:181], v[66:69]
	v_mfma_f32_16x16x32_bf16 v[70:73], v[170:173], v[178:181], v[70:73]
	v_mfma_f32_16x16x32_bf16 v[54:57], v[162:165], v[186:189], v[54:57]
	v_mfma_f32_16x16x32_bf16 v[62:65], v[170:173], v[186:189], v[62:65]
	v_mfma_f32_16x16x32_bf16 v[42:45], v[162:165], v[194:197], v[42:45]
	v_mfma_f32_16x16x32_bf16 v[46:49], v[170:173], v[194:197], v[46:49]
	v_mfma_f32_16x16x32_bf16 v[26:29], v[162:165], v[202:205], v[26:29]
	v_mfma_f32_16x16x32_bf16 v[30:33], v[170:173], v[202:205], v[30:33]
	v_mfma_f32_16x16x32_bf16 v[66:69], v[166:169], v[182:185], v[66:69]
	v_mfma_f32_16x16x32_bf16 v[70:73], v[174:177], v[182:185], v[70:73]
	v_mfma_f32_16x16x32_bf16 v[54:57], v[166:169], v[190:193], v[54:57]
	v_mfma_f32_16x16x32_bf16 v[62:65], v[174:177], v[190:193], v[62:65]
	v_mfma_f32_16x16x32_bf16 v[42:45], v[166:169], v[198:201], v[42:45]
	v_mfma_f32_16x16x32_bf16 v[46:49], v[174:177], v[198:201], v[46:49]
	v_mfma_f32_16x16x32_bf16 v[26:29], v[166:169], v[206:209], v[26:29]
	v_mfma_f32_16x16x32_bf16 v[30:33], v[174:177], v[206:209], v[30:33]
	s_barrier
	s_setprio 0
	s_mov_b32 m0, vcc_lo
	s_mov_b64 s[98:99], s[76:77]
	s_add_u32 s20, s76, 0x100000
	ds_read_b128 v[178:181], v143 offset:16384
	ds_read_b128 v[182:185], v143 offset:17408
	ds_read_b128 v[186:189], v143 offset:18432
	ds_read_b128 v[190:193], v143 offset:19456
	ds_read_b128 v[194:197], v143 offset:20480
	ds_read_b128 v[198:201], v143 offset:21504
	ds_read_b128 v[202:205], v143 offset:22528
	global_load_lds_dwordx4 v132, s[76:77]
	s_mov_b32 m0, s84
	s_addc_u32 s21, s77, 0
	global_load_lds_dwordx4 v130, s[76:77]
	s_mov_b32 m0, s85
	s_mov_b64 s[100:101], s[80:81]
	global_load_lds_dwordx4 v132, s[20:21]
	s_mov_b32 m0, s46
	ds_read_b128 v[206:209], v143 offset:23552
	global_load_lds_dwordx4 v130, s[20:21]
	s_waitcnt vmcnt(6) lgkmcnt(0)
	s_setprio 1
	s_barrier
	v_mfma_f32_16x16x32_bf16 v[102:105], v[146:149], v[178:181], v[102:105]
	v_mfma_f32_16x16x32_bf16 v[110:113], v[154:157], v[178:181], v[110:113]
	v_mfma_f32_16x16x32_bf16 v[90:93], v[146:149], v[186:189], v[90:93]
	v_mfma_f32_16x16x32_bf16 v[94:97], v[154:157], v[186:189], v[94:97]
	v_mfma_f32_16x16x32_bf16 v[74:77], v[146:149], v[194:197], v[74:77]
	v_mfma_f32_16x16x32_bf16 v[78:81], v[154:157], v[194:197], v[78:81]
	v_mfma_f32_16x16x32_bf16 v[50:53], v[146:149], v[202:205], v[50:53]
	v_mfma_f32_16x16x32_bf16 v[58:61], v[154:157], v[202:205], v[58:61]
	v_mfma_f32_16x16x32_bf16 v[102:105], v[150:153], v[182:185], v[102:105]
	v_mfma_f32_16x16x32_bf16 v[110:113], v[158:161], v[182:185], v[110:113]
	v_mfma_f32_16x16x32_bf16 v[90:93], v[150:153], v[190:193], v[90:93]
	v_mfma_f32_16x16x32_bf16 v[94:97], v[158:161], v[190:193], v[94:97]
	v_mfma_f32_16x16x32_bf16 v[74:77], v[150:153], v[198:201], v[74:77]
	v_mfma_f32_16x16x32_bf16 v[78:81], v[158:161], v[198:201], v[78:81]
	v_mfma_f32_16x16x32_bf16 v[50:53], v[150:153], v[206:209], v[50:53]
	v_mfma_f32_16x16x32_bf16 v[58:61], v[158:161], v[206:209], v[58:61]
	s_setprio 0
	s_setprio 1
	v_mfma_f32_16x16x32_bf16 v[122:125], v[162:165], v[178:181], v[122:125]
	v_mfma_f32_16x16x32_bf16 v[126:129], v[170:173], v[178:181], v[126:129]
	v_mfma_f32_16x16x32_bf16 v[114:117], v[162:165], v[186:189], v[114:117]
	v_mfma_f32_16x16x32_bf16 v[118:121], v[170:173], v[186:189], v[118:121]
	v_mfma_f32_16x16x32_bf16 v[98:101], v[162:165], v[194:197], v[98:101]
	v_mfma_f32_16x16x32_bf16 v[106:109], v[170:173], v[194:197], v[106:109]
	v_mfma_f32_16x16x32_bf16 v[82:85], v[162:165], v[202:205], v[82:85]
	v_mfma_f32_16x16x32_bf16 v[86:89], v[170:173], v[202:205], v[86:89]
	v_mfma_f32_16x16x32_bf16 v[122:125], v[166:169], v[182:185], v[122:125]
	v_mfma_f32_16x16x32_bf16 v[126:129], v[174:177], v[182:185], v[126:129]
	v_mfma_f32_16x16x32_bf16 v[114:117], v[166:169], v[190:193], v[114:117]
	v_mfma_f32_16x16x32_bf16 v[118:121], v[174:177], v[190:193], v[118:121]
	v_mfma_f32_16x16x32_bf16 v[98:101], v[166:169], v[198:201], v[98:101]
	v_mfma_f32_16x16x32_bf16 v[106:109], v[174:177], v[198:201], v[106:109]
	v_mfma_f32_16x16x32_bf16 v[82:85], v[166:169], v[206:209], v[82:85]
	v_mfma_f32_16x16x32_bf16 v[86:89], v[174:177], v[206:209], v[86:89]
	s_barrier
; #define PG8_BAR __builtin_amdgcn_s_barrier()
;     ...
;         for (int t = 2; t < nt; t += 2) PG8_KITER(t);
;         if constexpr (ALIGN_EPI) { if (wr == 0) PG8_BAR; }
	s_setprio 0
	ds_read_b128 v[146:149], v134
	ds_read_b128 v[150:153], v134 offset:1024
	ds_read_b128 v[154:157], v134 offset:2048
	ds_read_b128 v[158:161], v134 offset:3072
	ds_read_b128 v[162:165], v144
	ds_read_b128 v[166:169], v144 offset:1024
	s_add_u32 s20, s80, 0x100000
	s_addc_u32 s21, s81, 0
	s_mov_b32 m0, s59
	ds_read_b128 v[174:177], v144 offset:3072
	global_load_lds_dwordx4 v132, s[100:101]
	s_mov_b32 m0, s82
	ds_read_b128 v[170:173], v144 offset:2048
	global_load_lds_dwordx4 v130, s[100:101]
	s_mov_b32 m0, s83
	ds_read_b128 v[178:181], v143 offset:32768
	ds_read_b128 v[182:185], v143 offset:33792
	ds_read_b128 v[186:189], v143 offset:34816
	ds_read_b128 v[190:193], v143 offset:35840
	ds_read_b128 v[194:197], v143 offset:36864
	ds_read_b128 v[198:201], v143 offset:37888
	ds_read_b128 v[202:205], v143 offset:38912
	global_load_lds_dwordx4 v132, s[20:21]
	s_mov_b32 m0, s86
	ds_read_b128 v[206:209], v143 offset:39936
	global_load_lds_dwordx4 v130, s[20:21]
	s_waitcnt vmcnt(8) lgkmcnt(0)
	s_setprio 1
	s_barrier
	v_mfma_f32_16x16x32_bf16 v[34:37], v[146:149], v[178:181], v[34:37]
	v_mfma_f32_16x16x32_bf16 v[38:41], v[154:157], v[178:181], v[38:41]
	v_mfma_f32_16x16x32_bf16 v[18:21], v[146:149], v[186:189], v[18:21]
	v_mfma_f32_16x16x32_bf16 v[22:25], v[154:157], v[186:189], v[22:25]
	v_mfma_f32_16x16x32_bf16 v[10:13], v[146:149], v[194:197], v[10:13]
	v_mfma_f32_16x16x32_bf16 v[14:17], v[154:157], v[194:197], v[14:17]
	v_mfma_f32_16x16x32_bf16 v[2:5], v[146:149], v[202:205], v[2:5]
	v_mfma_f32_16x16x32_bf16 v[6:9], v[154:157], v[202:205], v[6:9]
	v_mfma_f32_16x16x32_bf16 v[34:37], v[150:153], v[182:185], v[34:37]
	v_mfma_f32_16x16x32_bf16 v[38:41], v[158:161], v[182:185], v[38:41]
	v_mfma_f32_16x16x32_bf16 v[18:21], v[150:153], v[190:193], v[18:21]
	v_mfma_f32_16x16x32_bf16 v[22:25], v[158:161], v[190:193], v[22:25]
	v_mfma_f32_16x16x32_bf16 v[10:13], v[150:153], v[198:201], v[10:13]
	v_mfma_f32_16x16x32_bf16 v[14:17], v[158:161], v[198:201], v[14:17]
	v_mfma_f32_16x16x32_bf16 v[2:5], v[150:153], v[206:209], v[2:5]
	v_mfma_f32_16x16x32_bf16 v[6:9], v[158:161], v[206:209], v[6:9]
	s_setprio 0
	s_setprio 1
	v_mfma_f32_16x16x32_bf16 v[66:69], v[162:165], v[178:181], v[66:69]
	v_mfma_f32_16x16x32_bf16 v[70:73], v[170:173], v[178:181], v[70:73]
	v_mfma_f32_16x16x32_bf16 v[54:57], v[162:165], v[186:189], v[54:57]
	v_mfma_f32_16x16x32_bf16 v[62:65], v[170:173], v[186:189], v[62:65]
	v_mfma_f32_16x16x32_bf16 v[42:45], v[162:165], v[194:197], v[42:45]
	v_mfma_f32_16x16x32_bf16 v[46:49], v[170:173], v[194:197], v[46:49]
	v_mfma_f32_16x16x32_bf16 v[26:29], v[162:165], v[202:205], v[26:29]
	v_mfma_f32_16x16x32_bf16 v[30:33], v[170:173], v[202:205], v[30:33]
	v_mfma_f32_16x16x32_bf16 v[66:69], v[166:169], v[182:185], v[66:69]
	v_mfma_f32_16x16x32_bf16 v[70:73], v[174:177], v[182:185], v[70:73]
	v_mfma_f32_16x16x32_bf16 v[54:57], v[166:169], v[190:193], v[54:57]
	v_mfma_f32_16x16x32_bf16 v[62:65], v[174:177], v[190:193], v[62:65]
	v_mfma_f32_16x16x32_bf16 v[42:45], v[166:169], v[198:201], v[42:45]
	v_mfma_f32_16x16x32_bf16 v[46:49], v[174:177], v[198:201], v[46:49]
	v_mfma_f32_16x16x32_bf16 v[26:29], v[166:169], v[206:209], v[26:29]
	v_mfma_f32_16x16x32_bf16 v[30:33], v[174:177], v[206:209], v[30:33]
	s_barrier
	s_setprio 0
	s_mov_b32 m0, s47
	s_add_u32 s98, s98, 0x80
	s_addc_u32 s99, s99, 0
	s_add_u32 s100, s100, 0x80
	s_addc_u32 s101, s101, 0
	s_add_u32 s20, s76, 0x100080
	ds_read_b128 v[178:181], v143 offset:49152
	ds_read_b128 v[182:185], v143 offset:50176
	ds_read_b128 v[186:189], v143 offset:51200
	ds_read_b128 v[190:193], v143 offset:52224
	global_load_lds_dwordx4 v132, s[98:99]
	s_mov_b32 m0, vcc_hi
	s_addc_u32 s21, s77, 0
	global_load_lds_dwordx4 v130, s[98:99]
	s_mov_b32 m0, s56
	ds_read_b128 v[206:209], v143 offset:56320
	global_load_lds_dwordx4 v132, s[20:21]
	s_mov_b32 m0, s57
	ds_read_b128 v[202:205], v143 offset:55296
	global_load_lds_dwordx4 v130, s[20:21]
	s_mov_b32 m0, s88
	ds_read_b128 v[198:201], v143 offset:54272
	global_load_lds_dwordx4 v132, s[100:101]
	s_mov_b32 m0, s89
	ds_read_b128 v[194:197], v143 offset:53248
	global_load_lds_dwordx4 v130, s[100:101]
	s_waitcnt vmcnt(8) lgkmcnt(0)
	s_setprio 1
	s_barrier
	v_mfma_f32_16x16x32_bf16 v[102:105], v[146:149], v[178:181], v[102:105]
	v_mfma_f32_16x16x32_bf16 v[110:113], v[154:157], v[178:181], v[110:113]
	v_mfma_f32_16x16x32_bf16 v[90:93], v[146:149], v[186:189], v[90:93]
	v_mfma_f32_16x16x32_bf16 v[94:97], v[154:157], v[186:189], v[94:97]
	v_mfma_f32_16x16x32_bf16 v[74:77], v[146:149], v[194:197], v[74:77]
	v_mfma_f32_16x16x32_bf16 v[78:81], v[154:157], v[194:197], v[78:81]
	v_mfma_f32_16x16x32_bf16 v[50:53], v[146:149], v[202:205], v[50:53]
	v_mfma_f32_16x16x32_bf16 v[58:61], v[154:157], v[202:205], v[58:61]
	v_mfma_f32_16x16x32_bf16 v[102:105], v[150:153], v[182:185], v[102:105]
	v_mfma_f32_16x16x32_bf16 v[110:113], v[158:161], v[182:185], v[110:113]
	v_mfma_f32_16x16x32_bf16 v[90:93], v[150:153], v[190:193], v[90:93]
	v_mfma_f32_16x16x32_bf16 v[94:97], v[158:161], v[190:193], v[94:97]
	v_mfma_f32_16x16x32_bf16 v[74:77], v[150:153], v[198:201], v[74:77]
	v_mfma_f32_16x16x32_bf16 v[78:81], v[158:161], v[198:201], v[78:81]
	v_mfma_f32_16x16x32_bf16 v[50:53], v[150:153], v[206:209], v[50:53]
	v_mfma_f32_16x16x32_bf16 v[58:61], v[158:161], v[206:209], v[58:61]
	s_setprio 0
	s_setprio 1
	v_mfma_f32_16x16x32_bf16 v[122:125], v[162:165], v[178:181], v[122:125]
	v_mfma_f32_16x16x32_bf16 v[126:129], v[170:173], v[178:181], v[126:129]
	v_mfma_f32_16x16x32_bf16 v[114:117], v[162:165], v[186:189], v[114:117]
	v_mfma_f32_16x16x32_bf16 v[118:121], v[170:173], v[186:189], v[118:121]
	v_mfma_f32_16x16x32_bf16 v[98:101], v[162:165], v[194:197], v[98:101]
	v_mfma_f32_16x16x32_bf16 v[106:109], v[170:173], v[194:197], v[106:109]
	v_mfma_f32_16x16x32_bf16 v[82:85], v[162:165], v[202:205], v[82:85]
	v_mfma_f32_16x16x32_bf16 v[86:89], v[170:173], v[202:205], v[86:89]
	v_mfma_f32_16x16x32_bf16 v[122:125], v[166:169], v[182:185], v[122:125]
	v_mfma_f32_16x16x32_bf16 v[126:129], v[174:177], v[182:185], v[126:129]
	v_mfma_f32_16x16x32_bf16 v[114:117], v[166:169], v[190:193], v[114:117]
	v_mfma_f32_16x16x32_bf16 v[118:121], v[174:177], v[190:193], v[118:121]
	v_mfma_f32_16x16x32_bf16 v[98:101], v[166:169], v[198:201], v[98:101]
	v_mfma_f32_16x16x32_bf16 v[106:109], v[174:177], v[198:201], v[106:109]
	v_mfma_f32_16x16x32_bf16 v[82:85], v[166:169], v[206:209], v[82:85]
	v_mfma_f32_16x16x32_bf16 v[86:89], v[174:177], v[206:209], v[86:89]
	s_barrier
	s_setprio 0
	s_add_i32 s16, s16, 2
	s_add_u32 s78, s78, 0x100
	s_addc_u32 s79, s79, 0
	s_add_u32 s14, s14, 0x100
	s_addc_u32 s15, s15, 0
	s_cmp_gt_u32 s16, 61
	s_cbranch_scc0 .LBB0_435
	s_and_b64 vcc, exec, s[30:31]
	s_cbranch_vccz .LBB0_438
	s_barrier

.LBB0_644:
	ds_read_b128 v[146:149], v1
	ds_read_b128 v[154:157], v1 offset:1024
	ds_read_b128 v[158:161], v1 offset:2048
	ds_read_b128 v[162:165], v1 offset:3072
	ds_read_b128 v[166:169], v150
	ds_read_b128 v[170:173], v150 offset:1024
	ds_read_b128 v[174:177], v150 offset:2048
	ds_read_b128 v[178:181], v150 offset:3072
	s_add_u32 s27, s62, 0xfffc0080
	s_addc_u32 s46, s63, -1
	s_cmp_eq_u32 s26, 12
	s_cselect_b32 s65, s23, s46
	s_cselect_b32 s64, s83, s27
	s_cselect_b32 s55, s0, s15
	s_cselect_b32 s54, s86, s14
	s_mov_b32 m0, s69
	ds_read_b128 v[182:185], v151
	ds_read_b128 v[186:189], v151 offset:1024
	ds_read_b128 v[190:193], v151 offset:2048
	ds_read_b128 v[194:197], v151 offset:3072
	ds_read_b128 v[198:201], v151 offset:4096
	ds_read_b128 v[202:205], v151 offset:5120
	ds_read_b128 v[206:209], v151 offset:6144
	global_load_lds_dwordx4 v138, s[62:63]
	s_mov_b32 m0, s70
	ds_read_b128 v[210:213], v151 offset:7168
	global_load_lds_dwordx4 v140, s[62:63]
	s_waitcnt vmcnt(8) lgkmcnt(0)
	s_setprio 1
	s_barrier
	v_mfma_f32_16x16x32_bf16 v[122:125], v[146:149], v[182:185], v[122:125]
	v_mfma_f32_16x16x32_bf16 v[114:117], v[158:161], v[182:185], v[114:117]
	v_mfma_f32_16x16x32_bf16 v[106:109], v[146:149], v[190:193], v[106:109]
	v_mfma_f32_16x16x32_bf16 v[98:101], v[158:161], v[190:193], v[98:101]
	v_mfma_f32_16x16x32_bf16 v[90:93], v[146:149], v[198:201], v[90:93]
	v_mfma_f32_16x16x32_bf16 v[82:85], v[158:161], v[198:201], v[82:85]
	v_mfma_f32_16x16x32_bf16 v[58:61], v[146:149], v[206:209], v[58:61]
	v_mfma_f32_16x16x32_bf16 v[50:53], v[158:161], v[206:209], v[50:53]
	v_mfma_f32_16x16x32_bf16 v[122:125], v[154:157], v[186:189], v[122:125]
	v_mfma_f32_16x16x32_bf16 v[114:117], v[162:165], v[186:189], v[114:117]
	v_mfma_f32_16x16x32_bf16 v[106:109], v[154:157], v[194:197], v[106:109]
	v_mfma_f32_16x16x32_bf16 v[98:101], v[162:165], v[194:197], v[98:101]
	v_mfma_f32_16x16x32_bf16 v[90:93], v[154:157], v[202:205], v[90:93]
	v_mfma_f32_16x16x32_bf16 v[82:85], v[162:165], v[202:205], v[82:85]
	v_mfma_f32_16x16x32_bf16 v[58:61], v[154:157], v[210:213], v[58:61]
	v_mfma_f32_16x16x32_bf16 v[50:53], v[162:165], v[210:213], v[50:53]
	s_setprio 0
	s_setprio 1
	v_mfma_f32_16x16x32_bf16 v[126:129], v[166:169], v[182:185], v[126:129]
	v_mfma_f32_16x16x32_bf16 v[118:121], v[174:177], v[182:185], v[118:121]
	v_mfma_f32_16x16x32_bf16 v[110:113], v[166:169], v[190:193], v[110:113]
	v_mfma_f32_16x16x32_bf16 v[102:105], v[174:177], v[190:193], v[102:105]
	v_mfma_f32_16x16x32_bf16 v[94:97], v[166:169], v[198:201], v[94:97]
	v_mfma_f32_16x16x32_bf16 v[86:89], v[174:177], v[198:201], v[86:89]
	v_mfma_f32_16x16x32_bf16 v[62:65], v[166:169], v[206:209], v[62:65]
	v_mfma_f32_16x16x32_bf16 v[54:57], v[174:177], v[206:209], v[54:57]
	v_mfma_f32_16x16x32_bf16 v[126:129], v[170:173], v[186:189], v[126:129]
	v_mfma_f32_16x16x32_bf16 v[118:121], v[178:181], v[186:189], v[118:121]
	v_mfma_f32_16x16x32_bf16 v[110:113], v[170:173], v[194:197], v[110:113]
	v_mfma_f32_16x16x32_bf16 v[102:105], v[178:181], v[194:197], v[102:105]
	v_mfma_f32_16x16x32_bf16 v[94:97], v[170:173], v[202:205], v[94:97]
	v_mfma_f32_16x16x32_bf16 v[86:89], v[178:181], v[202:205], v[86:89]
	v_mfma_f32_16x16x32_bf16 v[62:65], v[170:173], v[210:213], v[62:65]
	v_mfma_f32_16x16x32_bf16 v[54:57], v[178:181], v[210:213], v[54:57]
	s_barrier
	s_setprio 0
	s_mov_b32 m0, s72
	s_mov_b64 s[98:99], s[54:55]
	s_add_u32 s46, s54, 0x40000
	ds_read_b128 v[182:185], v151 offset:16384
	ds_read_b128 v[186:189], v151 offset:17408
	ds_read_b128 v[190:193], v151 offset:18432
	ds_read_b128 v[194:197], v151 offset:19456
	ds_read_b128 v[198:201], v151 offset:20480
	ds_read_b128 v[202:205], v151 offset:21504
	ds_read_b128 v[206:209], v151 offset:22528
	global_load_lds_dwordx4 v134, s[54:55]
	s_mov_b32 m0, s73
	s_addc_u32 s47, s55, 0
	global_load_lds_dwordx4 v130, s[54:55]
	s_mov_b32 m0, s74
	s_mov_b64 s[100:101], s[64:65]
	global_load_lds_dwordx4 v134, s[46:47]
	s_mov_b32 m0, s75
	ds_read_b128 v[210:213], v151 offset:23552
	global_load_lds_dwordx4 v130, s[46:47]
	s_waitcnt vmcnt(6) lgkmcnt(0)
	s_setprio 1
	s_barrier
	v_mfma_f32_16x16x32_bf16 v[74:77], v[146:149], v[182:185], v[74:77]
	v_mfma_f32_16x16x32_bf16 v[66:69], v[158:161], v[182:185], v[66:69]
	v_mfma_f32_16x16x32_bf16 v[42:45], v[146:149], v[190:193], v[42:45]
	v_mfma_f32_16x16x32_bf16 v[34:37], v[158:161], v[190:193], v[34:37]
	v_mfma_f32_16x16x32_bf16 v[26:29], v[146:149], v[198:201], v[26:29]
	v_mfma_f32_16x16x32_bf16 v[18:21], v[158:161], v[198:201], v[18:21]
	v_mfma_f32_16x16x32_bf16 v[10:13], v[146:149], v[206:209], v[10:13]
	v_mfma_f32_16x16x32_bf16 v[2:5], v[158:161], v[206:209], v[2:5]
	v_mfma_f32_16x16x32_bf16 v[74:77], v[154:157], v[186:189], v[74:77]
	v_mfma_f32_16x16x32_bf16 v[66:69], v[162:165], v[186:189], v[66:69]
	v_mfma_f32_16x16x32_bf16 v[42:45], v[154:157], v[194:197], v[42:45]
	v_mfma_f32_16x16x32_bf16 v[34:37], v[162:165], v[194:197], v[34:37]
	v_mfma_f32_16x16x32_bf16 v[26:29], v[154:157], v[202:205], v[26:29]
	v_mfma_f32_16x16x32_bf16 v[18:21], v[162:165], v[202:205], v[18:21]
	v_mfma_f32_16x16x32_bf16 v[10:13], v[154:157], v[210:213], v[10:13]
	v_mfma_f32_16x16x32_bf16 v[2:5], v[162:165], v[210:213], v[2:5]
	s_setprio 0
	s_setprio 1
	v_mfma_f32_16x16x32_bf16 v[78:81], v[166:169], v[182:185], v[78:81]
	v_mfma_f32_16x16x32_bf16 v[70:73], v[174:177], v[182:185], v[70:73]
	v_mfma_f32_16x16x32_bf16 v[46:49], v[166:169], v[190:193], v[46:49]
	v_mfma_f32_16x16x32_bf16 v[38:41], v[174:177], v[190:193], v[38:41]
	v_mfma_f32_16x16x32_bf16 v[30:33], v[166:169], v[198:201], v[30:33]
	v_mfma_f32_16x16x32_bf16 v[22:25], v[174:177], v[198:201], v[22:25]
	v_mfma_f32_16x16x32_bf16 v[14:17], v[166:169], v[206:209], v[14:17]
	v_mfma_f32_16x16x32_bf16 v[6:9], v[174:177], v[206:209], v[6:9]
	v_mfma_f32_16x16x32_bf16 v[78:81], v[170:173], v[186:189], v[78:81]
	v_mfma_f32_16x16x32_bf16 v[70:73], v[178:181], v[186:189], v[70:73]
	v_mfma_f32_16x16x32_bf16 v[46:49], v[170:173], v[194:197], v[46:49]
	v_mfma_f32_16x16x32_bf16 v[38:41], v[178:181], v[194:197], v[38:41]
	v_mfma_f32_16x16x32_bf16 v[30:33], v[170:173], v[202:205], v[30:33]
	v_mfma_f32_16x16x32_bf16 v[22:25], v[178:181], v[202:205], v[22:25]
	v_mfma_f32_16x16x32_bf16 v[14:17], v[170:173], v[210:213], v[14:17]
	v_mfma_f32_16x16x32_bf16 v[6:9], v[178:181], v[210:213], v[6:9]
	s_barrier
; #define PG8_BAR __builtin_amdgcn_s_barrier()
;     ...
;         for (int t = 2; t < nt; t += 2) PG8_KITER(t);
;         if constexpr (ALIGN_EPI) { if (wr == 0) PG8_BAR; }
	s_setprio 0
	ds_read_b128 v[146:149], v152
	ds_read_b128 v[154:157], v152 offset:1024
	ds_read_b128 v[158:161], v152 offset:2048
	ds_read_b128 v[162:165], v152 offset:3072
	ds_read_b128 v[166:169], v153
	ds_read_b128 v[170:173], v153 offset:1024
	s_add_u32 s46, s64, 0x40000
	s_addc_u32 s47, s65, 0
	s_mov_b32 m0, s33
	ds_read_b128 v[178:181], v153 offset:3072
	global_load_lds_dwordx4 v136, s[100:101]
	s_mov_b32 m0, s41
	ds_read_b128 v[174:177], v153 offset:2048
	global_load_lds_dwordx4 v132, s[100:101]
	s_mov_b32 m0, s58
	ds_read_b128 v[182:185], v151 offset:32768
	ds_read_b128 v[186:189], v151 offset:33792
	ds_read_b128 v[190:193], v151 offset:34816
	ds_read_b128 v[194:197], v151 offset:35840
	ds_read_b128 v[198:201], v151 offset:36864
	ds_read_b128 v[202:205], v151 offset:37888
	ds_read_b128 v[206:209], v151 offset:38912
	global_load_lds_dwordx4 v136, s[46:47]
	s_mov_b32 m0, s59
	ds_read_b128 v[210:213], v151 offset:39936
	global_load_lds_dwordx4 v132, s[46:47]
	s_waitcnt vmcnt(8) lgkmcnt(0)
	s_setprio 1
	s_barrier
	v_mfma_f32_16x16x32_bf16 v[122:125], v[146:149], v[182:185], v[122:125]
	v_mfma_f32_16x16x32_bf16 v[114:117], v[158:161], v[182:185], v[114:117]
	v_mfma_f32_16x16x32_bf16 v[106:109], v[146:149], v[190:193], v[106:109]
	v_mfma_f32_16x16x32_bf16 v[98:101], v[158:161], v[190:193], v[98:101]
	v_mfma_f32_16x16x32_bf16 v[90:93], v[146:149], v[198:201], v[90:93]
	v_mfma_f32_16x16x32_bf16 v[82:85], v[158:161], v[198:201], v[82:85]
	v_mfma_f32_16x16x32_bf16 v[58:61], v[146:149], v[206:209], v[58:61]
	v_mfma_f32_16x16x32_bf16 v[50:53], v[158:161], v[206:209], v[50:53]
	v_mfma_f32_16x16x32_bf16 v[122:125], v[154:157], v[186:189], v[122:125]
	v_mfma_f32_16x16x32_bf16 v[114:117], v[162:165], v[186:189], v[114:117]
	v_mfma_f32_16x16x32_bf16 v[106:109], v[154:157], v[194:197], v[106:109]
	v_mfma_f32_16x16x32_bf16 v[98:101], v[162:165], v[194:197], v[98:101]
	v_mfma_f32_16x16x32_bf16 v[90:93], v[154:157], v[202:205], v[90:93]
	v_mfma_f32_16x16x32_bf16 v[82:85], v[162:165], v[202:205], v[82:85]
	v_mfma_f32_16x16x32_bf16 v[58:61], v[154:157], v[210:213], v[58:61]
	v_mfma_f32_16x16x32_bf16 v[50:53], v[162:165], v[210:213], v[50:53]
	s_setprio 0
	s_setprio 1
	v_mfma_f32_16x16x32_bf16 v[126:129], v[166:169], v[182:185], v[126:129]
	v_mfma_f32_16x16x32_bf16 v[118:121], v[174:177], v[182:185], v[118:121]
	v_mfma_f32_16x16x32_bf16 v[110:113], v[166:169], v[190:193], v[110:113]
	v_mfma_f32_16x16x32_bf16 v[102:105], v[174:177], v[190:193], v[102:105]
	v_mfma_f32_16x16x32_bf16 v[94:97], v[166:169], v[198:201], v[94:97]
	v_mfma_f32_16x16x32_bf16 v[86:89], v[174:177], v[198:201], v[86:89]
	v_mfma_f32_16x16x32_bf16 v[62:65], v[166:169], v[206:209], v[62:65]
	v_mfma_f32_16x16x32_bf16 v[54:57], v[174:177], v[206:209], v[54:57]
	v_mfma_f32_16x16x32_bf16 v[126:129], v[170:173], v[186:189], v[126:129]
	v_mfma_f32_16x16x32_bf16 v[118:121], v[178:181], v[186:189], v[118:121]
	v_mfma_f32_16x16x32_bf16 v[110:113], v[170:173], v[194:197], v[110:113]
	v_mfma_f32_16x16x32_bf16 v[102:105], v[178:181], v[194:197], v[102:105]
	v_mfma_f32_16x16x32_bf16 v[94:97], v[170:173], v[202:205], v[94:97]
	v_mfma_f32_16x16x32_bf16 v[86:89], v[178:181], v[202:205], v[86:89]
	v_mfma_f32_16x16x32_bf16 v[62:65], v[170:173], v[210:213], v[62:65]
	v_mfma_f32_16x16x32_bf16 v[54:57], v[178:181], v[210:213], v[54:57]
	s_barrier
	s_setprio 0
	s_mov_b32 m0, s76
	s_add_u32 s98, s98, 0x80
	s_addc_u32 s99, s99, 0
	s_add_u32 s100, s100, 0x80
	s_addc_u32 s101, s101, 0
	s_add_u32 s46, s54, 0x40080
	ds_read_b128 v[182:185], v151 offset:49152
	ds_read_b128 v[186:189], v151 offset:50176
	ds_read_b128 v[190:193], v151 offset:51200
	ds_read_b128 v[194:197], v151 offset:52224
	global_load_lds_dwordx4 v134, s[98:99]
	s_mov_b32 m0, s77
	s_addc_u32 s47, s55, 0
	global_load_lds_dwordx4 v130, s[98:99]
	s_mov_b32 m0, s78
	ds_read_b128 v[210:213], v151 offset:56320
	global_load_lds_dwordx4 v134, s[46:47]
	s_mov_b32 m0, s79
	ds_read_b128 v[206:209], v151 offset:55296
	global_load_lds_dwordx4 v130, s[46:47]
	s_mov_b32 m0, s66
	ds_read_b128 v[202:205], v151 offset:54272
	global_load_lds_dwordx4 v136, s[100:101]
	s_mov_b32 m0, s67
	ds_read_b128 v[198:201], v151 offset:53248
	global_load_lds_dwordx4 v132, s[100:101]
	s_waitcnt vmcnt(8) lgkmcnt(0)
	s_setprio 1
	s_barrier
	v_mfma_f32_16x16x32_bf16 v[74:77], v[146:149], v[182:185], v[74:77]
	v_mfma_f32_16x16x32_bf16 v[66:69], v[158:161], v[182:185], v[66:69]
	v_mfma_f32_16x16x32_bf16 v[42:45], v[146:149], v[190:193], v[42:45]
	v_mfma_f32_16x16x32_bf16 v[34:37], v[158:161], v[190:193], v[34:37]
	v_mfma_f32_16x16x32_bf16 v[26:29], v[146:149], v[198:201], v[26:29]
	v_mfma_f32_16x16x32_bf16 v[18:21], v[158:161], v[198:201], v[18:21]
	v_mfma_f32_16x16x32_bf16 v[10:13], v[146:149], v[206:209], v[10:13]
	v_mfma_f32_16x16x32_bf16 v[2:5], v[158:161], v[206:209], v[2:5]
	v_mfma_f32_16x16x32_bf16 v[74:77], v[154:157], v[186:189], v[74:77]
	v_mfma_f32_16x16x32_bf16 v[66:69], v[162:165], v[186:189], v[66:69]
	v_mfma_f32_16x16x32_bf16 v[42:45], v[154:157], v[194:197], v[42:45]
	v_mfma_f32_16x16x32_bf16 v[34:37], v[162:165], v[194:197], v[34:37]
	v_mfma_f32_16x16x32_bf16 v[26:29], v[154:157], v[202:205], v[26:29]
	v_mfma_f32_16x16x32_bf16 v[18:21], v[162:165], v[202:205], v[18:21]
	v_mfma_f32_16x16x32_bf16 v[10:13], v[154:157], v[210:213], v[10:13]
	v_mfma_f32_16x16x32_bf16 v[2:5], v[162:165], v[210:213], v[2:5]
	s_setprio 0
	s_setprio 1
	v_mfma_f32_16x16x32_bf16 v[78:81], v[166:169], v[182:185], v[78:81]
	v_mfma_f32_16x16x32_bf16 v[70:73], v[174:177], v[182:185], v[70:73]
	v_mfma_f32_16x16x32_bf16 v[46:49], v[166:169], v[190:193], v[46:49]
	v_mfma_f32_16x16x32_bf16 v[38:41], v[174:177], v[190:193], v[38:41]
	v_mfma_f32_16x16x32_bf16 v[30:33], v[166:169], v[198:201], v[30:33]
	v_mfma_f32_16x16x32_bf16 v[22:25], v[174:177], v[198:201], v[22:25]
	v_mfma_f32_16x16x32_bf16 v[14:17], v[166:169], v[206:209], v[14:17]
	v_mfma_f32_16x16x32_bf16 v[6:9], v[174:177], v[206:209], v[6:9]
	v_mfma_f32_16x16x32_bf16 v[78:81], v[170:173], v[186:189], v[78:81]
	v_mfma_f32_16x16x32_bf16 v[70:73], v[178:181], v[186:189], v[70:73]
	v_mfma_f32_16x16x32_bf16 v[46:49], v[170:173], v[194:197], v[46:49]
	v_mfma_f32_16x16x32_bf16 v[38:41], v[178:181], v[194:197], v[38:41]
	v_mfma_f32_16x16x32_bf16 v[30:33], v[170:173], v[202:205], v[30:33]
	v_mfma_f32_16x16x32_bf16 v[22:25], v[178:181], v[202:205], v[22:25]
	v_mfma_f32_16x16x32_bf16 v[14:17], v[170:173], v[210:213], v[14:17]
	v_mfma_f32_16x16x32_bf16 v[6:9], v[178:181], v[210:213], v[6:9]
	s_barrier
	s_setprio 0
	s_add_i32 s26, s26, 2
	s_add_u32 s62, s62, 0x100
	s_addc_u32 s63, s63, 0
	s_add_u32 s14, s14, 0x100
	s_addc_u32 s15, s15, 0
	s_cmp_gt_u32 s26, 13
	s_cbranch_scc0 .LBB0_644
	s_and_b64 vcc, exec, s[16:17]
	s_cbranch_vccz .LBB0_647
	s_barrier

.LBB0_670:
	ds_read_b128 v[132:135], v158
	ds_read_b128 v[154:157], v158 offset:1024
	ds_read_b128 v[162:165], v158 offset:2048
	ds_read_b128 v[166:169], v158 offset:3072
	ds_read_b128 v[170:173], v159
	ds_read_b128 v[174:177], v159 offset:1024
	ds_read_b128 v[178:181], v159 offset:2048
	ds_read_b128 v[182:185], v159 offset:3072
	s_add_u32 s6, s64, 0xfffe0080
	s_addc_u32 s7, s65, -1
	s_cmp_eq_u32 s26, 4
	s_cselect_b32 s67, s29, s7
	s_cselect_b32 s66, s79, s6
	s_cselect_b32 s7, s0, s15
	s_cselect_b32 s6, s80, s14
	s_mov_b32 m0, s81
	ds_read_b128 v[186:189], v160
	ds_read_b128 v[190:193], v160 offset:1024
	ds_read_b128 v[194:197], v160 offset:2048
	ds_read_b128 v[198:201], v160 offset:3072
	ds_read_b128 v[202:205], v160 offset:4096
	ds_read_b128 v[206:209], v160 offset:5120
	ds_read_b128 v[210:213], v160 offset:6144
	global_load_lds_dwordx4 v146, s[64:65]
	s_mov_b32 m0, s82
	ds_read_b128 v[214:217], v160 offset:7168
	global_load_lds_dwordx4 v148, s[64:65]
	s_waitcnt vmcnt(8) lgkmcnt(0)
	s_setprio 1
	s_barrier
	v_mfma_f32_16x16x32_bf16 v[118:121], v[132:135], v[186:189], v[118:121]
	v_mfma_f32_16x16x32_bf16 v[114:117], v[162:165], v[186:189], v[114:117]
	v_mfma_f32_16x16x32_bf16 v[110:113], v[132:135], v[194:197], v[110:113]
	v_mfma_f32_16x16x32_bf16 v[98:101], v[162:165], v[194:197], v[98:101]
	v_mfma_f32_16x16x32_bf16 v[94:97], v[132:135], v[202:205], v[94:97]
	v_mfma_f32_16x16x32_bf16 v[90:93], v[162:165], v[202:205], v[90:93]
	v_mfma_f32_16x16x32_bf16 v[78:81], v[132:135], v[210:213], v[78:81]
	v_mfma_f32_16x16x32_bf16 v[70:73], v[162:165], v[210:213], v[70:73]
	v_mfma_f32_16x16x32_bf16 v[118:121], v[154:157], v[190:193], v[118:121]
	v_mfma_f32_16x16x32_bf16 v[114:117], v[166:169], v[190:193], v[114:117]
	v_mfma_f32_16x16x32_bf16 v[110:113], v[154:157], v[198:201], v[110:113]
	v_mfma_f32_16x16x32_bf16 v[98:101], v[166:169], v[198:201], v[98:101]
	v_mfma_f32_16x16x32_bf16 v[94:97], v[154:157], v[206:209], v[94:97]
	v_mfma_f32_16x16x32_bf16 v[90:93], v[166:169], v[206:209], v[90:93]
	v_mfma_f32_16x16x32_bf16 v[78:81], v[154:157], v[214:217], v[78:81]
	v_mfma_f32_16x16x32_bf16 v[70:73], v[166:169], v[214:217], v[70:73]
	s_setprio 0
	s_setprio 1
	v_mfma_f32_16x16x32_bf16 v[126:129], v[170:173], v[186:189], v[126:129]
	v_mfma_f32_16x16x32_bf16 v[122:125], v[178:181], v[186:189], v[122:125]
	v_mfma_f32_16x16x32_bf16 v[106:109], v[170:173], v[194:197], v[106:109]
	v_mfma_f32_16x16x32_bf16 v[102:105], v[178:181], v[194:197], v[102:105]
	v_mfma_f32_16x16x32_bf16 v[86:89], v[170:173], v[202:205], v[86:89]
	v_mfma_f32_16x16x32_bf16 v[82:85], v[178:181], v[202:205], v[82:85]
	v_mfma_f32_16x16x32_bf16 v[62:65], v[170:173], v[210:213], v[62:65]
	v_mfma_f32_16x16x32_bf16 v[58:61], v[178:181], v[210:213], v[58:61]
	v_mfma_f32_16x16x32_bf16 v[126:129], v[174:177], v[190:193], v[126:129]
	v_mfma_f32_16x16x32_bf16 v[122:125], v[182:185], v[190:193], v[122:125]
	v_mfma_f32_16x16x32_bf16 v[106:109], v[174:177], v[198:201], v[106:109]
	v_mfma_f32_16x16x32_bf16 v[102:105], v[182:185], v[198:201], v[102:105]
	v_mfma_f32_16x16x32_bf16 v[86:89], v[174:177], v[206:209], v[86:89]
	v_mfma_f32_16x16x32_bf16 v[82:85], v[182:185], v[206:209], v[82:85]
	v_mfma_f32_16x16x32_bf16 v[62:65], v[174:177], v[214:217], v[62:65]
	v_mfma_f32_16x16x32_bf16 v[58:61], v[182:185], v[214:217], v[58:61]
	s_barrier
	s_setprio 0
	s_mov_b32 m0, s83
	s_mov_b64 s[98:99], s[6:7]
	s_add_u32 s88, s6, 0x20000
	ds_read_b128 v[186:189], v160 offset:16384
	ds_read_b128 v[190:193], v160 offset:17408
	ds_read_b128 v[194:197], v160 offset:18432
	ds_read_b128 v[198:201], v160 offset:19456
	ds_read_b128 v[202:205], v160 offset:20480
	ds_read_b128 v[206:209], v160 offset:21504
	ds_read_b128 v[210:213], v160 offset:22528
	global_load_lds_dwordx4 v140, s[6:7]
	s_mov_b32 m0, s84
	s_addc_u32 s89, s7, 0
	global_load_lds_dwordx4 v144, s[6:7]
	s_mov_b32 m0, s85
	s_mov_b64 s[100:101], s[66:67]
	global_load_lds_dwordx4 v140, s[88:89]
	s_mov_b32 m0, s46
	ds_read_b128 v[214:217], v160 offset:23552
	global_load_lds_dwordx4 v144, s[88:89]
	s_waitcnt vmcnt(6) lgkmcnt(0)
	s_setprio 1
	s_barrier
	v_mfma_f32_16x16x32_bf16 v[74:77], v[132:135], v[186:189], v[74:77]
	v_mfma_f32_16x16x32_bf16 v[66:69], v[162:165], v[186:189], v[66:69]
	v_mfma_f32_16x16x32_bf16 v[46:49], v[132:135], v[194:197], v[46:49]
	v_mfma_f32_16x16x32_bf16 v[42:45], v[162:165], v[194:197], v[42:45]
	v_mfma_f32_16x16x32_bf16 v[30:33], v[132:135], v[202:205], v[30:33]
	v_mfma_f32_16x16x32_bf16 v[26:29], v[162:165], v[202:205], v[26:29]
	v_mfma_f32_16x16x32_bf16 v[14:17], v[132:135], v[210:213], v[14:17]
	v_mfma_f32_16x16x32_bf16 v[10:13], v[162:165], v[210:213], v[10:13]
	v_mfma_f32_16x16x32_bf16 v[74:77], v[154:157], v[190:193], v[74:77]
	v_mfma_f32_16x16x32_bf16 v[66:69], v[166:169], v[190:193], v[66:69]
	v_mfma_f32_16x16x32_bf16 v[46:49], v[154:157], v[198:201], v[46:49]
	v_mfma_f32_16x16x32_bf16 v[42:45], v[166:169], v[198:201], v[42:45]
	v_mfma_f32_16x16x32_bf16 v[30:33], v[154:157], v[206:209], v[30:33]
	v_mfma_f32_16x16x32_bf16 v[26:29], v[166:169], v[206:209], v[26:29]
	v_mfma_f32_16x16x32_bf16 v[14:17], v[154:157], v[214:217], v[14:17]
	v_mfma_f32_16x16x32_bf16 v[10:13], v[166:169], v[214:217], v[10:13]
	s_setprio 0
	s_setprio 1
	v_mfma_f32_16x16x32_bf16 v[54:57], v[170:173], v[186:189], v[54:57]
	v_mfma_f32_16x16x32_bf16 v[50:53], v[178:181], v[186:189], v[50:53]
	v_mfma_f32_16x16x32_bf16 v[38:41], v[170:173], v[194:197], v[38:41]
	v_mfma_f32_16x16x32_bf16 v[34:37], v[178:181], v[194:197], v[34:37]
	v_mfma_f32_16x16x32_bf16 v[22:25], v[170:173], v[202:205], v[22:25]
	v_mfma_f32_16x16x32_bf16 v[18:21], v[178:181], v[202:205], v[18:21]
	v_mfma_f32_16x16x32_bf16 v[6:9], v[170:173], v[210:213], v[6:9]
	v_mfma_f32_16x16x32_bf16 v[2:5], v[178:181], v[210:213], v[2:5]
	v_mfma_f32_16x16x32_bf16 v[54:57], v[174:177], v[190:193], v[54:57]
	v_mfma_f32_16x16x32_bf16 v[50:53], v[182:185], v[190:193], v[50:53]
	v_mfma_f32_16x16x32_bf16 v[38:41], v[174:177], v[198:201], v[38:41]
	v_mfma_f32_16x16x32_bf16 v[34:37], v[182:185], v[198:201], v[34:37]
	v_mfma_f32_16x16x32_bf16 v[22:25], v[174:177], v[206:209], v[22:25]
	v_mfma_f32_16x16x32_bf16 v[18:21], v[182:185], v[206:209], v[18:21]
	v_mfma_f32_16x16x32_bf16 v[6:9], v[174:177], v[214:217], v[6:9]
	v_mfma_f32_16x16x32_bf16 v[2:5], v[182:185], v[214:217], v[2:5]
	s_barrier
; #define PG8_BAR __builtin_amdgcn_s_barrier()
;     ...
;         for (int t = 2; t < nt; t += 2) PG8_KITER(t);
;         if constexpr (ALIGN_EPI) { if (wr == 0) PG8_BAR; }
	s_setprio 0
	ds_read_b128 v[132:135], v130
	ds_read_b128 v[154:157], v130 offset:1024
	ds_read_b128 v[162:165], v130 offset:2048
	ds_read_b128 v[166:169], v130 offset:3072
	ds_read_b128 v[170:173], v131
	ds_read_b128 v[174:177], v131 offset:1024
	s_add_u32 s66, s66, 0x20000
	s_addc_u32 s67, s67, 0
	s_mov_b32 m0, s58
	ds_read_b128 v[182:185], v131 offset:3072
	global_load_lds_dwordx4 v138, s[100:101]
	s_mov_b32 m0, s59
	ds_read_b128 v[178:181], v131 offset:2048
	global_load_lds_dwordx4 v142, s[100:101]
	s_mov_b32 m0, s63
	ds_read_b128 v[186:189], v160 offset:32768
	ds_read_b128 v[190:193], v160 offset:33792
	ds_read_b128 v[194:197], v160 offset:34816
	ds_read_b128 v[198:201], v160 offset:35840
	ds_read_b128 v[202:205], v160 offset:36864
	ds_read_b128 v[206:209], v160 offset:37888
	ds_read_b128 v[210:213], v160 offset:38912
	global_load_lds_dwordx4 v138, s[66:67]
	s_mov_b32 m0, s68
	ds_read_b128 v[214:217], v160 offset:39936
	global_load_lds_dwordx4 v142, s[66:67]
	s_waitcnt vmcnt(8) lgkmcnt(0)
	s_setprio 1
	s_barrier
	v_mfma_f32_16x16x32_bf16 v[118:121], v[132:135], v[186:189], v[118:121]
	v_mfma_f32_16x16x32_bf16 v[114:117], v[162:165], v[186:189], v[114:117]
	v_mfma_f32_16x16x32_bf16 v[110:113], v[132:135], v[194:197], v[110:113]
	v_mfma_f32_16x16x32_bf16 v[98:101], v[162:165], v[194:197], v[98:101]
	v_mfma_f32_16x16x32_bf16 v[94:97], v[132:135], v[202:205], v[94:97]
	v_mfma_f32_16x16x32_bf16 v[90:93], v[162:165], v[202:205], v[90:93]
	v_mfma_f32_16x16x32_bf16 v[78:81], v[132:135], v[210:213], v[78:81]
	v_mfma_f32_16x16x32_bf16 v[70:73], v[162:165], v[210:213], v[70:73]
	v_mfma_f32_16x16x32_bf16 v[118:121], v[154:157], v[190:193], v[118:121]
	v_mfma_f32_16x16x32_bf16 v[114:117], v[166:169], v[190:193], v[114:117]
	v_mfma_f32_16x16x32_bf16 v[110:113], v[154:157], v[198:201], v[110:113]
	v_mfma_f32_16x16x32_bf16 v[98:101], v[166:169], v[198:201], v[98:101]
	v_mfma_f32_16x16x32_bf16 v[94:97], v[154:157], v[206:209], v[94:97]
	v_mfma_f32_16x16x32_bf16 v[90:93], v[166:169], v[206:209], v[90:93]
	v_mfma_f32_16x16x32_bf16 v[78:81], v[154:157], v[214:217], v[78:81]
	v_mfma_f32_16x16x32_bf16 v[70:73], v[166:169], v[214:217], v[70:73]
	s_setprio 0
	s_setprio 1
	v_mfma_f32_16x16x32_bf16 v[126:129], v[170:173], v[186:189], v[126:129]
	v_mfma_f32_16x16x32_bf16 v[122:125], v[178:181], v[186:189], v[122:125]
	v_mfma_f32_16x16x32_bf16 v[106:109], v[170:173], v[194:197], v[106:109]
	v_mfma_f32_16x16x32_bf16 v[102:105], v[178:181], v[194:197], v[102:105]
	v_mfma_f32_16x16x32_bf16 v[86:89], v[170:173], v[202:205], v[86:89]
	v_mfma_f32_16x16x32_bf16 v[82:85], v[178:181], v[202:205], v[82:85]
	v_mfma_f32_16x16x32_bf16 v[62:65], v[170:173], v[210:213], v[62:65]
	v_mfma_f32_16x16x32_bf16 v[58:61], v[178:181], v[210:213], v[58:61]
	v_mfma_f32_16x16x32_bf16 v[126:129], v[174:177], v[190:193], v[126:129]
	v_mfma_f32_16x16x32_bf16 v[122:125], v[182:185], v[190:193], v[122:125]
	v_mfma_f32_16x16x32_bf16 v[106:109], v[174:177], v[198:201], v[106:109]
	v_mfma_f32_16x16x32_bf16 v[102:105], v[182:185], v[198:201], v[102:105]
	v_mfma_f32_16x16x32_bf16 v[86:89], v[174:177], v[206:209], v[86:89]
	v_mfma_f32_16x16x32_bf16 v[82:85], v[182:185], v[206:209], v[82:85]
	v_mfma_f32_16x16x32_bf16 v[62:65], v[174:177], v[214:217], v[62:65]
	v_mfma_f32_16x16x32_bf16 v[58:61], v[182:185], v[214:217], v[58:61]
	s_barrier
	s_setprio 0
	s_mov_b32 m0, s47
	s_add_u32 s98, s98, 0x80
	s_addc_u32 s99, s99, 0
	s_add_u32 s100, s100, 0x80
	s_addc_u32 s101, s101, 0
	s_add_u32 s6, s6, 0x20080
	ds_read_b128 v[186:189], v160 offset:49152
	ds_read_b128 v[190:193], v160 offset:50176
	ds_read_b128 v[194:197], v160 offset:51200
	ds_read_b128 v[198:201], v160 offset:52224
	global_load_lds_dwordx4 v140, s[98:99]
	s_mov_b32 m0, s86
	s_addc_u32 s7, s7, 0
	global_load_lds_dwordx4 v144, s[98:99]
	s_mov_b32 m0, s56
	ds_read_b128 v[214:217], v160 offset:56320
	global_load_lds_dwordx4 v140, s[6:7]
	s_mov_b32 m0, s57
	ds_read_b128 v[210:213], v160 offset:55296
	global_load_lds_dwordx4 v144, s[6:7]
	s_mov_b32 m0, s69
	ds_read_b128 v[206:209], v160 offset:54272
	global_load_lds_dwordx4 v138, s[100:101]
	s_mov_b32 m0, s70
	ds_read_b128 v[202:205], v160 offset:53248
	global_load_lds_dwordx4 v142, s[100:101]
	s_waitcnt vmcnt(8) lgkmcnt(0)
	s_setprio 1
	s_barrier
	v_mfma_f32_16x16x32_bf16 v[74:77], v[132:135], v[186:189], v[74:77]
	v_mfma_f32_16x16x32_bf16 v[66:69], v[162:165], v[186:189], v[66:69]
	v_mfma_f32_16x16x32_bf16 v[46:49], v[132:135], v[194:197], v[46:49]
	v_mfma_f32_16x16x32_bf16 v[42:45], v[162:165], v[194:197], v[42:45]
	v_mfma_f32_16x16x32_bf16 v[30:33], v[132:135], v[202:205], v[30:33]
	v_mfma_f32_16x16x32_bf16 v[26:29], v[162:165], v[202:205], v[26:29]
	v_mfma_f32_16x16x32_bf16 v[14:17], v[132:135], v[210:213], v[14:17]
	v_mfma_f32_16x16x32_bf16 v[10:13], v[162:165], v[210:213], v[10:13]
	v_mfma_f32_16x16x32_bf16 v[74:77], v[154:157], v[190:193], v[74:77]
	v_mfma_f32_16x16x32_bf16 v[66:69], v[166:169], v[190:193], v[66:69]
	v_mfma_f32_16x16x32_bf16 v[46:49], v[154:157], v[198:201], v[46:49]
	v_mfma_f32_16x16x32_bf16 v[42:45], v[166:169], v[198:201], v[42:45]
	v_mfma_f32_16x16x32_bf16 v[30:33], v[154:157], v[206:209], v[30:33]
	v_mfma_f32_16x16x32_bf16 v[26:29], v[166:169], v[206:209], v[26:29]
	v_mfma_f32_16x16x32_bf16 v[14:17], v[154:157], v[214:217], v[14:17]
	v_mfma_f32_16x16x32_bf16 v[10:13], v[166:169], v[214:217], v[10:13]
	s_setprio 0
	s_setprio 1
	v_mfma_f32_16x16x32_bf16 v[54:57], v[170:173], v[186:189], v[54:57]
	v_mfma_f32_16x16x32_bf16 v[50:53], v[178:181], v[186:189], v[50:53]
	v_mfma_f32_16x16x32_bf16 v[38:41], v[170:173], v[194:197], v[38:41]
	v_mfma_f32_16x16x32_bf16 v[34:37], v[178:181], v[194:197], v[34:37]
	v_mfma_f32_16x16x32_bf16 v[22:25], v[170:173], v[202:205], v[22:25]
	v_mfma_f32_16x16x32_bf16 v[18:21], v[178:181], v[202:205], v[18:21]
	v_mfma_f32_16x16x32_bf16 v[6:9], v[170:173], v[210:213], v[6:9]
	v_mfma_f32_16x16x32_bf16 v[2:5], v[178:181], v[210:213], v[2:5]
	v_mfma_f32_16x16x32_bf16 v[54:57], v[174:177], v[190:193], v[54:57]
	v_mfma_f32_16x16x32_bf16 v[50:53], v[182:185], v[190:193], v[50:53]
	v_mfma_f32_16x16x32_bf16 v[38:41], v[174:177], v[198:201], v[38:41]
	v_mfma_f32_16x16x32_bf16 v[34:37], v[182:185], v[198:201], v[34:37]
	v_mfma_f32_16x16x32_bf16 v[22:25], v[174:177], v[206:209], v[22:25]
	v_mfma_f32_16x16x32_bf16 v[18:21], v[182:185], v[206:209], v[18:21]
	v_mfma_f32_16x16x32_bf16 v[6:9], v[174:177], v[214:217], v[6:9]
	v_mfma_f32_16x16x32_bf16 v[2:5], v[182:185], v[214:217], v[2:5]
	s_barrier
	s_setprio 0
	s_add_i32 s26, s26, 2
	s_add_u32 s64, s64, 0x100
	s_addc_u32 s65, s65, 0
	s_add_u32 s14, s14, 0x100
	s_addc_u32 s15, s15, 0
	s_cmp_gt_u32 s26, 5
	s_cbranch_scc0 .LBB0_670
	s_and_b64 vcc, exec, s[18:19]
	s_cbranch_vccz .LBB0_673
	s_barrier

.LBB0_716:
	ds_read_b128 v[132:135], v164
	ds_read_b128 v[136:139], v164 offset:1024
	ds_read_b128 v[140:143], v164 offset:2048
	ds_read_b128 v[168:171], v164 offset:3072
	ds_read_b128 v[172:175], v165
	ds_read_b128 v[176:179], v165 offset:1024
	ds_read_b128 v[180:183], v165 offset:2048
	ds_read_b128 v[184:187], v165 offset:3072
	s_add_u32 s27, s62, 0xfff80080
	s_addc_u32 s50, s63, -1
	s_cmp_eq_u32 s26, 4
	s_cselect_b32 s65, s1, s50
	s_cselect_b32 s64, s0, s27
	s_cselect_b32 s51, s29, s15
	s_cselect_b32 s50, s28, s14
	s_mov_b32 m0, s23
	ds_read_b128 v[188:191], v166
	ds_read_b128 v[192:195], v166 offset:1024
	ds_read_b128 v[196:199], v166 offset:2048
	ds_read_b128 v[200:203], v166 offset:3072
	ds_read_b128 v[204:207], v166 offset:4096
	ds_read_b128 v[208:211], v166 offset:5120
	ds_read_b128 v[212:215], v166 offset:6144
	global_load_lds_dwordx4 v154, s[62:63]
	s_mov_b32 m0, s77
	ds_read_b128 v[216:219], v166 offset:7168
	global_load_lds_dwordx4 v156, s[62:63]
	s_waitcnt vmcnt(8) lgkmcnt(0)
	s_setprio 1
	s_barrier
	v_mfma_f32_16x16x32_bf16 v[102:105], v[132:135], v[188:191], v[102:105]
	v_mfma_f32_16x16x32_bf16 v[98:101], v[140:143], v[188:191], v[98:101]
	v_mfma_f32_16x16x32_bf16 v[94:97], v[132:135], v[196:199], v[94:97]
	v_mfma_f32_16x16x32_bf16 v[90:93], v[140:143], v[196:199], v[90:93]
	v_mfma_f32_16x16x32_bf16 v[86:89], v[132:135], v[204:207], v[86:89]
	v_mfma_f32_16x16x32_bf16 v[82:85], v[140:143], v[204:207], v[82:85]
	v_mfma_f32_16x16x32_bf16 v[78:81], v[132:135], v[212:215], v[78:81]
	v_mfma_f32_16x16x32_bf16 v[62:65], v[140:143], v[212:215], v[62:65]
	v_mfma_f32_16x16x32_bf16 v[102:105], v[136:139], v[192:195], v[102:105]
	v_mfma_f32_16x16x32_bf16 v[98:101], v[168:171], v[192:195], v[98:101]
	v_mfma_f32_16x16x32_bf16 v[94:97], v[136:139], v[200:203], v[94:97]
	v_mfma_f32_16x16x32_bf16 v[90:93], v[168:171], v[200:203], v[90:93]
	v_mfma_f32_16x16x32_bf16 v[86:89], v[136:139], v[208:211], v[86:89]
	v_mfma_f32_16x16x32_bf16 v[82:85], v[168:171], v[208:211], v[82:85]
	v_mfma_f32_16x16x32_bf16 v[78:81], v[136:139], v[216:219], v[78:81]
	v_mfma_f32_16x16x32_bf16 v[62:65], v[168:171], v[216:219], v[62:65]
	s_setprio 0
	s_setprio 1
	v_mfma_f32_16x16x32_bf16 v[126:129], v[172:175], v[188:191], v[126:129]
	v_mfma_f32_16x16x32_bf16 v[122:125], v[180:183], v[188:191], v[122:125]
	v_mfma_f32_16x16x32_bf16 v[118:121], v[172:175], v[196:199], v[118:121]
	v_mfma_f32_16x16x32_bf16 v[114:117], v[180:183], v[196:199], v[114:117]
	v_mfma_f32_16x16x32_bf16 v[110:113], v[172:175], v[204:207], v[110:113]
	v_mfma_f32_16x16x32_bf16 v[106:109], v[180:183], v[204:207], v[106:109]
	v_mfma_f32_16x16x32_bf16 v[54:57], v[172:175], v[212:215], v[54:57]
	v_mfma_f32_16x16x32_bf16 v[50:53], v[180:183], v[212:215], v[50:53]
	v_mfma_f32_16x16x32_bf16 v[126:129], v[176:179], v[192:195], v[126:129]
	v_mfma_f32_16x16x32_bf16 v[122:125], v[184:187], v[192:195], v[122:125]
	v_mfma_f32_16x16x32_bf16 v[118:121], v[176:179], v[200:203], v[118:121]
	v_mfma_f32_16x16x32_bf16 v[114:117], v[184:187], v[200:203], v[114:117]
	v_mfma_f32_16x16x32_bf16 v[110:113], v[176:179], v[208:211], v[110:113]
	v_mfma_f32_16x16x32_bf16 v[106:109], v[184:187], v[208:211], v[106:109]
	v_mfma_f32_16x16x32_bf16 v[54:57], v[176:179], v[216:219], v[54:57]
	v_mfma_f32_16x16x32_bf16 v[50:53], v[184:187], v[216:219], v[50:53]
	s_barrier
	s_setprio 0
	s_mov_b32 m0, s78
	s_mov_b64 s[98:99], s[50:51]
	s_add_u32 s82, s50, 0x80000
	ds_read_b128 v[188:191], v166 offset:16384
	ds_read_b128 v[192:195], v166 offset:17408
	ds_read_b128 v[196:199], v166 offset:18432
	ds_read_b128 v[200:203], v166 offset:19456
	ds_read_b128 v[204:207], v166 offset:20480
	ds_read_b128 v[208:211], v166 offset:21504
	ds_read_b128 v[212:215], v166 offset:22528
	global_load_lds_dwordx4 v148, s[50:51]
	s_mov_b32 m0, s79
	s_addc_u32 s83, s51, 0
	global_load_lds_dwordx4 v152, s[50:51]
	s_mov_b32 m0, s80
	s_mov_b64 s[100:101], s[64:65]
	global_load_lds_dwordx4 v148, s[82:83]
	s_mov_b32 m0, s46
	ds_read_b128 v[216:219], v166 offset:23552
	global_load_lds_dwordx4 v152, s[82:83]
	s_waitcnt vmcnt(6) lgkmcnt(0)
	s_setprio 1
	s_barrier
	v_mfma_f32_16x16x32_bf16 v[74:77], v[132:135], v[188:191], v[74:77]
	v_mfma_f32_16x16x32_bf16 v[70:73], v[140:143], v[188:191], v[70:73]
	v_mfma_f32_16x16x32_bf16 v[46:49], v[132:135], v[196:199], v[46:49]
	v_mfma_f32_16x16x32_bf16 v[42:45], v[140:143], v[196:199], v[42:45]
	v_mfma_f32_16x16x32_bf16 v[30:33], v[132:135], v[204:207], v[30:33]
	v_mfma_f32_16x16x32_bf16 v[26:29], v[140:143], v[204:207], v[26:29]
	v_mfma_f32_16x16x32_bf16 v[14:17], v[132:135], v[212:215], v[14:17]
	v_mfma_f32_16x16x32_bf16 v[10:13], v[140:143], v[212:215], v[10:13]
	v_mfma_f32_16x16x32_bf16 v[74:77], v[136:139], v[192:195], v[74:77]
	v_mfma_f32_16x16x32_bf16 v[70:73], v[168:171], v[192:195], v[70:73]
	v_mfma_f32_16x16x32_bf16 v[46:49], v[136:139], v[200:203], v[46:49]
	v_mfma_f32_16x16x32_bf16 v[42:45], v[168:171], v[200:203], v[42:45]
	v_mfma_f32_16x16x32_bf16 v[30:33], v[136:139], v[208:211], v[30:33]
	v_mfma_f32_16x16x32_bf16 v[26:29], v[168:171], v[208:211], v[26:29]
	v_mfma_f32_16x16x32_bf16 v[14:17], v[136:139], v[216:219], v[14:17]
	v_mfma_f32_16x16x32_bf16 v[10:13], v[168:171], v[216:219], v[10:13]
	s_setprio 0
	s_setprio 1
	v_mfma_f32_16x16x32_bf16 v[66:69], v[172:175], v[188:191], v[66:69]
	v_mfma_f32_16x16x32_bf16 v[58:61], v[180:183], v[188:191], v[58:61]
	v_mfma_f32_16x16x32_bf16 v[38:41], v[172:175], v[196:199], v[38:41]
	v_mfma_f32_16x16x32_bf16 v[34:37], v[180:183], v[196:199], v[34:37]
	v_mfma_f32_16x16x32_bf16 v[22:25], v[172:175], v[204:207], v[22:25]
	v_mfma_f32_16x16x32_bf16 v[18:21], v[180:183], v[204:207], v[18:21]
	v_mfma_f32_16x16x32_bf16 v[6:9], v[172:175], v[212:215], v[6:9]
	v_mfma_f32_16x16x32_bf16 v[2:5], v[180:183], v[212:215], v[2:5]
	v_mfma_f32_16x16x32_bf16 v[66:69], v[176:179], v[192:195], v[66:69]
	v_mfma_f32_16x16x32_bf16 v[58:61], v[184:187], v[192:195], v[58:61]
	v_mfma_f32_16x16x32_bf16 v[38:41], v[176:179], v[200:203], v[38:41]
	v_mfma_f32_16x16x32_bf16 v[34:37], v[184:187], v[200:203], v[34:37]
	v_mfma_f32_16x16x32_bf16 v[22:25], v[176:179], v[208:211], v[22:25]
	v_mfma_f32_16x16x32_bf16 v[18:21], v[184:187], v[208:211], v[18:21]
	v_mfma_f32_16x16x32_bf16 v[6:9], v[176:179], v[216:219], v[6:9]
	v_mfma_f32_16x16x32_bf16 v[2:5], v[184:187], v[216:219], v[2:5]
	s_barrier
; #define PG8_BAR __builtin_amdgcn_s_barrier()
;     ...
;         for (int t = 2; t < nt; t += 2) PG8_KITER(t);
;         if constexpr (ALIGN_EPI) { if (wr == 0) PG8_BAR; }
	s_setprio 0
	ds_read_b128 v[132:135], v130
	ds_read_b128 v[136:139], v130 offset:1024
	ds_read_b128 v[140:143], v130 offset:2048
	ds_read_b128 v[168:171], v130 offset:3072
	ds_read_b128 v[172:175], v131
	ds_read_b128 v[176:179], v131 offset:1024
	s_add_u32 s64, s64, 0x80000
	s_addc_u32 s65, s65, 0
	s_mov_b32 m0, s59
	ds_read_b128 v[184:187], v131 offset:3072
	global_load_lds_dwordx4 v146, s[100:101]
	s_mov_b32 m0, s31
	ds_read_b128 v[180:183], v131 offset:2048
	global_load_lds_dwordx4 v150, s[100:101]
	s_mov_b32 m0, s66
	ds_read_b128 v[188:191], v166 offset:32768
	ds_read_b128 v[192:195], v166 offset:33792
	ds_read_b128 v[196:199], v166 offset:34816
	ds_read_b128 v[200:203], v166 offset:35840
	ds_read_b128 v[204:207], v166 offset:36864
	ds_read_b128 v[208:211], v166 offset:37888
	ds_read_b128 v[212:215], v166 offset:38912
	global_load_lds_dwordx4 v146, s[64:65]
	s_mov_b32 m0, s67
	ds_read_b128 v[216:219], v166 offset:39936
	global_load_lds_dwordx4 v150, s[64:65]
	s_waitcnt vmcnt(8) lgkmcnt(0)
	s_setprio 1
	s_barrier
	v_mfma_f32_16x16x32_bf16 v[102:105], v[132:135], v[188:191], v[102:105]
	v_mfma_f32_16x16x32_bf16 v[98:101], v[140:143], v[188:191], v[98:101]
	v_mfma_f32_16x16x32_bf16 v[94:97], v[132:135], v[196:199], v[94:97]
	v_mfma_f32_16x16x32_bf16 v[90:93], v[140:143], v[196:199], v[90:93]
	v_mfma_f32_16x16x32_bf16 v[86:89], v[132:135], v[204:207], v[86:89]
	v_mfma_f32_16x16x32_bf16 v[82:85], v[140:143], v[204:207], v[82:85]
	v_mfma_f32_16x16x32_bf16 v[78:81], v[132:135], v[212:215], v[78:81]
	v_mfma_f32_16x16x32_bf16 v[62:65], v[140:143], v[212:215], v[62:65]
	v_mfma_f32_16x16x32_bf16 v[102:105], v[136:139], v[192:195], v[102:105]
	v_mfma_f32_16x16x32_bf16 v[98:101], v[168:171], v[192:195], v[98:101]
	v_mfma_f32_16x16x32_bf16 v[94:97], v[136:139], v[200:203], v[94:97]
	v_mfma_f32_16x16x32_bf16 v[90:93], v[168:171], v[200:203], v[90:93]
	v_mfma_f32_16x16x32_bf16 v[86:89], v[136:139], v[208:211], v[86:89]
	v_mfma_f32_16x16x32_bf16 v[82:85], v[168:171], v[208:211], v[82:85]
	v_mfma_f32_16x16x32_bf16 v[78:81], v[136:139], v[216:219], v[78:81]
	v_mfma_f32_16x16x32_bf16 v[62:65], v[168:171], v[216:219], v[62:65]
	s_setprio 0
	s_setprio 1
	v_mfma_f32_16x16x32_bf16 v[126:129], v[172:175], v[188:191], v[126:129]
	v_mfma_f32_16x16x32_bf16 v[122:125], v[180:183], v[188:191], v[122:125]
	v_mfma_f32_16x16x32_bf16 v[118:121], v[172:175], v[196:199], v[118:121]
	v_mfma_f32_16x16x32_bf16 v[114:117], v[180:183], v[196:199], v[114:117]
	v_mfma_f32_16x16x32_bf16 v[110:113], v[172:175], v[204:207], v[110:113]
	v_mfma_f32_16x16x32_bf16 v[106:109], v[180:183], v[204:207], v[106:109]
	v_mfma_f32_16x16x32_bf16 v[54:57], v[172:175], v[212:215], v[54:57]
	v_mfma_f32_16x16x32_bf16 v[50:53], v[180:183], v[212:215], v[50:53]
	v_mfma_f32_16x16x32_bf16 v[126:129], v[176:179], v[192:195], v[126:129]
	v_mfma_f32_16x16x32_bf16 v[122:125], v[184:187], v[192:195], v[122:125]
	v_mfma_f32_16x16x32_bf16 v[118:121], v[176:179], v[200:203], v[118:121]
	v_mfma_f32_16x16x32_bf16 v[114:117], v[184:187], v[200:203], v[114:117]
	v_mfma_f32_16x16x32_bf16 v[110:113], v[176:179], v[208:211], v[110:113]
	v_mfma_f32_16x16x32_bf16 v[106:109], v[184:187], v[208:211], v[106:109]
	v_mfma_f32_16x16x32_bf16 v[54:57], v[176:179], v[216:219], v[54:57]
	v_mfma_f32_16x16x32_bf16 v[50:53], v[184:187], v[216:219], v[50:53]
	s_barrier
	s_setprio 0
	s_mov_b32 m0, s47
	s_add_u32 s98, s98, 0x80
	s_addc_u32 s99, s99, 0
	s_add_u32 s100, s100, 0x80
	s_addc_u32 s101, s101, 0
	s_add_u32 s50, s50, 0x80080
	ds_read_b128 v[188:191], v166 offset:49152
	ds_read_b128 v[192:195], v166 offset:50176
	ds_read_b128 v[196:199], v166 offset:51200
	ds_read_b128 v[200:203], v166 offset:52224
	global_load_lds_dwordx4 v148, s[98:99]
	s_mov_b32 m0, s81
	s_addc_u32 s51, s51, 0
	global_load_lds_dwordx4 v152, s[98:99]
	s_mov_b32 m0, s56
	ds_read_b128 v[216:219], v166 offset:56320
	global_load_lds_dwordx4 v148, s[50:51]
	s_mov_b32 m0, s57
	ds_read_b128 v[212:215], v166 offset:55296
	global_load_lds_dwordx4 v152, s[50:51]
	s_mov_b32 m0, s69
	ds_read_b128 v[208:211], v166 offset:54272
	global_load_lds_dwordx4 v146, s[100:101]
	s_mov_b32 m0, s70
	ds_read_b128 v[204:207], v166 offset:53248
	global_load_lds_dwordx4 v150, s[100:101]
	s_waitcnt vmcnt(8) lgkmcnt(0)
	s_setprio 1
	s_barrier
	v_mfma_f32_16x16x32_bf16 v[74:77], v[132:135], v[188:191], v[74:77]
	v_mfma_f32_16x16x32_bf16 v[70:73], v[140:143], v[188:191], v[70:73]
	v_mfma_f32_16x16x32_bf16 v[46:49], v[132:135], v[196:199], v[46:49]
	v_mfma_f32_16x16x32_bf16 v[42:45], v[140:143], v[196:199], v[42:45]
	v_mfma_f32_16x16x32_bf16 v[30:33], v[132:135], v[204:207], v[30:33]
	v_mfma_f32_16x16x32_bf16 v[26:29], v[140:143], v[204:207], v[26:29]
	v_mfma_f32_16x16x32_bf16 v[14:17], v[132:135], v[212:215], v[14:17]
	v_mfma_f32_16x16x32_bf16 v[10:13], v[140:143], v[212:215], v[10:13]
	v_mfma_f32_16x16x32_bf16 v[74:77], v[136:139], v[192:195], v[74:77]
	v_mfma_f32_16x16x32_bf16 v[70:73], v[168:171], v[192:195], v[70:73]
	v_mfma_f32_16x16x32_bf16 v[46:49], v[136:139], v[200:203], v[46:49]
	v_mfma_f32_16x16x32_bf16 v[42:45], v[168:171], v[200:203], v[42:45]
	v_mfma_f32_16x16x32_bf16 v[30:33], v[136:139], v[208:211], v[30:33]
	v_mfma_f32_16x16x32_bf16 v[26:29], v[168:171], v[208:211], v[26:29]
	v_mfma_f32_16x16x32_bf16 v[14:17], v[136:139], v[216:219], v[14:17]
	v_mfma_f32_16x16x32_bf16 v[10:13], v[168:171], v[216:219], v[10:13]
	s_setprio 0
	s_setprio 1
	v_mfma_f32_16x16x32_bf16 v[66:69], v[172:175], v[188:191], v[66:69]
	v_mfma_f32_16x16x32_bf16 v[58:61], v[180:183], v[188:191], v[58:61]
	v_mfma_f32_16x16x32_bf16 v[38:41], v[172:175], v[196:199], v[38:41]
	v_mfma_f32_16x16x32_bf16 v[34:37], v[180:183], v[196:199], v[34:37]
	v_mfma_f32_16x16x32_bf16 v[22:25], v[172:175], v[204:207], v[22:25]
	v_mfma_f32_16x16x32_bf16 v[18:21], v[180:183], v[204:207], v[18:21]
	v_mfma_f32_16x16x32_bf16 v[6:9], v[172:175], v[212:215], v[6:9]
	v_mfma_f32_16x16x32_bf16 v[2:5], v[180:183], v[212:215], v[2:5]
	v_mfma_f32_16x16x32_bf16 v[66:69], v[176:179], v[192:195], v[66:69]
	v_mfma_f32_16x16x32_bf16 v[58:61], v[184:187], v[192:195], v[58:61]
	v_mfma_f32_16x16x32_bf16 v[38:41], v[176:179], v[200:203], v[38:41]
	v_mfma_f32_16x16x32_bf16 v[34:37], v[184:187], v[200:203], v[34:37]
	v_mfma_f32_16x16x32_bf16 v[22:25], v[176:179], v[208:211], v[22:25]
	v_mfma_f32_16x16x32_bf16 v[18:21], v[184:187], v[208:211], v[18:21]
	v_mfma_f32_16x16x32_bf16 v[6:9], v[176:179], v[216:219], v[6:9]
	v_mfma_f32_16x16x32_bf16 v[2:5], v[184:187], v[216:219], v[2:5]
	s_barrier
	s_setprio 0
	s_add_i32 s26, s26, 2
	s_add_u32 s62, s62, 0x100
	s_addc_u32 s63, s63, 0
	s_add_u32 s14, s14, 0x100
	s_addc_u32 s15, s15, 0
	s_cmp_gt_u32 s26, 5
	s_cbranch_scc0 .LBB0_716
	s_and_b64 vcc, exec, s[16:17]
	s_cbranch_vccz .LBB0_719
	s_barrier

.LBB0_930:
	ds_read_b128 v[134:137], v130
	ds_read_b128 v[138:141], v130 offset:1024
	ds_read_b128 v[142:145], v130 offset:2048
	ds_read_b128 v[146:149], v130 offset:3072
	ds_read_b128 v[168:171], v131
	ds_read_b128 v[174:177], v131 offset:1024
	ds_read_b128 v[178:181], v131 offset:2048
	ds_read_b128 v[182:185], v131 offset:3072
	s_add_u32 s27, s62, 0xfff80080
	s_addc_u32 s50, s63, -1
	s_cmp_eq_u32 s26, 28
	s_cselect_b32 s65, s7, s50
	s_cselect_b32 s64, s6, s27
	s_cselect_b32 s51, s49, s15
	s_cselect_b32 s50, s48, s14
	s_mov_b32 m0, s0
	ds_read_b128 v[186:189], v172
	ds_read_b128 v[190:193], v172 offset:1024
	ds_read_b128 v[194:197], v172 offset:2048
	ds_read_b128 v[198:201], v172 offset:3072
	ds_read_b128 v[202:205], v172 offset:4096
	ds_read_b128 v[206:209], v172 offset:5120
	ds_read_b128 v[210:213], v172 offset:6144
	global_load_lds_dwordx4 v160, s[62:63]
	s_mov_b32 m0, s11
	ds_read_b128 v[214:217], v172 offset:7168
	global_load_lds_dwordx4 v162, s[62:63]
	s_waitcnt vmcnt(8) lgkmcnt(0)
	s_setprio 1
	s_barrier
	v_mfma_f32_16x16x32_bf16 v[126:129], v[134:137], v[186:189], v[126:129]
	v_mfma_f32_16x16x32_bf16 v[122:125], v[142:145], v[186:189], v[122:125]
	v_mfma_f32_16x16x32_bf16 v[118:121], v[134:137], v[194:197], v[118:121]
	v_mfma_f32_16x16x32_bf16 v[114:117], v[142:145], v[194:197], v[114:117]
	v_mfma_f32_16x16x32_bf16 v[110:113], v[134:137], v[202:205], v[110:113]
	v_mfma_f32_16x16x32_bf16 v[106:109], v[142:145], v[202:205], v[106:109]
	v_mfma_f32_16x16x32_bf16 v[102:105], v[134:137], v[210:213], v[102:105]
	v_mfma_f32_16x16x32_bf16 v[98:101], v[142:145], v[210:213], v[98:101]
	v_mfma_f32_16x16x32_bf16 v[126:129], v[138:141], v[190:193], v[126:129]
	v_mfma_f32_16x16x32_bf16 v[122:125], v[146:149], v[190:193], v[122:125]
	v_mfma_f32_16x16x32_bf16 v[118:121], v[138:141], v[198:201], v[118:121]
	v_mfma_f32_16x16x32_bf16 v[114:117], v[146:149], v[198:201], v[114:117]
	v_mfma_f32_16x16x32_bf16 v[110:113], v[138:141], v[206:209], v[110:113]
	v_mfma_f32_16x16x32_bf16 v[106:109], v[146:149], v[206:209], v[106:109]
	v_mfma_f32_16x16x32_bf16 v[102:105], v[138:141], v[214:217], v[102:105]
	v_mfma_f32_16x16x32_bf16 v[98:101], v[146:149], v[214:217], v[98:101]
	s_setprio 0
	s_setprio 1
	v_mfma_f32_16x16x32_bf16 v[94:97], v[168:171], v[186:189], v[94:97]
	v_mfma_f32_16x16x32_bf16 v[90:93], v[178:181], v[186:189], v[90:93]
	v_mfma_f32_16x16x32_bf16 v[86:89], v[168:171], v[194:197], v[86:89]
	v_mfma_f32_16x16x32_bf16 v[82:85], v[178:181], v[194:197], v[82:85]
	v_mfma_f32_16x16x32_bf16 v[78:81], v[168:171], v[202:205], v[78:81]
	v_mfma_f32_16x16x32_bf16 v[74:77], v[178:181], v[202:205], v[74:77]
	v_mfma_f32_16x16x32_bf16 v[70:73], v[168:171], v[210:213], v[70:73]
	v_mfma_f32_16x16x32_bf16 v[66:69], v[178:181], v[210:213], v[66:69]
	v_mfma_f32_16x16x32_bf16 v[94:97], v[174:177], v[190:193], v[94:97]
	v_mfma_f32_16x16x32_bf16 v[90:93], v[182:185], v[190:193], v[90:93]
	v_mfma_f32_16x16x32_bf16 v[86:89], v[174:177], v[198:201], v[86:89]
	v_mfma_f32_16x16x32_bf16 v[82:85], v[182:185], v[198:201], v[82:85]
	v_mfma_f32_16x16x32_bf16 v[78:81], v[174:177], v[206:209], v[78:81]
	v_mfma_f32_16x16x32_bf16 v[74:77], v[182:185], v[206:209], v[74:77]
	v_mfma_f32_16x16x32_bf16 v[70:73], v[174:177], v[214:217], v[70:73]
	v_mfma_f32_16x16x32_bf16 v[66:69], v[182:185], v[214:217], v[66:69]
	s_barrier
	s_setprio 0
	s_mov_b32 m0, s12
	s_mov_b64 s[98:99], s[50:51]
	s_add_u32 s58, s50, 0x80000
	ds_read_b128 v[186:189], v172 offset:16384
	ds_read_b128 v[190:193], v172 offset:17408
	ds_read_b128 v[194:197], v172 offset:18432
	ds_read_b128 v[198:201], v172 offset:19456
	ds_read_b128 v[202:205], v172 offset:20480
	ds_read_b128 v[206:209], v172 offset:21504
	ds_read_b128 v[210:213], v172 offset:22528
	global_load_lds_dwordx4 v152, s[50:51]
	s_mov_b32 m0, s13
	s_addc_u32 s59, s51, 0
	global_load_lds_dwordx4 v156, s[50:51]
	s_mov_b32 m0, s43
	s_mov_b64 s[100:101], s[64:65]
	global_load_lds_dwordx4 v152, s[58:59]
	s_mov_b32 m0, s46
	ds_read_b128 v[214:217], v172 offset:23552
	global_load_lds_dwordx4 v156, s[58:59]
	s_waitcnt vmcnt(6) lgkmcnt(0)
	s_setprio 1
	s_barrier
	v_mfma_f32_16x16x32_bf16 v[62:65], v[134:137], v[186:189], v[62:65]
	v_mfma_f32_16x16x32_bf16 v[58:61], v[142:145], v[186:189], v[58:61]
	v_mfma_f32_16x16x32_bf16 v[54:57], v[134:137], v[194:197], v[54:57]
	v_mfma_f32_16x16x32_bf16 v[50:53], v[142:145], v[194:197], v[50:53]
	v_mfma_f32_16x16x32_bf16 v[46:49], v[134:137], v[202:205], v[46:49]
	v_mfma_f32_16x16x32_bf16 v[42:45], v[142:145], v[202:205], v[42:45]
	v_mfma_f32_16x16x32_bf16 v[38:41], v[134:137], v[210:213], v[38:41]
	v_mfma_f32_16x16x32_bf16 v[34:37], v[142:145], v[210:213], v[34:37]
	v_mfma_f32_16x16x32_bf16 v[62:65], v[138:141], v[190:193], v[62:65]
	v_mfma_f32_16x16x32_bf16 v[58:61], v[146:149], v[190:193], v[58:61]
	v_mfma_f32_16x16x32_bf16 v[54:57], v[138:141], v[198:201], v[54:57]
	v_mfma_f32_16x16x32_bf16 v[50:53], v[146:149], v[198:201], v[50:53]
	v_mfma_f32_16x16x32_bf16 v[46:49], v[138:141], v[206:209], v[46:49]
	v_mfma_f32_16x16x32_bf16 v[42:45], v[146:149], v[206:209], v[42:45]
	v_mfma_f32_16x16x32_bf16 v[38:41], v[138:141], v[214:217], v[38:41]
	v_mfma_f32_16x16x32_bf16 v[34:37], v[146:149], v[214:217], v[34:37]
	s_setprio 0
	s_setprio 1
	v_mfma_f32_16x16x32_bf16 v[30:33], v[168:171], v[186:189], v[30:33]
	v_mfma_f32_16x16x32_bf16 v[26:29], v[178:181], v[186:189], v[26:29]
	v_mfma_f32_16x16x32_bf16 v[22:25], v[168:171], v[194:197], v[22:25]
	v_mfma_f32_16x16x32_bf16 v[18:21], v[178:181], v[194:197], v[18:21]
	v_mfma_f32_16x16x32_bf16 v[14:17], v[168:171], v[202:205], v[14:17]
	v_mfma_f32_16x16x32_bf16 v[10:13], v[178:181], v[202:205], v[10:13]
	v_mfma_f32_16x16x32_bf16 v[6:9], v[168:171], v[210:213], v[6:9]
	v_mfma_f32_16x16x32_bf16 v[2:5], v[178:181], v[210:213], v[2:5]
	v_mfma_f32_16x16x32_bf16 v[30:33], v[174:177], v[190:193], v[30:33]
	v_mfma_f32_16x16x32_bf16 v[26:29], v[182:185], v[190:193], v[26:29]
	v_mfma_f32_16x16x32_bf16 v[22:25], v[174:177], v[198:201], v[22:25]
	v_mfma_f32_16x16x32_bf16 v[18:21], v[182:185], v[198:201], v[18:21]
	v_mfma_f32_16x16x32_bf16 v[14:17], v[174:177], v[206:209], v[14:17]
	v_mfma_f32_16x16x32_bf16 v[10:13], v[182:185], v[206:209], v[10:13]
	v_mfma_f32_16x16x32_bf16 v[6:9], v[174:177], v[214:217], v[6:9]
	v_mfma_f32_16x16x32_bf16 v[2:5], v[182:185], v[214:217], v[2:5]
	s_barrier
; #define PG8_BAR __builtin_amdgcn_s_barrier()
;     ...
;         for (int t = 2; t < nt; t += 2) PG8_KITER(t);
;         if constexpr (ALIGN_EPI) { if (wr == 0) PG8_BAR; }
	s_setprio 0
	ds_read_b128 v[134:137], v132
	ds_read_b128 v[138:141], v132 offset:1024
	ds_read_b128 v[142:145], v132 offset:2048
	ds_read_b128 v[146:149], v132 offset:3072
	ds_read_b128 v[168:171], v133
	ds_read_b128 v[174:177], v133 offset:1024
	s_add_u32 s58, s64, 0x80000
	s_addc_u32 s59, s65, 0
	s_mov_b32 m0, s69
	ds_read_b128 v[182:185], v133 offset:3072
	global_load_lds_dwordx4 v150, s[100:101]
	s_mov_b32 m0, s70
	ds_read_b128 v[178:181], v133 offset:2048
	global_load_lds_dwordx4 v154, s[100:101]
	s_mov_b32 m0, s71
	ds_read_b128 v[186:189], v172 offset:32768
	ds_read_b128 v[190:193], v172 offset:33792
	ds_read_b128 v[194:197], v172 offset:34816
	ds_read_b128 v[198:201], v172 offset:35840
	ds_read_b128 v[202:205], v172 offset:36864
	ds_read_b128 v[206:209], v172 offset:37888
	ds_read_b128 v[210:213], v172 offset:38912
	global_load_lds_dwordx4 v150, s[58:59]
	s_mov_b32 m0, s72
	ds_read_b128 v[214:217], v172 offset:39936
	global_load_lds_dwordx4 v154, s[58:59]
	s_waitcnt vmcnt(8) lgkmcnt(0)
	s_setprio 1
	s_barrier
	v_mfma_f32_16x16x32_bf16 v[126:129], v[134:137], v[186:189], v[126:129]
	v_mfma_f32_16x16x32_bf16 v[122:125], v[142:145], v[186:189], v[122:125]
	v_mfma_f32_16x16x32_bf16 v[118:121], v[134:137], v[194:197], v[118:121]
	v_mfma_f32_16x16x32_bf16 v[114:117], v[142:145], v[194:197], v[114:117]
	v_mfma_f32_16x16x32_bf16 v[110:113], v[134:137], v[202:205], v[110:113]
	v_mfma_f32_16x16x32_bf16 v[106:109], v[142:145], v[202:205], v[106:109]
	v_mfma_f32_16x16x32_bf16 v[102:105], v[134:137], v[210:213], v[102:105]
	v_mfma_f32_16x16x32_bf16 v[98:101], v[142:145], v[210:213], v[98:101]
	v_mfma_f32_16x16x32_bf16 v[126:129], v[138:141], v[190:193], v[126:129]
	v_mfma_f32_16x16x32_bf16 v[122:125], v[146:149], v[190:193], v[122:125]
	v_mfma_f32_16x16x32_bf16 v[118:121], v[138:141], v[198:201], v[118:121]
	v_mfma_f32_16x16x32_bf16 v[114:117], v[146:149], v[198:201], v[114:117]
	v_mfma_f32_16x16x32_bf16 v[110:113], v[138:141], v[206:209], v[110:113]
	v_mfma_f32_16x16x32_bf16 v[106:109], v[146:149], v[206:209], v[106:109]
	v_mfma_f32_16x16x32_bf16 v[102:105], v[138:141], v[214:217], v[102:105]
	v_mfma_f32_16x16x32_bf16 v[98:101], v[146:149], v[214:217], v[98:101]
	s_setprio 0
	s_setprio 1
	v_mfma_f32_16x16x32_bf16 v[94:97], v[168:171], v[186:189], v[94:97]
	v_mfma_f32_16x16x32_bf16 v[90:93], v[178:181], v[186:189], v[90:93]
	v_mfma_f32_16x16x32_bf16 v[86:89], v[168:171], v[194:197], v[86:89]
	v_mfma_f32_16x16x32_bf16 v[82:85], v[178:181], v[194:197], v[82:85]
	v_mfma_f32_16x16x32_bf16 v[78:81], v[168:171], v[202:205], v[78:81]
	v_mfma_f32_16x16x32_bf16 v[74:77], v[178:181], v[202:205], v[74:77]
	v_mfma_f32_16x16x32_bf16 v[70:73], v[168:171], v[210:213], v[70:73]
	v_mfma_f32_16x16x32_bf16 v[66:69], v[178:181], v[210:213], v[66:69]
	v_mfma_f32_16x16x32_bf16 v[94:97], v[174:177], v[190:193], v[94:97]
	v_mfma_f32_16x16x32_bf16 v[90:93], v[182:185], v[190:193], v[90:93]
	v_mfma_f32_16x16x32_bf16 v[86:89], v[174:177], v[198:201], v[86:89]
	v_mfma_f32_16x16x32_bf16 v[82:85], v[182:185], v[198:201], v[82:85]
	v_mfma_f32_16x16x32_bf16 v[78:81], v[174:177], v[206:209], v[78:81]
	v_mfma_f32_16x16x32_bf16 v[74:77], v[182:185], v[206:209], v[74:77]
	v_mfma_f32_16x16x32_bf16 v[70:73], v[174:177], v[214:217], v[70:73]
	v_mfma_f32_16x16x32_bf16 v[66:69], v[182:185], v[214:217], v[66:69]
	s_barrier
	s_setprio 0
	s_mov_b32 m0, s47
	s_add_u32 s98, s98, 0x80
	s_addc_u32 s99, s99, 0
	s_add_u32 s100, s100, 0x80
	s_addc_u32 s101, s101, 0
	s_add_u32 s50, s50, 0x80080
	ds_read_b128 v[186:189], v172 offset:49152
	ds_read_b128 v[190:193], v172 offset:50176
	ds_read_b128 v[194:197], v172 offset:51200
	ds_read_b128 v[198:201], v172 offset:52224
	global_load_lds_dwordx4 v152, s[98:99]
	s_mov_b32 m0, s53
	s_addc_u32 s51, s51, 0
	global_load_lds_dwordx4 v156, s[98:99]
	s_mov_b32 m0, s55
	ds_read_b128 v[214:217], v172 offset:56320
	global_load_lds_dwordx4 v152, s[50:51]
	s_mov_b32 m0, s56
	ds_read_b128 v[210:213], v172 offset:55296
	global_load_lds_dwordx4 v156, s[50:51]
	s_mov_b32 m0, s77
	ds_read_b128 v[206:209], v172 offset:54272
	global_load_lds_dwordx4 v150, s[100:101]
	s_mov_b32 m0, s78
	ds_read_b128 v[202:205], v172 offset:53248
	global_load_lds_dwordx4 v154, s[100:101]
	s_waitcnt vmcnt(8) lgkmcnt(0)
	s_setprio 1
	s_barrier
	v_mfma_f32_16x16x32_bf16 v[62:65], v[134:137], v[186:189], v[62:65]
	v_mfma_f32_16x16x32_bf16 v[58:61], v[142:145], v[186:189], v[58:61]
	v_mfma_f32_16x16x32_bf16 v[54:57], v[134:137], v[194:197], v[54:57]
	v_mfma_f32_16x16x32_bf16 v[50:53], v[142:145], v[194:197], v[50:53]
	v_mfma_f32_16x16x32_bf16 v[46:49], v[134:137], v[202:205], v[46:49]
	v_mfma_f32_16x16x32_bf16 v[42:45], v[142:145], v[202:205], v[42:45]
	v_mfma_f32_16x16x32_bf16 v[38:41], v[134:137], v[210:213], v[38:41]
	v_mfma_f32_16x16x32_bf16 v[34:37], v[142:145], v[210:213], v[34:37]
	v_mfma_f32_16x16x32_bf16 v[62:65], v[138:141], v[190:193], v[62:65]
	v_mfma_f32_16x16x32_bf16 v[58:61], v[146:149], v[190:193], v[58:61]
	v_mfma_f32_16x16x32_bf16 v[54:57], v[138:141], v[198:201], v[54:57]
	v_mfma_f32_16x16x32_bf16 v[50:53], v[146:149], v[198:201], v[50:53]
	v_mfma_f32_16x16x32_bf16 v[46:49], v[138:141], v[206:209], v[46:49]
	v_mfma_f32_16x16x32_bf16 v[42:45], v[146:149], v[206:209], v[42:45]
	v_mfma_f32_16x16x32_bf16 v[38:41], v[138:141], v[214:217], v[38:41]
	v_mfma_f32_16x16x32_bf16 v[34:37], v[146:149], v[214:217], v[34:37]
	s_setprio 0
	s_setprio 1
	v_mfma_f32_16x16x32_bf16 v[30:33], v[168:171], v[186:189], v[30:33]
	v_mfma_f32_16x16x32_bf16 v[26:29], v[178:181], v[186:189], v[26:29]
	v_mfma_f32_16x16x32_bf16 v[22:25], v[168:171], v[194:197], v[22:25]
	v_mfma_f32_16x16x32_bf16 v[18:21], v[178:181], v[194:197], v[18:21]
	v_mfma_f32_16x16x32_bf16 v[14:17], v[168:171], v[202:205], v[14:17]
	v_mfma_f32_16x16x32_bf16 v[10:13], v[178:181], v[202:205], v[10:13]
	v_mfma_f32_16x16x32_bf16 v[6:9], v[168:171], v[210:213], v[6:9]
	v_mfma_f32_16x16x32_bf16 v[2:5], v[178:181], v[210:213], v[2:5]
	v_mfma_f32_16x16x32_bf16 v[30:33], v[174:177], v[190:193], v[30:33]
	v_mfma_f32_16x16x32_bf16 v[26:29], v[182:185], v[190:193], v[26:29]
	v_mfma_f32_16x16x32_bf16 v[22:25], v[174:177], v[198:201], v[22:25]
	v_mfma_f32_16x16x32_bf16 v[18:21], v[182:185], v[198:201], v[18:21]
	v_mfma_f32_16x16x32_bf16 v[14:17], v[174:177], v[206:209], v[14:17]
	v_mfma_f32_16x16x32_bf16 v[10:13], v[182:185], v[206:209], v[10:13]
	v_mfma_f32_16x16x32_bf16 v[6:9], v[174:177], v[214:217], v[6:9]
	v_mfma_f32_16x16x32_bf16 v[2:5], v[182:185], v[214:217], v[2:5]
	s_barrier
	s_setprio 0
	s_add_i32 s26, s26, 2
	s_add_u32 s62, s62, 0x100
	s_addc_u32 s63, s63, 0
	s_add_u32 s14, s14, 0x100
	s_addc_u32 s15, s15, 0
	s_cmp_gt_u32 s26, 29
	s_cbranch_scc0 .LBB0_930
	s_and_b64 vcc, exec, s[18:19]
	s_cbranch_vccz .LBB0_933
	s_barrier

.LBB0_1014:
	ds_read_b128 v[132:135], v182
	ds_read_b128 v[136:139], v182 offset:1024
	ds_read_b128 v[140:143], v182 offset:2048
	ds_read_b128 v[144:147], v182 offset:3072
	ds_read_b128 v[148:151], v183
	ds_read_b128 v[170:173], v183 offset:1024
	ds_read_b128 v[174:177], v183 offset:2048
	ds_read_b128 v[178:181], v183 offset:3072
	s_add_u32 s27, s48, 0xfff00080
	s_addc_u32 s42, s49, -1
	s_cmp_eq_u32 s26, 60
	s_cselect_b32 s51, s29, s42
	s_cselect_b32 s50, s41, s27
	s_cselect_b32 s43, s0, s15
	s_cselect_b32 s42, s68, s14
	s_mov_b32 m0, s61
	ds_read_b128 v[186:189], v184
	ds_read_b128 v[190:193], v184 offset:1024
	ds_read_b128 v[194:197], v184 offset:2048
	ds_read_b128 v[198:201], v184 offset:3072
	ds_read_b128 v[202:205], v184 offset:4096
	ds_read_b128 v[206:209], v184 offset:5120
	ds_read_b128 v[210:213], v184 offset:6144
	global_load_lds_dwordx4 v162, s[48:49]
	s_mov_b32 m0, s62
	ds_read_b128 v[214:217], v184 offset:7168
	global_load_lds_dwordx4 v164, s[48:49]
	s_waitcnt vmcnt(8) lgkmcnt(0)
	s_setprio 1
	s_barrier
	v_mfma_f32_16x16x32_bf16 v[122:125], v[132:135], v[186:189], v[122:125]
	v_mfma_f32_16x16x32_bf16 v[118:121], v[140:143], v[186:189], v[118:121]
	v_mfma_f32_16x16x32_bf16 v[110:113], v[132:135], v[194:197], v[110:113]
	v_mfma_f32_16x16x32_bf16 v[106:109], v[140:143], v[194:197], v[106:109]
	v_mfma_f32_16x16x32_bf16 v[94:97], v[132:135], v[202:205], v[94:97]
	v_mfma_f32_16x16x32_bf16 v[90:93], v[140:143], v[202:205], v[90:93]
	v_mfma_f32_16x16x32_bf16 v[78:81], v[132:135], v[210:213], v[78:81]
	v_mfma_f32_16x16x32_bf16 v[74:77], v[140:143], v[210:213], v[74:77]
	v_mfma_f32_16x16x32_bf16 v[122:125], v[136:139], v[190:193], v[122:125]
	v_mfma_f32_16x16x32_bf16 v[118:121], v[144:147], v[190:193], v[118:121]
	v_mfma_f32_16x16x32_bf16 v[110:113], v[136:139], v[198:201], v[110:113]
	v_mfma_f32_16x16x32_bf16 v[106:109], v[144:147], v[198:201], v[106:109]
	v_mfma_f32_16x16x32_bf16 v[94:97], v[136:139], v[206:209], v[94:97]
	v_mfma_f32_16x16x32_bf16 v[90:93], v[144:147], v[206:209], v[90:93]
	v_mfma_f32_16x16x32_bf16 v[78:81], v[136:139], v[214:217], v[78:81]
	v_mfma_f32_16x16x32_bf16 v[74:77], v[144:147], v[214:217], v[74:77]
	s_setprio 0
	s_setprio 1
	v_mfma_f32_16x16x32_bf16 v[126:129], v[148:151], v[186:189], v[126:129]
	v_mfma_f32_16x16x32_bf16 v[114:117], v[174:177], v[186:189], v[114:117]
	v_mfma_f32_16x16x32_bf16 v[102:105], v[148:151], v[194:197], v[102:105]
	v_mfma_f32_16x16x32_bf16 v[98:101], v[174:177], v[194:197], v[98:101]
	v_mfma_f32_16x16x32_bf16 v[86:89], v[148:151], v[202:205], v[86:89]
	v_mfma_f32_16x16x32_bf16 v[82:85], v[174:177], v[202:205], v[82:85]
	v_mfma_f32_16x16x32_bf16 v[70:73], v[148:151], v[210:213], v[70:73]
	v_mfma_f32_16x16x32_bf16 v[66:69], v[174:177], v[210:213], v[66:69]
	v_mfma_f32_16x16x32_bf16 v[126:129], v[170:173], v[190:193], v[126:129]
	v_mfma_f32_16x16x32_bf16 v[114:117], v[178:181], v[190:193], v[114:117]
	v_mfma_f32_16x16x32_bf16 v[102:105], v[170:173], v[198:201], v[102:105]
	v_mfma_f32_16x16x32_bf16 v[98:101], v[178:181], v[198:201], v[98:101]
	v_mfma_f32_16x16x32_bf16 v[86:89], v[170:173], v[206:209], v[86:89]
	v_mfma_f32_16x16x32_bf16 v[82:85], v[178:181], v[206:209], v[82:85]
	v_mfma_f32_16x16x32_bf16 v[70:73], v[170:173], v[214:217], v[70:73]
	v_mfma_f32_16x16x32_bf16 v[66:69], v[178:181], v[214:217], v[66:69]
	s_barrier
	s_setprio 0
	s_mov_b32 m0, s63
	s_mov_b64 s[98:99], s[42:43]
	s_add_u32 s72, s42, 0x100000
	ds_read_b128 v[186:189], v184 offset:16384
	ds_read_b128 v[190:193], v184 offset:17408
	ds_read_b128 v[194:197], v184 offset:18432
	ds_read_b128 v[198:201], v184 offset:19456
	ds_read_b128 v[202:205], v184 offset:20480
	ds_read_b128 v[206:209], v184 offset:21504
	ds_read_b128 v[210:213], v184 offset:22528
	global_load_lds_dwordx4 v156, s[42:43]
	s_mov_b32 m0, s64
	s_addc_u32 s73, s43, 0
	global_load_lds_dwordx4 v160, s[42:43]
	s_mov_b32 m0, s69
	s_mov_b64 s[100:101], s[50:51]
	global_load_lds_dwordx4 v156, s[72:73]
	s_mov_b32 m0, s46
	ds_read_b128 v[214:217], v184 offset:23552
	global_load_lds_dwordx4 v160, s[72:73]
	s_waitcnt vmcnt(6) lgkmcnt(0)
	s_setprio 1
	s_barrier
	v_mfma_f32_16x16x32_bf16 v[58:61], v[132:135], v[186:189], v[58:61]
	v_mfma_f32_16x16x32_bf16 v[54:57], v[140:143], v[186:189], v[54:57]
	v_mfma_f32_16x16x32_bf16 v[46:49], v[132:135], v[194:197], v[46:49]
	v_mfma_f32_16x16x32_bf16 v[42:45], v[140:143], v[194:197], v[42:45]
	v_mfma_f32_16x16x32_bf16 v[30:33], v[132:135], v[202:205], v[30:33]
	v_mfma_f32_16x16x32_bf16 v[26:29], v[140:143], v[202:205], v[26:29]
	v_mfma_f32_16x16x32_bf16 v[14:17], v[132:135], v[210:213], v[14:17]
	v_mfma_f32_16x16x32_bf16 v[10:13], v[140:143], v[210:213], v[10:13]
	v_mfma_f32_16x16x32_bf16 v[58:61], v[136:139], v[190:193], v[58:61]
	v_mfma_f32_16x16x32_bf16 v[54:57], v[144:147], v[190:193], v[54:57]
	v_mfma_f32_16x16x32_bf16 v[46:49], v[136:139], v[198:201], v[46:49]
	v_mfma_f32_16x16x32_bf16 v[42:45], v[144:147], v[198:201], v[42:45]
	v_mfma_f32_16x16x32_bf16 v[30:33], v[136:139], v[206:209], v[30:33]
	v_mfma_f32_16x16x32_bf16 v[26:29], v[144:147], v[206:209], v[26:29]
	v_mfma_f32_16x16x32_bf16 v[14:17], v[136:139], v[214:217], v[14:17]
	v_mfma_f32_16x16x32_bf16 v[10:13], v[144:147], v[214:217], v[10:13]
	s_setprio 0
	s_setprio 1
	v_mfma_f32_16x16x32_bf16 v[62:65], v[148:151], v[186:189], v[62:65]
	v_mfma_f32_16x16x32_bf16 v[50:53], v[174:177], v[186:189], v[50:53]
	v_mfma_f32_16x16x32_bf16 v[38:41], v[148:151], v[194:197], v[38:41]
	v_mfma_f32_16x16x32_bf16 v[34:37], v[174:177], v[194:197], v[34:37]
	v_mfma_f32_16x16x32_bf16 v[22:25], v[148:151], v[202:205], v[22:25]
	v_mfma_f32_16x16x32_bf16 v[18:21], v[174:177], v[202:205], v[18:21]
	v_mfma_f32_16x16x32_bf16 v[6:9], v[148:151], v[210:213], v[6:9]
	v_mfma_f32_16x16x32_bf16 v[2:5], v[174:177], v[210:213], v[2:5]
	v_mfma_f32_16x16x32_bf16 v[62:65], v[170:173], v[190:193], v[62:65]
	v_mfma_f32_16x16x32_bf16 v[50:53], v[178:181], v[190:193], v[50:53]
	v_mfma_f32_16x16x32_bf16 v[38:41], v[170:173], v[198:201], v[38:41]
	v_mfma_f32_16x16x32_bf16 v[34:37], v[178:181], v[198:201], v[34:37]
	v_mfma_f32_16x16x32_bf16 v[22:25], v[170:173], v[206:209], v[22:25]
	v_mfma_f32_16x16x32_bf16 v[18:21], v[178:181], v[206:209], v[18:21]
	v_mfma_f32_16x16x32_bf16 v[6:9], v[170:173], v[214:217], v[6:9]
	v_mfma_f32_16x16x32_bf16 v[2:5], v[178:181], v[214:217], v[2:5]
	s_barrier
; #define PG8_BAR __builtin_amdgcn_s_barrier()
;     ...
;         for (int t = 2; t < nt; t += 2) PG8_KITER(t);
;         if constexpr (ALIGN_EPI) { if (wr == 0) PG8_BAR; }
	s_setprio 0
	ds_read_b128 v[132:135], v130
	ds_read_b128 v[136:139], v130 offset:1024
	ds_read_b128 v[140:143], v130 offset:2048
	ds_read_b128 v[144:147], v130 offset:3072
	ds_read_b128 v[148:151], v131
	ds_read_b128 v[170:173], v131 offset:1024
	s_add_u32 s50, s50, 0x100000
	s_addc_u32 s51, s51, 0
	s_mov_b32 m0, s13
	ds_read_b128 v[178:181], v131 offset:3072
	global_load_lds_dwordx4 v154, s[100:101]
	s_mov_b32 m0, s33
	ds_read_b128 v[174:177], v131 offset:2048
	global_load_lds_dwordx4 v158, s[100:101]
	s_mov_b32 m0, s52
	ds_read_b128 v[186:189], v184 offset:32768
	ds_read_b128 v[190:193], v184 offset:33792
	ds_read_b128 v[194:197], v184 offset:34816
	ds_read_b128 v[198:201], v184 offset:35840
	ds_read_b128 v[202:205], v184 offset:36864
	ds_read_b128 v[206:209], v184 offset:37888
	ds_read_b128 v[210:213], v184 offset:38912
	global_load_lds_dwordx4 v154, s[50:51]
	s_mov_b32 m0, s53
	ds_read_b128 v[214:217], v184 offset:39936
	global_load_lds_dwordx4 v158, s[50:51]
	s_waitcnt vmcnt(8) lgkmcnt(0)
	s_setprio 1
	s_barrier
	v_mfma_f32_16x16x32_bf16 v[122:125], v[132:135], v[186:189], v[122:125]
	v_mfma_f32_16x16x32_bf16 v[118:121], v[140:143], v[186:189], v[118:121]
	v_mfma_f32_16x16x32_bf16 v[110:113], v[132:135], v[194:197], v[110:113]
	v_mfma_f32_16x16x32_bf16 v[106:109], v[140:143], v[194:197], v[106:109]
	v_mfma_f32_16x16x32_bf16 v[94:97], v[132:135], v[202:205], v[94:97]
	v_mfma_f32_16x16x32_bf16 v[90:93], v[140:143], v[202:205], v[90:93]
	v_mfma_f32_16x16x32_bf16 v[78:81], v[132:135], v[210:213], v[78:81]
	v_mfma_f32_16x16x32_bf16 v[74:77], v[140:143], v[210:213], v[74:77]
	v_mfma_f32_16x16x32_bf16 v[122:125], v[136:139], v[190:193], v[122:125]
	v_mfma_f32_16x16x32_bf16 v[118:121], v[144:147], v[190:193], v[118:121]
	v_mfma_f32_16x16x32_bf16 v[110:113], v[136:139], v[198:201], v[110:113]
	v_mfma_f32_16x16x32_bf16 v[106:109], v[144:147], v[198:201], v[106:109]
	v_mfma_f32_16x16x32_bf16 v[94:97], v[136:139], v[206:209], v[94:97]
	v_mfma_f32_16x16x32_bf16 v[90:93], v[144:147], v[206:209], v[90:93]
	v_mfma_f32_16x16x32_bf16 v[78:81], v[136:139], v[214:217], v[78:81]
	v_mfma_f32_16x16x32_bf16 v[74:77], v[144:147], v[214:217], v[74:77]
	s_setprio 0
	s_setprio 1
	v_mfma_f32_16x16x32_bf16 v[126:129], v[148:151], v[186:189], v[126:129]
	v_mfma_f32_16x16x32_bf16 v[114:117], v[174:177], v[186:189], v[114:117]
	v_mfma_f32_16x16x32_bf16 v[102:105], v[148:151], v[194:197], v[102:105]
	v_mfma_f32_16x16x32_bf16 v[98:101], v[174:177], v[194:197], v[98:101]
	v_mfma_f32_16x16x32_bf16 v[86:89], v[148:151], v[202:205], v[86:89]
	v_mfma_f32_16x16x32_bf16 v[82:85], v[174:177], v[202:205], v[82:85]
	v_mfma_f32_16x16x32_bf16 v[70:73], v[148:151], v[210:213], v[70:73]
	v_mfma_f32_16x16x32_bf16 v[66:69], v[174:177], v[210:213], v[66:69]
	v_mfma_f32_16x16x32_bf16 v[126:129], v[170:173], v[190:193], v[126:129]
	v_mfma_f32_16x16x32_bf16 v[114:117], v[178:181], v[190:193], v[114:117]
	v_mfma_f32_16x16x32_bf16 v[102:105], v[170:173], v[198:201], v[102:105]
	v_mfma_f32_16x16x32_bf16 v[98:101], v[178:181], v[198:201], v[98:101]
	v_mfma_f32_16x16x32_bf16 v[86:89], v[170:173], v[206:209], v[86:89]
	v_mfma_f32_16x16x32_bf16 v[82:85], v[178:181], v[206:209], v[82:85]
	v_mfma_f32_16x16x32_bf16 v[70:73], v[170:173], v[214:217], v[70:73]
	v_mfma_f32_16x16x32_bf16 v[66:69], v[178:181], v[214:217], v[66:69]
	s_barrier
	s_setprio 0
	s_mov_b32 m0, s47
	s_add_u32 s98, s98, 0x80
	s_addc_u32 s99, s99, 0
	s_add_u32 s100, s100, 0x80
	s_addc_u32 s101, s101, 0
	s_add_u32 s42, s42, 0x100080
	ds_read_b128 v[186:189], v184 offset:49152
	ds_read_b128 v[190:193], v184 offset:50176
	ds_read_b128 v[194:197], v184 offset:51200
	ds_read_b128 v[198:201], v184 offset:52224
	global_load_lds_dwordx4 v156, s[98:99]
	s_mov_b32 m0, s70
	s_addc_u32 s43, s43, 0
	global_load_lds_dwordx4 v160, s[98:99]
	s_mov_b32 m0, s56
	ds_read_b128 v[214:217], v184 offset:56320
	global_load_lds_dwordx4 v156, s[42:43]
	s_mov_b32 m0, s57
	ds_read_b128 v[210:213], v184 offset:55296
	global_load_lds_dwordx4 v160, s[42:43]
	s_mov_b32 m0, s54
	ds_read_b128 v[206:209], v184 offset:54272
	global_load_lds_dwordx4 v154, s[100:101]
	s_mov_b32 m0, s55
	ds_read_b128 v[202:205], v184 offset:53248
	global_load_lds_dwordx4 v158, s[100:101]
	s_waitcnt vmcnt(8) lgkmcnt(0)
	s_setprio 1
	s_barrier
	v_mfma_f32_16x16x32_bf16 v[58:61], v[132:135], v[186:189], v[58:61]
	v_mfma_f32_16x16x32_bf16 v[54:57], v[140:143], v[186:189], v[54:57]
	v_mfma_f32_16x16x32_bf16 v[46:49], v[132:135], v[194:197], v[46:49]
	v_mfma_f32_16x16x32_bf16 v[42:45], v[140:143], v[194:197], v[42:45]
	v_mfma_f32_16x16x32_bf16 v[30:33], v[132:135], v[202:205], v[30:33]
	v_mfma_f32_16x16x32_bf16 v[26:29], v[140:143], v[202:205], v[26:29]
	v_mfma_f32_16x16x32_bf16 v[14:17], v[132:135], v[210:213], v[14:17]
	v_mfma_f32_16x16x32_bf16 v[10:13], v[140:143], v[210:213], v[10:13]
	v_mfma_f32_16x16x32_bf16 v[58:61], v[136:139], v[190:193], v[58:61]
	v_mfma_f32_16x16x32_bf16 v[54:57], v[144:147], v[190:193], v[54:57]
	v_mfma_f32_16x16x32_bf16 v[46:49], v[136:139], v[198:201], v[46:49]
	v_mfma_f32_16x16x32_bf16 v[42:45], v[144:147], v[198:201], v[42:45]
	v_mfma_f32_16x16x32_bf16 v[30:33], v[136:139], v[206:209], v[30:33]
	v_mfma_f32_16x16x32_bf16 v[26:29], v[144:147], v[206:209], v[26:29]
	v_mfma_f32_16x16x32_bf16 v[14:17], v[136:139], v[214:217], v[14:17]
	v_mfma_f32_16x16x32_bf16 v[10:13], v[144:147], v[214:217], v[10:13]
	s_setprio 0
	s_setprio 1
	v_mfma_f32_16x16x32_bf16 v[62:65], v[148:151], v[186:189], v[62:65]
	v_mfma_f32_16x16x32_bf16 v[50:53], v[174:177], v[186:189], v[50:53]
	v_mfma_f32_16x16x32_bf16 v[38:41], v[148:151], v[194:197], v[38:41]
	v_mfma_f32_16x16x32_bf16 v[34:37], v[174:177], v[194:197], v[34:37]
	v_mfma_f32_16x16x32_bf16 v[22:25], v[148:151], v[202:205], v[22:25]
	v_mfma_f32_16x16x32_bf16 v[18:21], v[174:177], v[202:205], v[18:21]
	v_mfma_f32_16x16x32_bf16 v[6:9], v[148:151], v[210:213], v[6:9]
	v_mfma_f32_16x16x32_bf16 v[2:5], v[174:177], v[210:213], v[2:5]
	v_mfma_f32_16x16x32_bf16 v[62:65], v[170:173], v[190:193], v[62:65]
	v_mfma_f32_16x16x32_bf16 v[50:53], v[178:181], v[190:193], v[50:53]
	v_mfma_f32_16x16x32_bf16 v[38:41], v[170:173], v[198:201], v[38:41]
	v_mfma_f32_16x16x32_bf16 v[34:37], v[178:181], v[198:201], v[34:37]
	v_mfma_f32_16x16x32_bf16 v[22:25], v[170:173], v[206:209], v[22:25]
	v_mfma_f32_16x16x32_bf16 v[18:21], v[178:181], v[206:209], v[18:21]
	v_mfma_f32_16x16x32_bf16 v[6:9], v[170:173], v[214:217], v[6:9]
	v_mfma_f32_16x16x32_bf16 v[2:5], v[178:181], v[214:217], v[2:5]
	s_barrier
	s_setprio 0
	s_add_i32 s26, s26, 2
	s_add_u32 s48, s48, 0x100
	s_addc_u32 s49, s49, 0
	s_add_u32 s14, s14, 0x100
	s_addc_u32 s15, s15, 0
	s_cmp_gt_u32 s26, 61
	s_cbranch_scc0 .LBB0_1014
	s_and_b64 vcc, exec, s[18:19]
	s_cbranch_vccz .LBB0_1017
	s_barrier

.LBB0_1110:
	ds_read_b128 v[152:155], v148
	ds_read_b128 v[156:159], v148 offset:1024
	ds_read_b128 v[160:163], v148 offset:2048
	ds_read_b128 v[164:167], v148 offset:3072
	ds_read_b128 v[168:171], v149
	ds_read_b128 v[172:175], v149 offset:1024
	ds_read_b128 v[176:179], v149 offset:2048
	ds_read_b128 v[180:183], v149 offset:3072
	s_add_u32 s27, s0, 0xfff00080
	s_addc_u32 s52, s1, -1
	s_cmp_eq_u32 s26, 28
	s_cselect_b32 s55, s43, s52
	s_cselect_b32 s54, s42, s27
	s_cselect_b32 s53, s49, s15
	s_cselect_b32 s52, s48, s14
	s_mov_b32 m0, s41
	ds_read_b128 v[184:187], v150
	ds_read_b128 v[188:191], v150 offset:1024
	ds_read_b128 v[192:195], v150 offset:2048
	ds_read_b128 v[196:199], v150 offset:3072
	ds_read_b128 v[200:203], v150 offset:4096
	ds_read_b128 v[204:207], v150 offset:5120
	ds_read_b128 v[208:211], v150 offset:6144
	global_load_lds_dwordx4 v136, s[0:1]
	s_mov_b32 m0, s73
	ds_read_b128 v[212:215], v150 offset:7168
	global_load_lds_dwordx4 v138, s[0:1]
	s_waitcnt vmcnt(8) lgkmcnt(0)
	s_setprio 1
	s_barrier
	v_mfma_f32_16x16x32_bf16 v[118:121], v[152:155], v[184:187], v[118:121]
	v_mfma_f32_16x16x32_bf16 v[114:117], v[160:163], v[184:187], v[114:117]
	v_mfma_f32_16x16x32_bf16 v[102:105], v[152:155], v[192:195], v[102:105]
	v_mfma_f32_16x16x32_bf16 v[98:101], v[160:163], v[192:195], v[98:101]
	v_mfma_f32_16x16x32_bf16 v[86:89], v[152:155], v[200:203], v[86:89]
	v_mfma_f32_16x16x32_bf16 v[82:85], v[160:163], v[200:203], v[82:85]
	v_mfma_f32_16x16x32_bf16 v[74:77], v[152:155], v[208:211], v[74:77]
	v_mfma_f32_16x16x32_bf16 v[54:57], v[160:163], v[208:211], v[54:57]
	v_mfma_f32_16x16x32_bf16 v[118:121], v[156:159], v[188:191], v[118:121]
	v_mfma_f32_16x16x32_bf16 v[114:117], v[164:167], v[188:191], v[114:117]
	v_mfma_f32_16x16x32_bf16 v[102:105], v[156:159], v[196:199], v[102:105]
	v_mfma_f32_16x16x32_bf16 v[98:101], v[164:167], v[196:199], v[98:101]
	v_mfma_f32_16x16x32_bf16 v[86:89], v[156:159], v[204:207], v[86:89]
	v_mfma_f32_16x16x32_bf16 v[82:85], v[164:167], v[204:207], v[82:85]
	v_mfma_f32_16x16x32_bf16 v[74:77], v[156:159], v[212:215], v[74:77]
	v_mfma_f32_16x16x32_bf16 v[54:57], v[164:167], v[212:215], v[54:57]
	s_setprio 0
	s_setprio 1
	v_mfma_f32_16x16x32_bf16 v[126:129], v[168:171], v[184:187], v[126:129]
	v_mfma_f32_16x16x32_bf16 v[122:125], v[176:179], v[184:187], v[122:125]
	v_mfma_f32_16x16x32_bf16 v[110:113], v[168:171], v[192:195], v[110:113]
	v_mfma_f32_16x16x32_bf16 v[106:109], v[176:179], v[192:195], v[106:109]
	v_mfma_f32_16x16x32_bf16 v[94:97], v[168:171], v[200:203], v[94:97]
	v_mfma_f32_16x16x32_bf16 v[90:93], v[176:179], v[200:203], v[90:93]
	v_mfma_f32_16x16x32_bf16 v[70:73], v[168:171], v[208:211], v[70:73]
	v_mfma_f32_16x16x32_bf16 v[50:53], v[176:179], v[208:211], v[50:53]
	v_mfma_f32_16x16x32_bf16 v[126:129], v[172:175], v[188:191], v[126:129]
	v_mfma_f32_16x16x32_bf16 v[122:125], v[180:183], v[188:191], v[122:125]
	v_mfma_f32_16x16x32_bf16 v[110:113], v[172:175], v[196:199], v[110:113]
	v_mfma_f32_16x16x32_bf16 v[106:109], v[180:183], v[196:199], v[106:109]
	v_mfma_f32_16x16x32_bf16 v[94:97], v[172:175], v[204:207], v[94:97]
	v_mfma_f32_16x16x32_bf16 v[90:93], v[180:183], v[204:207], v[90:93]
	v_mfma_f32_16x16x32_bf16 v[70:73], v[172:175], v[212:215], v[70:73]
	v_mfma_f32_16x16x32_bf16 v[50:53], v[180:183], v[212:215], v[50:53]
	s_barrier
	s_setprio 0
	s_mov_b32 m0, s74
	s_mov_b64 s[98:99], s[52:53]
	s_add_u32 s78, s52, 0x100000
	ds_read_b128 v[184:187], v150 offset:16384
	ds_read_b128 v[188:191], v150 offset:17408
	ds_read_b128 v[192:195], v150 offset:18432
	ds_read_b128 v[196:199], v150 offset:19456
	ds_read_b128 v[200:203], v150 offset:20480
	ds_read_b128 v[204:207], v150 offset:21504
	ds_read_b128 v[208:211], v150 offset:22528
	global_load_lds_dwordx4 v130, s[52:53]
	s_mov_b32 m0, s75
	s_addc_u32 s79, s53, 0
	global_load_lds_dwordx4 v132, s[52:53]
	s_mov_b32 m0, s76
	s_mov_b64 s[100:101], s[54:55]
	global_load_lds_dwordx4 v130, s[78:79]
	s_mov_b32 m0, s46
	ds_read_b128 v[212:215], v150 offset:23552
	global_load_lds_dwordx4 v132, s[78:79]
	s_waitcnt vmcnt(6) lgkmcnt(0)
	s_setprio 1
	s_barrier
	v_mfma_f32_16x16x32_bf16 v[66:69], v[152:155], v[184:187], v[66:69]
	v_mfma_f32_16x16x32_bf16 v[62:65], v[160:163], v[184:187], v[62:65]
	v_mfma_f32_16x16x32_bf16 v[42:45], v[152:155], v[192:195], v[42:45]
	v_mfma_f32_16x16x32_bf16 v[38:41], v[160:163], v[192:195], v[38:41]
	v_mfma_f32_16x16x32_bf16 v[26:29], v[152:155], v[200:203], v[26:29]
	v_mfma_f32_16x16x32_bf16 v[22:25], v[160:163], v[200:203], v[22:25]
	v_mfma_f32_16x16x32_bf16 v[6:9], v[152:155], v[208:211], v[6:9]
	v_mfma_f32_16x16x32_bf16 v[2:5], v[160:163], v[208:211], v[2:5]
	v_mfma_f32_16x16x32_bf16 v[66:69], v[156:159], v[188:191], v[66:69]
	v_mfma_f32_16x16x32_bf16 v[62:65], v[164:167], v[188:191], v[62:65]
	v_mfma_f32_16x16x32_bf16 v[42:45], v[156:159], v[196:199], v[42:45]
	v_mfma_f32_16x16x32_bf16 v[38:41], v[164:167], v[196:199], v[38:41]
	v_mfma_f32_16x16x32_bf16 v[26:29], v[156:159], v[204:207], v[26:29]
	v_mfma_f32_16x16x32_bf16 v[22:25], v[164:167], v[204:207], v[22:25]
	v_mfma_f32_16x16x32_bf16 v[6:9], v[156:159], v[212:215], v[6:9]
	v_mfma_f32_16x16x32_bf16 v[2:5], v[164:167], v[212:215], v[2:5]
	s_setprio 0
	s_setprio 1
	v_mfma_f32_16x16x32_bf16 v[78:81], v[168:171], v[184:187], v[78:81]
	v_mfma_f32_16x16x32_bf16 v[58:61], v[176:179], v[184:187], v[58:61]
	v_mfma_f32_16x16x32_bf16 v[46:49], v[168:171], v[192:195], v[46:49]
	v_mfma_f32_16x16x32_bf16 v[34:37], v[176:179], v[192:195], v[34:37]
	v_mfma_f32_16x16x32_bf16 v[30:33], v[168:171], v[200:203], v[30:33]
	v_mfma_f32_16x16x32_bf16 v[18:21], v[176:179], v[200:203], v[18:21]
	v_mfma_f32_16x16x32_bf16 v[14:17], v[168:171], v[208:211], v[14:17]
	v_mfma_f32_16x16x32_bf16 v[10:13], v[176:179], v[208:211], v[10:13]
	v_mfma_f32_16x16x32_bf16 v[78:81], v[172:175], v[188:191], v[78:81]
	v_mfma_f32_16x16x32_bf16 v[58:61], v[180:183], v[188:191], v[58:61]
	v_mfma_f32_16x16x32_bf16 v[46:49], v[172:175], v[196:199], v[46:49]
	v_mfma_f32_16x16x32_bf16 v[34:37], v[180:183], v[196:199], v[34:37]
	v_mfma_f32_16x16x32_bf16 v[30:33], v[172:175], v[204:207], v[30:33]
	v_mfma_f32_16x16x32_bf16 v[18:21], v[180:183], v[204:207], v[18:21]
	v_mfma_f32_16x16x32_bf16 v[14:17], v[172:175], v[212:215], v[14:17]
	v_mfma_f32_16x16x32_bf16 v[10:13], v[180:183], v[212:215], v[10:13]
	s_barrier
; #define PG8_BAR __builtin_amdgcn_s_barrier()
;     ...
;         for (int t = 2; t < nt; t += 2) PG8_KITER(t);
;         if constexpr (ALIGN_EPI) { if (wr == 0) PG8_BAR; }
	s_setprio 0
	ds_read_b128 v[152:155], v134
	ds_read_b128 v[156:159], v134 offset:1024
	ds_read_b128 v[160:163], v134 offset:2048
	ds_read_b128 v[164:167], v134 offset:3072
	ds_read_b128 v[168:171], v144
	ds_read_b128 v[172:175], v144 offset:1024
	s_add_u32 s54, s54, 0x100000
	s_addc_u32 s55, s55, 0
	s_mov_b32 m0, s33
	ds_read_b128 v[180:183], v144 offset:3072
	global_load_lds_dwordx4 v130, s[100:101]
	s_mov_b32 m0, s51
	ds_read_b128 v[176:179], v144 offset:2048
	global_load_lds_dwordx4 v132, s[100:101]
	s_mov_b32 m0, s58
	ds_read_b128 v[184:187], v150 offset:32768
	ds_read_b128 v[188:191], v150 offset:33792
	ds_read_b128 v[192:195], v150 offset:34816
	ds_read_b128 v[196:199], v150 offset:35840
	ds_read_b128 v[200:203], v150 offset:36864
	ds_read_b128 v[204:207], v150 offset:37888
	ds_read_b128 v[208:211], v150 offset:38912
	global_load_lds_dwordx4 v130, s[54:55]
	s_mov_b32 m0, s59
	ds_read_b128 v[212:215], v150 offset:39936
	global_load_lds_dwordx4 v132, s[54:55]
	s_waitcnt vmcnt(8) lgkmcnt(0)
	s_setprio 1
	s_barrier
	v_mfma_f32_16x16x32_bf16 v[118:121], v[152:155], v[184:187], v[118:121]
	v_mfma_f32_16x16x32_bf16 v[114:117], v[160:163], v[184:187], v[114:117]
	v_mfma_f32_16x16x32_bf16 v[102:105], v[152:155], v[192:195], v[102:105]
	v_mfma_f32_16x16x32_bf16 v[98:101], v[160:163], v[192:195], v[98:101]
	v_mfma_f32_16x16x32_bf16 v[86:89], v[152:155], v[200:203], v[86:89]
	v_mfma_f32_16x16x32_bf16 v[82:85], v[160:163], v[200:203], v[82:85]
	v_mfma_f32_16x16x32_bf16 v[74:77], v[152:155], v[208:211], v[74:77]
	v_mfma_f32_16x16x32_bf16 v[54:57], v[160:163], v[208:211], v[54:57]
	v_mfma_f32_16x16x32_bf16 v[118:121], v[156:159], v[188:191], v[118:121]
	v_mfma_f32_16x16x32_bf16 v[114:117], v[164:167], v[188:191], v[114:117]
	v_mfma_f32_16x16x32_bf16 v[102:105], v[156:159], v[196:199], v[102:105]
	v_mfma_f32_16x16x32_bf16 v[98:101], v[164:167], v[196:199], v[98:101]
	v_mfma_f32_16x16x32_bf16 v[86:89], v[156:159], v[204:207], v[86:89]
	v_mfma_f32_16x16x32_bf16 v[82:85], v[164:167], v[204:207], v[82:85]
	v_mfma_f32_16x16x32_bf16 v[74:77], v[156:159], v[212:215], v[74:77]
	v_mfma_f32_16x16x32_bf16 v[54:57], v[164:167], v[212:215], v[54:57]
	s_setprio 0
	s_setprio 1
	v_mfma_f32_16x16x32_bf16 v[126:129], v[168:171], v[184:187], v[126:129]
	v_mfma_f32_16x16x32_bf16 v[122:125], v[176:179], v[184:187], v[122:125]
	v_mfma_f32_16x16x32_bf16 v[110:113], v[168:171], v[192:195], v[110:113]
	v_mfma_f32_16x16x32_bf16 v[106:109], v[176:179], v[192:195], v[106:109]
	v_mfma_f32_16x16x32_bf16 v[94:97], v[168:171], v[200:203], v[94:97]
	v_mfma_f32_16x16x32_bf16 v[90:93], v[176:179], v[200:203], v[90:93]
	v_mfma_f32_16x16x32_bf16 v[70:73], v[168:171], v[208:211], v[70:73]
	v_mfma_f32_16x16x32_bf16 v[50:53], v[176:179], v[208:211], v[50:53]
	v_mfma_f32_16x16x32_bf16 v[126:129], v[172:175], v[188:191], v[126:129]
	v_mfma_f32_16x16x32_bf16 v[122:125], v[180:183], v[188:191], v[122:125]
	v_mfma_f32_16x16x32_bf16 v[110:113], v[172:175], v[196:199], v[110:113]
	v_mfma_f32_16x16x32_bf16 v[106:109], v[180:183], v[196:199], v[106:109]
	v_mfma_f32_16x16x32_bf16 v[94:97], v[172:175], v[204:207], v[94:97]
	v_mfma_f32_16x16x32_bf16 v[90:93], v[180:183], v[204:207], v[90:93]
	v_mfma_f32_16x16x32_bf16 v[70:73], v[172:175], v[212:215], v[70:73]
	v_mfma_f32_16x16x32_bf16 v[50:53], v[180:183], v[212:215], v[50:53]
	s_barrier
	s_setprio 0
	s_mov_b32 m0, s47
	s_add_u32 s98, s98, 0x80
	s_addc_u32 s99, s99, 0
	s_add_u32 s100, s100, 0x80
	s_addc_u32 s101, s101, 0
	s_add_u32 s52, s52, 0x100080
	ds_read_b128 v[184:187], v150 offset:49152
	ds_read_b128 v[188:191], v150 offset:50176
	ds_read_b128 v[192:195], v150 offset:51200
	ds_read_b128 v[196:199], v150 offset:52224
	global_load_lds_dwordx4 v130, s[98:99]
	s_mov_b32 m0, s77
	s_addc_u32 s53, s53, 0
	global_load_lds_dwordx4 v132, s[98:99]
	s_mov_b32 m0, s56
	ds_read_b128 v[212:215], v150 offset:56320
	global_load_lds_dwordx4 v130, s[52:53]
	s_mov_b32 m0, s57
	ds_read_b128 v[208:211], v150 offset:55296
	global_load_lds_dwordx4 v132, s[52:53]
	s_mov_b32 m0, s61
	ds_read_b128 v[204:207], v150 offset:54272
	global_load_lds_dwordx4 v130, s[100:101]
	s_mov_b32 m0, s62
	ds_read_b128 v[200:203], v150 offset:53248
	global_load_lds_dwordx4 v132, s[100:101]
	s_waitcnt vmcnt(8) lgkmcnt(0)
	s_setprio 1
	s_barrier
	v_mfma_f32_16x16x32_bf16 v[66:69], v[152:155], v[184:187], v[66:69]
	v_mfma_f32_16x16x32_bf16 v[62:65], v[160:163], v[184:187], v[62:65]
	v_mfma_f32_16x16x32_bf16 v[42:45], v[152:155], v[192:195], v[42:45]
	v_mfma_f32_16x16x32_bf16 v[38:41], v[160:163], v[192:195], v[38:41]
	v_mfma_f32_16x16x32_bf16 v[26:29], v[152:155], v[200:203], v[26:29]
	v_mfma_f32_16x16x32_bf16 v[22:25], v[160:163], v[200:203], v[22:25]
	v_mfma_f32_16x16x32_bf16 v[6:9], v[152:155], v[208:211], v[6:9]
	v_mfma_f32_16x16x32_bf16 v[2:5], v[160:163], v[208:211], v[2:5]
	v_mfma_f32_16x16x32_bf16 v[66:69], v[156:159], v[188:191], v[66:69]
	v_mfma_f32_16x16x32_bf16 v[62:65], v[164:167], v[188:191], v[62:65]
	v_mfma_f32_16x16x32_bf16 v[42:45], v[156:159], v[196:199], v[42:45]
	v_mfma_f32_16x16x32_bf16 v[38:41], v[164:167], v[196:199], v[38:41]
	v_mfma_f32_16x16x32_bf16 v[26:29], v[156:159], v[204:207], v[26:29]
	v_mfma_f32_16x16x32_bf16 v[22:25], v[164:167], v[204:207], v[22:25]
	v_mfma_f32_16x16x32_bf16 v[6:9], v[156:159], v[212:215], v[6:9]
	v_mfma_f32_16x16x32_bf16 v[2:5], v[164:167], v[212:215], v[2:5]
	s_setprio 0
	s_setprio 1
	v_mfma_f32_16x16x32_bf16 v[78:81], v[168:171], v[184:187], v[78:81]
	v_mfma_f32_16x16x32_bf16 v[58:61], v[176:179], v[184:187], v[58:61]
	v_mfma_f32_16x16x32_bf16 v[46:49], v[168:171], v[192:195], v[46:49]
	v_mfma_f32_16x16x32_bf16 v[34:37], v[176:179], v[192:195], v[34:37]
	v_mfma_f32_16x16x32_bf16 v[30:33], v[168:171], v[200:203], v[30:33]
	v_mfma_f32_16x16x32_bf16 v[18:21], v[176:179], v[200:203], v[18:21]
	v_mfma_f32_16x16x32_bf16 v[14:17], v[168:171], v[208:211], v[14:17]
	v_mfma_f32_16x16x32_bf16 v[10:13], v[176:179], v[208:211], v[10:13]
	v_mfma_f32_16x16x32_bf16 v[78:81], v[172:175], v[188:191], v[78:81]
	v_mfma_f32_16x16x32_bf16 v[58:61], v[180:183], v[188:191], v[58:61]
	v_mfma_f32_16x16x32_bf16 v[46:49], v[172:175], v[196:199], v[46:49]
	v_mfma_f32_16x16x32_bf16 v[34:37], v[180:183], v[196:199], v[34:37]
	v_mfma_f32_16x16x32_bf16 v[30:33], v[172:175], v[204:207], v[30:33]
	v_mfma_f32_16x16x32_bf16 v[18:21], v[180:183], v[204:207], v[18:21]
	v_mfma_f32_16x16x32_bf16 v[14:17], v[172:175], v[212:215], v[14:17]
	v_mfma_f32_16x16x32_bf16 v[10:13], v[180:183], v[212:215], v[10:13]
	s_barrier
	s_setprio 0
	s_add_i32 s26, s26, 2
	s_add_u32 s0, s0, 0x100
	s_addc_u32 s1, s1, 0
	s_add_u32 s14, s14, 0x100
	s_addc_u32 s15, s15, 0
	s_cmp_gt_u32 s26, 29
	s_cbranch_scc0 .LBB0_1110
	s_and_b64 vcc, exec, s[18:19]
	s_cbranch_vccz .LBB0_1113
	s_barrier

.LBB0_1261:
	ds_read_b128 v[132:135], v182
	ds_read_b128 v[136:139], v182 offset:1024
	ds_read_b128 v[140:143], v182 offset:2048
	ds_read_b128 v[144:147], v182 offset:3072
	ds_read_b128 v[148:151], v183
	ds_read_b128 v[170:173], v183 offset:1024
	ds_read_b128 v[174:177], v183 offset:2048
	ds_read_b128 v[178:181], v183 offset:3072
	s_add_u32 s38, s40, 0xfffe0080
	s_addc_u32 s39, s41, -1
	s_cmp_eq_u32 s69, 4
	s_cselect_b32 s43, s23, s39
	s_cselect_b32 s42, s31, s38
	s_cselect_b32 s39, s0, s27
	s_cselect_b32 s38, s66, s26
	s_mov_b32 m0, s59
	ds_read_b128 v[186:189], v184
	ds_read_b128 v[190:193], v184 offset:1024
	ds_read_b128 v[194:197], v184 offset:2048
	ds_read_b128 v[198:201], v184 offset:3072
	ds_read_b128 v[202:205], v184 offset:4096
	ds_read_b128 v[206:209], v184 offset:5120
	ds_read_b128 v[210:213], v184 offset:6144
	global_load_lds_dwordx4 v162, s[40:41]
	s_mov_b32 m0, s60
	ds_read_b128 v[214:217], v184 offset:7168
	global_load_lds_dwordx4 v164, s[40:41]
	s_waitcnt vmcnt(8) lgkmcnt(0)
	s_setprio 1
	s_barrier
	v_mfma_f32_16x16x32_bf16 v[122:125], v[132:135], v[186:189], v[122:125]
	v_mfma_f32_16x16x32_bf16 v[118:121], v[140:143], v[186:189], v[118:121]
	v_mfma_f32_16x16x32_bf16 v[110:113], v[132:135], v[194:197], v[110:113]
	v_mfma_f32_16x16x32_bf16 v[106:109], v[140:143], v[194:197], v[106:109]
	v_mfma_f32_16x16x32_bf16 v[94:97], v[132:135], v[202:205], v[94:97]
	v_mfma_f32_16x16x32_bf16 v[90:93], v[140:143], v[202:205], v[90:93]
	v_mfma_f32_16x16x32_bf16 v[78:81], v[132:135], v[210:213], v[78:81]
	v_mfma_f32_16x16x32_bf16 v[74:77], v[140:143], v[210:213], v[74:77]
	v_mfma_f32_16x16x32_bf16 v[122:125], v[136:139], v[190:193], v[122:125]
	v_mfma_f32_16x16x32_bf16 v[118:121], v[144:147], v[190:193], v[118:121]
	v_mfma_f32_16x16x32_bf16 v[110:113], v[136:139], v[198:201], v[110:113]
	v_mfma_f32_16x16x32_bf16 v[106:109], v[144:147], v[198:201], v[106:109]
	v_mfma_f32_16x16x32_bf16 v[94:97], v[136:139], v[206:209], v[94:97]
	v_mfma_f32_16x16x32_bf16 v[90:93], v[144:147], v[206:209], v[90:93]
	v_mfma_f32_16x16x32_bf16 v[78:81], v[136:139], v[214:217], v[78:81]
	v_mfma_f32_16x16x32_bf16 v[74:77], v[144:147], v[214:217], v[74:77]
	s_setprio 0
	s_setprio 1
	v_mfma_f32_16x16x32_bf16 v[126:129], v[148:151], v[186:189], v[126:129]
	v_mfma_f32_16x16x32_bf16 v[114:117], v[174:177], v[186:189], v[114:117]
	v_mfma_f32_16x16x32_bf16 v[102:105], v[148:151], v[194:197], v[102:105]
	v_mfma_f32_16x16x32_bf16 v[98:101], v[174:177], v[194:197], v[98:101]
	v_mfma_f32_16x16x32_bf16 v[86:89], v[148:151], v[202:205], v[86:89]
	v_mfma_f32_16x16x32_bf16 v[82:85], v[174:177], v[202:205], v[82:85]
	v_mfma_f32_16x16x32_bf16 v[70:73], v[148:151], v[210:213], v[70:73]
	v_mfma_f32_16x16x32_bf16 v[66:69], v[174:177], v[210:213], v[66:69]
	v_mfma_f32_16x16x32_bf16 v[126:129], v[170:173], v[190:193], v[126:129]
	v_mfma_f32_16x16x32_bf16 v[114:117], v[178:181], v[190:193], v[114:117]
	v_mfma_f32_16x16x32_bf16 v[102:105], v[170:173], v[198:201], v[102:105]
	v_mfma_f32_16x16x32_bf16 v[98:101], v[178:181], v[198:201], v[98:101]
	v_mfma_f32_16x16x32_bf16 v[86:89], v[170:173], v[206:209], v[86:89]
	v_mfma_f32_16x16x32_bf16 v[82:85], v[178:181], v[206:209], v[82:85]
	v_mfma_f32_16x16x32_bf16 v[70:73], v[170:173], v[214:217], v[70:73]
	v_mfma_f32_16x16x32_bf16 v[66:69], v[178:181], v[214:217], v[66:69]
	s_barrier
	s_setprio 0
	s_mov_b32 m0, s61
	s_mov_b64 s[98:99], s[38:39]
	s_add_u32 s70, s38, 0x20000
	ds_read_b128 v[186:189], v184 offset:16384
	ds_read_b128 v[190:193], v184 offset:17408
	ds_read_b128 v[194:197], v184 offset:18432
	ds_read_b128 v[198:201], v184 offset:19456
	ds_read_b128 v[202:205], v184 offset:20480
	ds_read_b128 v[206:209], v184 offset:21504
	ds_read_b128 v[210:213], v184 offset:22528
	global_load_lds_dwordx4 v156, s[38:39]
	s_mov_b32 m0, s62
	s_addc_u32 s71, s39, 0
	global_load_lds_dwordx4 v160, s[38:39]
	s_mov_b32 m0, s67
	s_mov_b64 s[100:101], s[42:43]
	global_load_lds_dwordx4 v156, s[70:71]
	s_mov_b32 m0, s46
	ds_read_b128 v[214:217], v184 offset:23552
	global_load_lds_dwordx4 v160, s[70:71]
	s_waitcnt vmcnt(6) lgkmcnt(0)
	s_setprio 1
	s_barrier
	v_mfma_f32_16x16x32_bf16 v[58:61], v[132:135], v[186:189], v[58:61]
	v_mfma_f32_16x16x32_bf16 v[54:57], v[140:143], v[186:189], v[54:57]
	v_mfma_f32_16x16x32_bf16 v[46:49], v[132:135], v[194:197], v[46:49]
	v_mfma_f32_16x16x32_bf16 v[42:45], v[140:143], v[194:197], v[42:45]
	v_mfma_f32_16x16x32_bf16 v[30:33], v[132:135], v[202:205], v[30:33]
	v_mfma_f32_16x16x32_bf16 v[26:29], v[140:143], v[202:205], v[26:29]
	v_mfma_f32_16x16x32_bf16 v[14:17], v[132:135], v[210:213], v[14:17]
	v_mfma_f32_16x16x32_bf16 v[10:13], v[140:143], v[210:213], v[10:13]
	v_mfma_f32_16x16x32_bf16 v[58:61], v[136:139], v[190:193], v[58:61]
	v_mfma_f32_16x16x32_bf16 v[54:57], v[144:147], v[190:193], v[54:57]
	v_mfma_f32_16x16x32_bf16 v[46:49], v[136:139], v[198:201], v[46:49]
	v_mfma_f32_16x16x32_bf16 v[42:45], v[144:147], v[198:201], v[42:45]
	v_mfma_f32_16x16x32_bf16 v[30:33], v[136:139], v[206:209], v[30:33]
	v_mfma_f32_16x16x32_bf16 v[26:29], v[144:147], v[206:209], v[26:29]
	v_mfma_f32_16x16x32_bf16 v[14:17], v[136:139], v[214:217], v[14:17]
	v_mfma_f32_16x16x32_bf16 v[10:13], v[144:147], v[214:217], v[10:13]
	s_setprio 0
	s_setprio 1
	v_mfma_f32_16x16x32_bf16 v[62:65], v[148:151], v[186:189], v[62:65]
	v_mfma_f32_16x16x32_bf16 v[50:53], v[174:177], v[186:189], v[50:53]
	v_mfma_f32_16x16x32_bf16 v[38:41], v[148:151], v[194:197], v[38:41]
	v_mfma_f32_16x16x32_bf16 v[34:37], v[174:177], v[194:197], v[34:37]
	v_mfma_f32_16x16x32_bf16 v[22:25], v[148:151], v[202:205], v[22:25]
	v_mfma_f32_16x16x32_bf16 v[18:21], v[174:177], v[202:205], v[18:21]
	v_mfma_f32_16x16x32_bf16 v[6:9], v[148:151], v[210:213], v[6:9]
	v_mfma_f32_16x16x32_bf16 v[2:5], v[174:177], v[210:213], v[2:5]
	v_mfma_f32_16x16x32_bf16 v[62:65], v[170:173], v[190:193], v[62:65]
	v_mfma_f32_16x16x32_bf16 v[50:53], v[178:181], v[190:193], v[50:53]
	v_mfma_f32_16x16x32_bf16 v[38:41], v[170:173], v[198:201], v[38:41]
	v_mfma_f32_16x16x32_bf16 v[34:37], v[178:181], v[198:201], v[34:37]
	v_mfma_f32_16x16x32_bf16 v[22:25], v[170:173], v[206:209], v[22:25]
	v_mfma_f32_16x16x32_bf16 v[18:21], v[178:181], v[206:209], v[18:21]
	v_mfma_f32_16x16x32_bf16 v[6:9], v[170:173], v[214:217], v[6:9]
	v_mfma_f32_16x16x32_bf16 v[2:5], v[178:181], v[214:217], v[2:5]
	s_barrier
; #define PG8_BAR __builtin_amdgcn_s_barrier()
;     ...
;         for (int t = 2; t < nt; t += 2) PG8_KITER(t);
;         if constexpr (ALIGN_EPI) { if (wr == 0) PG8_BAR; }
	s_setprio 0
	ds_read_b128 v[132:135], v130
	ds_read_b128 v[136:139], v130 offset:1024
	ds_read_b128 v[140:143], v130 offset:2048
	ds_read_b128 v[144:147], v130 offset:3072
	ds_read_b128 v[148:151], v131
	ds_read_b128 v[170:173], v131 offset:1024
	s_add_u32 s42, s42, 0x20000
	s_addc_u32 s43, s43, 0
	s_mov_b32 m0, s48
	ds_read_b128 v[178:181], v131 offset:3072
	global_load_lds_dwordx4 v154, s[100:101]
	s_mov_b32 m0, s49
	ds_read_b128 v[174:177], v131 offset:2048
	global_load_lds_dwordx4 v158, s[100:101]
	s_mov_b32 m0, s50
	ds_read_b128 v[186:189], v184 offset:32768
	ds_read_b128 v[190:193], v184 offset:33792
	ds_read_b128 v[194:197], v184 offset:34816
	ds_read_b128 v[198:201], v184 offset:35840
	ds_read_b128 v[202:205], v184 offset:36864
	ds_read_b128 v[206:209], v184 offset:37888
	ds_read_b128 v[210:213], v184 offset:38912
	global_load_lds_dwordx4 v154, s[42:43]
	s_mov_b32 m0, s51
	ds_read_b128 v[214:217], v184 offset:39936
	global_load_lds_dwordx4 v158, s[42:43]
	s_waitcnt vmcnt(8) lgkmcnt(0)
	s_setprio 1
	s_barrier
	v_mfma_f32_16x16x32_bf16 v[122:125], v[132:135], v[186:189], v[122:125]
	v_mfma_f32_16x16x32_bf16 v[118:121], v[140:143], v[186:189], v[118:121]
	v_mfma_f32_16x16x32_bf16 v[110:113], v[132:135], v[194:197], v[110:113]
	v_mfma_f32_16x16x32_bf16 v[106:109], v[140:143], v[194:197], v[106:109]
	v_mfma_f32_16x16x32_bf16 v[94:97], v[132:135], v[202:205], v[94:97]
	v_mfma_f32_16x16x32_bf16 v[90:93], v[140:143], v[202:205], v[90:93]
	v_mfma_f32_16x16x32_bf16 v[78:81], v[132:135], v[210:213], v[78:81]
	v_mfma_f32_16x16x32_bf16 v[74:77], v[140:143], v[210:213], v[74:77]
	v_mfma_f32_16x16x32_bf16 v[122:125], v[136:139], v[190:193], v[122:125]
	v_mfma_f32_16x16x32_bf16 v[118:121], v[144:147], v[190:193], v[118:121]
	v_mfma_f32_16x16x32_bf16 v[110:113], v[136:139], v[198:201], v[110:113]
	v_mfma_f32_16x16x32_bf16 v[106:109], v[144:147], v[198:201], v[106:109]
	v_mfma_f32_16x16x32_bf16 v[94:97], v[136:139], v[206:209], v[94:97]
	v_mfma_f32_16x16x32_bf16 v[90:93], v[144:147], v[206:209], v[90:93]
	v_mfma_f32_16x16x32_bf16 v[78:81], v[136:139], v[214:217], v[78:81]
	v_mfma_f32_16x16x32_bf16 v[74:77], v[144:147], v[214:217], v[74:77]
	s_setprio 0
	s_setprio 1
	v_mfma_f32_16x16x32_bf16 v[126:129], v[148:151], v[186:189], v[126:129]
	v_mfma_f32_16x16x32_bf16 v[114:117], v[174:177], v[186:189], v[114:117]
	v_mfma_f32_16x16x32_bf16 v[102:105], v[148:151], v[194:197], v[102:105]
	v_mfma_f32_16x16x32_bf16 v[98:101], v[174:177], v[194:197], v[98:101]
	v_mfma_f32_16x16x32_bf16 v[86:89], v[148:151], v[202:205], v[86:89]
	v_mfma_f32_16x16x32_bf16 v[82:85], v[174:177], v[202:205], v[82:85]
	v_mfma_f32_16x16x32_bf16 v[70:73], v[148:151], v[210:213], v[70:73]
	v_mfma_f32_16x16x32_bf16 v[66:69], v[174:177], v[210:213], v[66:69]
	v_mfma_f32_16x16x32_bf16 v[126:129], v[170:173], v[190:193], v[126:129]
	v_mfma_f32_16x16x32_bf16 v[114:117], v[178:181], v[190:193], v[114:117]
	v_mfma_f32_16x16x32_bf16 v[102:105], v[170:173], v[198:201], v[102:105]
	v_mfma_f32_16x16x32_bf16 v[98:101], v[178:181], v[198:201], v[98:101]
	v_mfma_f32_16x16x32_bf16 v[86:89], v[170:173], v[206:209], v[86:89]
	v_mfma_f32_16x16x32_bf16 v[82:85], v[178:181], v[206:209], v[82:85]
	v_mfma_f32_16x16x32_bf16 v[70:73], v[170:173], v[214:217], v[70:73]
	v_mfma_f32_16x16x32_bf16 v[66:69], v[178:181], v[214:217], v[66:69]
	s_barrier
	s_setprio 0
	s_mov_b32 m0, s47
	s_add_u32 s98, s98, 0x80
	s_addc_u32 s99, s99, 0
	s_add_u32 s100, s100, 0x80
	s_addc_u32 s101, s101, 0
	s_add_u32 s38, s38, 0x20080
	ds_read_b128 v[186:189], v184 offset:49152
	ds_read_b128 v[190:193], v184 offset:50176
	ds_read_b128 v[194:197], v184 offset:51200
	ds_read_b128 v[198:201], v184 offset:52224
	global_load_lds_dwordx4 v156, s[98:99]
	s_mov_b32 m0, s68
	s_addc_u32 s39, s39, 0
	global_load_lds_dwordx4 v160, s[98:99]
	s_mov_b32 m0, s56
	ds_read_b128 v[214:217], v184 offset:56320
	global_load_lds_dwordx4 v156, s[38:39]
	s_mov_b32 m0, s57
	ds_read_b128 v[210:213], v184 offset:55296
	global_load_lds_dwordx4 v160, s[38:39]
	s_mov_b32 m0, s52
	ds_read_b128 v[206:209], v184 offset:54272
	global_load_lds_dwordx4 v154, s[100:101]
	s_mov_b32 m0, s53
	ds_read_b128 v[202:205], v184 offset:53248
	global_load_lds_dwordx4 v158, s[100:101]
	s_waitcnt vmcnt(8) lgkmcnt(0)
	s_setprio 1
	s_barrier
	v_mfma_f32_16x16x32_bf16 v[58:61], v[132:135], v[186:189], v[58:61]
	v_mfma_f32_16x16x32_bf16 v[54:57], v[140:143], v[186:189], v[54:57]
	v_mfma_f32_16x16x32_bf16 v[46:49], v[132:135], v[194:197], v[46:49]
	v_mfma_f32_16x16x32_bf16 v[42:45], v[140:143], v[194:197], v[42:45]
	v_mfma_f32_16x16x32_bf16 v[30:33], v[132:135], v[202:205], v[30:33]
	v_mfma_f32_16x16x32_bf16 v[26:29], v[140:143], v[202:205], v[26:29]
	v_mfma_f32_16x16x32_bf16 v[14:17], v[132:135], v[210:213], v[14:17]
	v_mfma_f32_16x16x32_bf16 v[10:13], v[140:143], v[210:213], v[10:13]
	v_mfma_f32_16x16x32_bf16 v[58:61], v[136:139], v[190:193], v[58:61]
	v_mfma_f32_16x16x32_bf16 v[54:57], v[144:147], v[190:193], v[54:57]
	v_mfma_f32_16x16x32_bf16 v[46:49], v[136:139], v[198:201], v[46:49]
	v_mfma_f32_16x16x32_bf16 v[42:45], v[144:147], v[198:201], v[42:45]
	v_mfma_f32_16x16x32_bf16 v[30:33], v[136:139], v[206:209], v[30:33]
	v_mfma_f32_16x16x32_bf16 v[26:29], v[144:147], v[206:209], v[26:29]
	v_mfma_f32_16x16x32_bf16 v[14:17], v[136:139], v[214:217], v[14:17]
	v_mfma_f32_16x16x32_bf16 v[10:13], v[144:147], v[214:217], v[10:13]
	s_setprio 0
	s_setprio 1
	v_mfma_f32_16x16x32_bf16 v[62:65], v[148:151], v[186:189], v[62:65]
	v_mfma_f32_16x16x32_bf16 v[50:53], v[174:177], v[186:189], v[50:53]
	v_mfma_f32_16x16x32_bf16 v[38:41], v[148:151], v[194:197], v[38:41]
	v_mfma_f32_16x16x32_bf16 v[34:37], v[174:177], v[194:197], v[34:37]
	v_mfma_f32_16x16x32_bf16 v[22:25], v[148:151], v[202:205], v[22:25]
	v_mfma_f32_16x16x32_bf16 v[18:21], v[174:177], v[202:205], v[18:21]
	v_mfma_f32_16x16x32_bf16 v[6:9], v[148:151], v[210:213], v[6:9]
	v_mfma_f32_16x16x32_bf16 v[2:5], v[174:177], v[210:213], v[2:5]
	v_mfma_f32_16x16x32_bf16 v[62:65], v[170:173], v[190:193], v[62:65]
	v_mfma_f32_16x16x32_bf16 v[50:53], v[178:181], v[190:193], v[50:53]
	v_mfma_f32_16x16x32_bf16 v[38:41], v[170:173], v[198:201], v[38:41]
	v_mfma_f32_16x16x32_bf16 v[34:37], v[178:181], v[198:201], v[34:37]
	v_mfma_f32_16x16x32_bf16 v[22:25], v[170:173], v[206:209], v[22:25]
	v_mfma_f32_16x16x32_bf16 v[18:21], v[178:181], v[206:209], v[18:21]
	v_mfma_f32_16x16x32_bf16 v[6:9], v[170:173], v[214:217], v[6:9]
	v_mfma_f32_16x16x32_bf16 v[2:5], v[178:181], v[214:217], v[2:5]
	s_barrier
	s_setprio 0
	s_add_i32 s69, s69, 2
	s_add_u32 s40, s40, 0x100
	s_addc_u32 s41, s41, 0
	s_add_u32 s26, s26, 0x100
	s_addc_u32 s27, s27, 0
	s_cmp_gt_u32 s69, 5
	s_cbranch_scc0 .LBB0_1261
	s_and_b64 vcc, exec, s[16:17]
	s_cbranch_vccz .LBB0_1264
	s_barrier

.LBB0_1345:
	ds_read_b128 v[156:159], v150
	ds_read_b128 v[160:163], v150 offset:1024
	ds_read_b128 v[164:167], v150 offset:2048
	ds_read_b128 v[168:171], v150 offset:3072
	ds_read_b128 v[172:175], v151
	ds_read_b128 v[176:179], v151 offset:1024
	ds_read_b128 v[180:183], v151 offset:2048
	ds_read_b128 v[184:187], v151 offset:3072
	s_add_u32 s38, s40, 0xfff00080
	s_addc_u32 s39, s41, -1
	s_cmp_eq_u32 s68, 60
	s_cselect_b32 s43, s1, s39
	s_cselect_b32 s42, s25, s38
	s_cselect_b32 s39, s8, s27
	s_cselect_b32 s38, s67, s26
	s_mov_b32 m0, s53
	ds_read_b128 v[188:191], v152
	ds_read_b128 v[192:195], v152 offset:1024
	ds_read_b128 v[196:199], v152 offset:2048
	ds_read_b128 v[200:203], v152 offset:3072
	ds_read_b128 v[204:207], v152 offset:4096
	ds_read_b128 v[208:211], v152 offset:5120
	ds_read_b128 v[212:215], v152 offset:6144
	global_load_lds_dwordx4 v0, s[40:41]
	s_mov_b32 m0, s54
	ds_read_b128 v[216:219], v152 offset:7168
	global_load_lds_dwordx4 v140, s[40:41]
	s_waitcnt vmcnt(8) lgkmcnt(0)
	s_setprio 1
	s_barrier
	v_mfma_f32_16x16x32_bf16 v[118:121], v[156:159], v[188:191], v[118:121]
	v_mfma_f32_16x16x32_bf16 v[114:117], v[164:167], v[188:191], v[114:117]
	v_mfma_f32_16x16x32_bf16 v[102:105], v[156:159], v[196:199], v[102:105]
	v_mfma_f32_16x16x32_bf16 v[98:101], v[164:167], v[196:199], v[98:101]
	v_mfma_f32_16x16x32_bf16 v[86:89], v[156:159], v[204:207], v[86:89]
	v_mfma_f32_16x16x32_bf16 v[82:85], v[164:167], v[204:207], v[82:85]
	v_mfma_f32_16x16x32_bf16 v[66:69], v[156:159], v[212:215], v[66:69]
	v_mfma_f32_16x16x32_bf16 v[62:65], v[164:167], v[212:215], v[62:65]
	v_mfma_f32_16x16x32_bf16 v[118:121], v[160:163], v[192:195], v[118:121]
	v_mfma_f32_16x16x32_bf16 v[114:117], v[168:171], v[192:195], v[114:117]
	v_mfma_f32_16x16x32_bf16 v[102:105], v[160:163], v[200:203], v[102:105]
	v_mfma_f32_16x16x32_bf16 v[98:101], v[168:171], v[200:203], v[98:101]
	v_mfma_f32_16x16x32_bf16 v[86:89], v[160:163], v[208:211], v[86:89]
	v_mfma_f32_16x16x32_bf16 v[82:85], v[168:171], v[208:211], v[82:85]
	v_mfma_f32_16x16x32_bf16 v[66:69], v[160:163], v[216:219], v[66:69]
	v_mfma_f32_16x16x32_bf16 v[62:65], v[168:171], v[216:219], v[62:65]
	s_setprio 0
	s_setprio 1
	v_mfma_f32_16x16x32_bf16 v[126:129], v[172:175], v[188:191], v[126:129]
	v_mfma_f32_16x16x32_bf16 v[122:125], v[180:183], v[188:191], v[122:125]
	v_mfma_f32_16x16x32_bf16 v[110:113], v[172:175], v[196:199], v[110:113]
	v_mfma_f32_16x16x32_bf16 v[106:109], v[180:183], v[196:199], v[106:109]
	v_mfma_f32_16x16x32_bf16 v[94:97], v[172:175], v[204:207], v[94:97]
	v_mfma_f32_16x16x32_bf16 v[90:93], v[180:183], v[204:207], v[90:93]
	v_mfma_f32_16x16x32_bf16 v[78:81], v[172:175], v[212:215], v[78:81]
	v_mfma_f32_16x16x32_bf16 v[74:77], v[180:183], v[212:215], v[74:77]
	v_mfma_f32_16x16x32_bf16 v[126:129], v[176:179], v[192:195], v[126:129]
	v_mfma_f32_16x16x32_bf16 v[122:125], v[184:187], v[192:195], v[122:125]
	v_mfma_f32_16x16x32_bf16 v[110:113], v[176:179], v[200:203], v[110:113]
	v_mfma_f32_16x16x32_bf16 v[106:109], v[184:187], v[200:203], v[106:109]
	v_mfma_f32_16x16x32_bf16 v[94:97], v[176:179], v[208:211], v[94:97]
	v_mfma_f32_16x16x32_bf16 v[90:93], v[184:187], v[208:211], v[90:93]
	v_mfma_f32_16x16x32_bf16 v[78:81], v[176:179], v[216:219], v[78:81]
	v_mfma_f32_16x16x32_bf16 v[74:77], v[184:187], v[216:219], v[74:77]
	s_barrier
	s_setprio 0
	s_mov_b32 m0, s59
	s_mov_b64 s[98:99], s[38:39]
	s_add_u32 s70, s38, 0x100000
	ds_read_b128 v[188:191], v152 offset:16384
	ds_read_b128 v[192:195], v152 offset:17408
	ds_read_b128 v[196:199], v152 offset:18432
	ds_read_b128 v[200:203], v152 offset:19456
	ds_read_b128 v[204:207], v152 offset:20480
	ds_read_b128 v[208:211], v152 offset:21504
	ds_read_b128 v[212:215], v152 offset:22528
	global_load_lds_dwordx4 v134, s[38:39]
	s_mov_b32 m0, s60
	s_addc_u32 s71, s39, 0
	global_load_lds_dwordx4 v130, s[38:39]
	s_mov_b32 m0, s61
	s_mov_b64 s[100:101], s[42:43]
	global_load_lds_dwordx4 v134, s[70:71]
	s_mov_b32 m0, s62
	ds_read_b128 v[216:219], v152 offset:23552
	global_load_lds_dwordx4 v130, s[70:71]
	s_waitcnt vmcnt(6) lgkmcnt(0)
	s_setprio 1
	s_barrier
	v_mfma_f32_16x16x32_bf16 v[54:57], v[156:159], v[188:191], v[54:57]
	v_mfma_f32_16x16x32_bf16 v[50:53], v[164:167], v[188:191], v[50:53]
	v_mfma_f32_16x16x32_bf16 v[38:41], v[156:159], v[196:199], v[38:41]
	v_mfma_f32_16x16x32_bf16 v[34:37], v[164:167], v[196:199], v[34:37]
	v_mfma_f32_16x16x32_bf16 v[22:25], v[156:159], v[204:207], v[22:25]
	v_mfma_f32_16x16x32_bf16 v[18:21], v[164:167], v[204:207], v[18:21]
	v_mfma_f32_16x16x32_bf16 v[6:9], v[156:159], v[212:215], v[6:9]
	v_mfma_f32_16x16x32_bf16 v[2:5], v[164:167], v[212:215], v[2:5]
	v_mfma_f32_16x16x32_bf16 v[54:57], v[160:163], v[192:195], v[54:57]
	v_mfma_f32_16x16x32_bf16 v[50:53], v[168:171], v[192:195], v[50:53]
	v_mfma_f32_16x16x32_bf16 v[38:41], v[160:163], v[200:203], v[38:41]
	v_mfma_f32_16x16x32_bf16 v[34:37], v[168:171], v[200:203], v[34:37]
	v_mfma_f32_16x16x32_bf16 v[22:25], v[160:163], v[208:211], v[22:25]
	v_mfma_f32_16x16x32_bf16 v[18:21], v[168:171], v[208:211], v[18:21]
	v_mfma_f32_16x16x32_bf16 v[6:9], v[160:163], v[216:219], v[6:9]
	v_mfma_f32_16x16x32_bf16 v[2:5], v[168:171], v[216:219], v[2:5]
	s_setprio 0
	s_setprio 1
	v_mfma_f32_16x16x32_bf16 v[70:73], v[172:175], v[188:191], v[70:73]
	v_mfma_f32_16x16x32_bf16 v[58:61], v[180:183], v[188:191], v[58:61]
	v_mfma_f32_16x16x32_bf16 v[46:49], v[172:175], v[196:199], v[46:49]
	v_mfma_f32_16x16x32_bf16 v[42:45], v[180:183], v[196:199], v[42:45]
	v_mfma_f32_16x16x32_bf16 v[30:33], v[172:175], v[204:207], v[30:33]
	v_mfma_f32_16x16x32_bf16 v[26:29], v[180:183], v[204:207], v[26:29]
	v_mfma_f32_16x16x32_bf16 v[14:17], v[172:175], v[212:215], v[14:17]
	v_mfma_f32_16x16x32_bf16 v[10:13], v[180:183], v[212:215], v[10:13]
	v_mfma_f32_16x16x32_bf16 v[70:73], v[176:179], v[192:195], v[70:73]
	v_mfma_f32_16x16x32_bf16 v[58:61], v[184:187], v[192:195], v[58:61]
	v_mfma_f32_16x16x32_bf16 v[46:49], v[176:179], v[200:203], v[46:49]
	v_mfma_f32_16x16x32_bf16 v[42:45], v[184:187], v[200:203], v[42:45]
	v_mfma_f32_16x16x32_bf16 v[30:33], v[176:179], v[208:211], v[30:33]
	v_mfma_f32_16x16x32_bf16 v[26:29], v[184:187], v[208:211], v[26:29]
	v_mfma_f32_16x16x32_bf16 v[14:17], v[176:179], v[216:219], v[14:17]
	v_mfma_f32_16x16x32_bf16 v[10:13], v[184:187], v[216:219], v[10:13]
	s_barrier
; #define PG8_BAR __builtin_amdgcn_s_barrier()
;     ...
;         for (int t = 2; t < nt; t += 2) PG8_KITER(t);
;         if constexpr (ALIGN_EPI) { if (wr == 0) PG8_BAR; }
	s_setprio 0
	ds_read_b128 v[156:159], v154
	ds_read_b128 v[160:163], v154 offset:1024
	ds_read_b128 v[164:167], v154 offset:2048
	ds_read_b128 v[168:171], v154 offset:3072
	ds_read_b128 v[172:175], v146
	ds_read_b128 v[176:179], v146 offset:1024
	s_add_u32 s42, s42, 0x100000
	s_addc_u32 s43, s43, 0
	s_mov_b32 m0, s13
	ds_read_b128 v[184:187], v146 offset:3072
	global_load_lds_dwordx4 v136, s[100:101]
	s_mov_b32 m0, s33
	ds_read_b128 v[180:183], v146 offset:2048
	global_load_lds_dwordx4 v132, s[100:101]
	s_mov_b32 m0, s48
	ds_read_b128 v[188:191], v152 offset:32768
	ds_read_b128 v[192:195], v152 offset:33792
	ds_read_b128 v[196:199], v152 offset:34816
	ds_read_b128 v[200:203], v152 offset:35840
	ds_read_b128 v[204:207], v152 offset:36864
	ds_read_b128 v[208:211], v152 offset:37888
	ds_read_b128 v[212:215], v152 offset:38912
	global_load_lds_dwordx4 v136, s[42:43]
	s_mov_b32 m0, s49
	ds_read_b128 v[216:219], v152 offset:39936
	global_load_lds_dwordx4 v132, s[42:43]
	s_waitcnt vmcnt(8) lgkmcnt(0)
	s_setprio 1
	s_barrier
	v_mfma_f32_16x16x32_bf16 v[118:121], v[156:159], v[188:191], v[118:121]
	v_mfma_f32_16x16x32_bf16 v[114:117], v[164:167], v[188:191], v[114:117]
	v_mfma_f32_16x16x32_bf16 v[102:105], v[156:159], v[196:199], v[102:105]
	v_mfma_f32_16x16x32_bf16 v[98:101], v[164:167], v[196:199], v[98:101]
	v_mfma_f32_16x16x32_bf16 v[86:89], v[156:159], v[204:207], v[86:89]
	v_mfma_f32_16x16x32_bf16 v[82:85], v[164:167], v[204:207], v[82:85]
	v_mfma_f32_16x16x32_bf16 v[66:69], v[156:159], v[212:215], v[66:69]
	v_mfma_f32_16x16x32_bf16 v[62:65], v[164:167], v[212:215], v[62:65]
	v_mfma_f32_16x16x32_bf16 v[118:121], v[160:163], v[192:195], v[118:121]
	v_mfma_f32_16x16x32_bf16 v[114:117], v[168:171], v[192:195], v[114:117]
	v_mfma_f32_16x16x32_bf16 v[102:105], v[160:163], v[200:203], v[102:105]
	v_mfma_f32_16x16x32_bf16 v[98:101], v[168:171], v[200:203], v[98:101]
	v_mfma_f32_16x16x32_bf16 v[86:89], v[160:163], v[208:211], v[86:89]
	v_mfma_f32_16x16x32_bf16 v[82:85], v[168:171], v[208:211], v[82:85]
	v_mfma_f32_16x16x32_bf16 v[66:69], v[160:163], v[216:219], v[66:69]
	v_mfma_f32_16x16x32_bf16 v[62:65], v[168:171], v[216:219], v[62:65]
	s_setprio 0
	s_setprio 1
	v_mfma_f32_16x16x32_bf16 v[126:129], v[172:175], v[188:191], v[126:129]
	v_mfma_f32_16x16x32_bf16 v[122:125], v[180:183], v[188:191], v[122:125]
	v_mfma_f32_16x16x32_bf16 v[110:113], v[172:175], v[196:199], v[110:113]
	v_mfma_f32_16x16x32_bf16 v[106:109], v[180:183], v[196:199], v[106:109]
	v_mfma_f32_16x16x32_bf16 v[94:97], v[172:175], v[204:207], v[94:97]
	v_mfma_f32_16x16x32_bf16 v[90:93], v[180:183], v[204:207], v[90:93]
	v_mfma_f32_16x16x32_bf16 v[78:81], v[172:175], v[212:215], v[78:81]
	v_mfma_f32_16x16x32_bf16 v[74:77], v[180:183], v[212:215], v[74:77]
	v_mfma_f32_16x16x32_bf16 v[126:129], v[176:179], v[192:195], v[126:129]
	v_mfma_f32_16x16x32_bf16 v[122:125], v[184:187], v[192:195], v[122:125]
	v_mfma_f32_16x16x32_bf16 v[110:113], v[176:179], v[200:203], v[110:113]
	v_mfma_f32_16x16x32_bf16 v[106:109], v[184:187], v[200:203], v[106:109]
	v_mfma_f32_16x16x32_bf16 v[94:97], v[176:179], v[208:211], v[94:97]
	v_mfma_f32_16x16x32_bf16 v[90:93], v[184:187], v[208:211], v[90:93]
	v_mfma_f32_16x16x32_bf16 v[78:81], v[176:179], v[216:219], v[78:81]
	v_mfma_f32_16x16x32_bf16 v[74:77], v[184:187], v[216:219], v[74:77]
	s_barrier
	s_setprio 0
	s_mov_b32 m0, s46
	s_add_u32 s98, s98, 0x80
	s_addc_u32 s99, s99, 0
	s_add_u32 s100, s100, 0x80
	s_addc_u32 s101, s101, 0
	s_add_u32 s38, s38, 0x100080
	ds_read_b128 v[188:191], v152 offset:49152
	ds_read_b128 v[192:195], v152 offset:50176
	ds_read_b128 v[196:199], v152 offset:51200
	ds_read_b128 v[200:203], v152 offset:52224
	global_load_lds_dwordx4 v134, s[98:99]
	s_mov_b32 m0, s47
	s_addc_u32 s39, s39, 0
	global_load_lds_dwordx4 v130, s[98:99]
	s_mov_b32 m0, s56
	ds_read_b128 v[216:219], v152 offset:56320
	global_load_lds_dwordx4 v134, s[38:39]
	s_mov_b32 m0, s57
	ds_read_b128 v[212:215], v152 offset:55296
	global_load_lds_dwordx4 v130, s[38:39]
	s_mov_b32 m0, s50
	ds_read_b128 v[208:211], v152 offset:54272
	global_load_lds_dwordx4 v136, s[100:101]
	s_mov_b32 m0, s51
	ds_read_b128 v[204:207], v152 offset:53248
	global_load_lds_dwordx4 v132, s[100:101]
	s_waitcnt vmcnt(8) lgkmcnt(0)
	s_setprio 1
	s_barrier
	v_mfma_f32_16x16x32_bf16 v[54:57], v[156:159], v[188:191], v[54:57]
	v_mfma_f32_16x16x32_bf16 v[50:53], v[164:167], v[188:191], v[50:53]
	v_mfma_f32_16x16x32_bf16 v[38:41], v[156:159], v[196:199], v[38:41]
	v_mfma_f32_16x16x32_bf16 v[34:37], v[164:167], v[196:199], v[34:37]
	v_mfma_f32_16x16x32_bf16 v[22:25], v[156:159], v[204:207], v[22:25]
	v_mfma_f32_16x16x32_bf16 v[18:21], v[164:167], v[204:207], v[18:21]
	v_mfma_f32_16x16x32_bf16 v[6:9], v[156:159], v[212:215], v[6:9]
	v_mfma_f32_16x16x32_bf16 v[2:5], v[164:167], v[212:215], v[2:5]
	v_mfma_f32_16x16x32_bf16 v[54:57], v[160:163], v[192:195], v[54:57]
	v_mfma_f32_16x16x32_bf16 v[50:53], v[168:171], v[192:195], v[50:53]
	v_mfma_f32_16x16x32_bf16 v[38:41], v[160:163], v[200:203], v[38:41]
	v_mfma_f32_16x16x32_bf16 v[34:37], v[168:171], v[200:203], v[34:37]
	v_mfma_f32_16x16x32_bf16 v[22:25], v[160:163], v[208:211], v[22:25]
	v_mfma_f32_16x16x32_bf16 v[18:21], v[168:171], v[208:211], v[18:21]
	v_mfma_f32_16x16x32_bf16 v[6:9], v[160:163], v[216:219], v[6:9]
	v_mfma_f32_16x16x32_bf16 v[2:5], v[168:171], v[216:219], v[2:5]
	s_setprio 0
	s_setprio 1
	v_mfma_f32_16x16x32_bf16 v[70:73], v[172:175], v[188:191], v[70:73]
	v_mfma_f32_16x16x32_bf16 v[58:61], v[180:183], v[188:191], v[58:61]
	v_mfma_f32_16x16x32_bf16 v[46:49], v[172:175], v[196:199], v[46:49]
	v_mfma_f32_16x16x32_bf16 v[42:45], v[180:183], v[196:199], v[42:45]
	v_mfma_f32_16x16x32_bf16 v[30:33], v[172:175], v[204:207], v[30:33]
	v_mfma_f32_16x16x32_bf16 v[26:29], v[180:183], v[204:207], v[26:29]
	v_mfma_f32_16x16x32_bf16 v[14:17], v[172:175], v[212:215], v[14:17]
	v_mfma_f32_16x16x32_bf16 v[10:13], v[180:183], v[212:215], v[10:13]
	v_mfma_f32_16x16x32_bf16 v[70:73], v[176:179], v[192:195], v[70:73]
	v_mfma_f32_16x16x32_bf16 v[58:61], v[184:187], v[192:195], v[58:61]
	v_mfma_f32_16x16x32_bf16 v[46:49], v[176:179], v[200:203], v[46:49]
	v_mfma_f32_16x16x32_bf16 v[42:45], v[184:187], v[200:203], v[42:45]
	v_mfma_f32_16x16x32_bf16 v[30:33], v[176:179], v[208:211], v[30:33]
	v_mfma_f32_16x16x32_bf16 v[26:29], v[184:187], v[208:211], v[26:29]
	v_mfma_f32_16x16x32_bf16 v[14:17], v[176:179], v[216:219], v[14:17]
	v_mfma_f32_16x16x32_bf16 v[10:13], v[184:187], v[216:219], v[10:13]
	s_barrier
	s_setprio 0
	s_add_i32 s68, s68, 2
	s_add_u32 s40, s40, 0x100
	s_addc_u32 s41, s41, 0
	s_add_u32 s26, s26, 0x100
	s_addc_u32 s27, s27, 0
	s_cmp_gt_u32 s68, 61
	s_cbranch_scc0 .LBB0_1345
	s_and_b64 vcc, exec, s[18:19]
	s_cbranch_vccz .LBB0_1348
	s_barrier

.LBB0_1425:
	ds_read_b128 v[148:151], v152
	ds_read_b128 v[156:159], v152 offset:1024
	ds_read_b128 v[160:163], v152 offset:2048
	ds_read_b128 v[164:167], v152 offset:3072
	ds_read_b128 v[168:171], v153
	ds_read_b128 v[172:175], v153 offset:1024
	ds_read_b128 v[176:179], v153 offset:2048
	ds_read_b128 v[180:183], v153 offset:3072
	s_add_u32 s20, s18, 0x200
	s_addc_u32 s21, s19, 0
	s_cmpk_eq_i32 s57, 0xa8
	s_cselect_b32 s23, s5, s21
	s_cselect_b32 s22, s4, s20
	s_cselect_b32 s21, s17, s27
	s_cselect_b32 s20, s16, s26
	s_mov_b32 m0, s49
	ds_read_b128 v[184:187], v154
	ds_read_b128 v[188:191], v154 offset:1024
	ds_read_b128 v[192:195], v154 offset:2048
	ds_read_b128 v[196:199], v154 offset:3072
	ds_read_b128 v[200:203], v154 offset:4096
	ds_read_b128 v[204:207], v154 offset:5120
	ds_read_b128 v[208:211], v154 offset:6144
	global_load_lds_dwordx4 v138, s[18:19]
	s_mov_b32 m0, s50
	ds_read_b128 v[212:215], v154 offset:7168
	global_load_lds_dwordx4 v140, s[18:19]
	s_waitcnt vmcnt(8) lgkmcnt(0)
	s_setprio 1
	s_barrier
	v_mfma_f32_16x16x32_bf16 v[126:129], v[148:151], v[184:187], v[126:129]
	v_mfma_f32_16x16x32_bf16 v[122:125], v[160:163], v[184:187], v[122:125]
	v_mfma_f32_16x16x32_bf16 v[110:113], v[148:151], v[192:195], v[110:113]
	v_mfma_f32_16x16x32_bf16 v[106:109], v[160:163], v[192:195], v[106:109]
	v_mfma_f32_16x16x32_bf16 v[94:97], v[148:151], v[200:203], v[94:97]
	v_mfma_f32_16x16x32_bf16 v[90:93], v[160:163], v[200:203], v[90:93]
	v_mfma_f32_16x16x32_bf16 v[78:81], v[148:151], v[208:211], v[78:81]
	v_mfma_f32_16x16x32_bf16 v[74:77], v[160:163], v[208:211], v[74:77]
	v_mfma_f32_16x16x32_bf16 v[126:129], v[156:159], v[188:191], v[126:129]
	v_mfma_f32_16x16x32_bf16 v[122:125], v[164:167], v[188:191], v[122:125]
	v_mfma_f32_16x16x32_bf16 v[110:113], v[156:159], v[196:199], v[110:113]
	v_mfma_f32_16x16x32_bf16 v[106:109], v[164:167], v[196:199], v[106:109]
	v_mfma_f32_16x16x32_bf16 v[94:97], v[156:159], v[204:207], v[94:97]
	v_mfma_f32_16x16x32_bf16 v[90:93], v[164:167], v[204:207], v[90:93]
	v_mfma_f32_16x16x32_bf16 v[78:81], v[156:159], v[212:215], v[78:81]
	v_mfma_f32_16x16x32_bf16 v[74:77], v[164:167], v[212:215], v[74:77]
	s_setprio 0
	s_setprio 1
	v_mfma_f32_16x16x32_bf16 v[118:121], v[168:171], v[184:187], v[118:121]
	v_mfma_f32_16x16x32_bf16 v[114:117], v[176:179], v[184:187], v[114:117]
	v_mfma_f32_16x16x32_bf16 v[102:105], v[168:171], v[192:195], v[102:105]
	v_mfma_f32_16x16x32_bf16 v[98:101], v[176:179], v[192:195], v[98:101]
	v_mfma_f32_16x16x32_bf16 v[86:89], v[168:171], v[200:203], v[86:89]
	v_mfma_f32_16x16x32_bf16 v[82:85], v[176:179], v[200:203], v[82:85]
	v_mfma_f32_16x16x32_bf16 v[70:73], v[168:171], v[208:211], v[70:73]
	v_mfma_f32_16x16x32_bf16 v[66:69], v[176:179], v[208:211], v[66:69]
	v_mfma_f32_16x16x32_bf16 v[118:121], v[172:175], v[188:191], v[118:121]
	v_mfma_f32_16x16x32_bf16 v[114:117], v[180:183], v[188:191], v[114:117]
	v_mfma_f32_16x16x32_bf16 v[102:105], v[172:175], v[196:199], v[102:105]
	v_mfma_f32_16x16x32_bf16 v[98:101], v[180:183], v[196:199], v[98:101]
	v_mfma_f32_16x16x32_bf16 v[86:89], v[172:175], v[204:207], v[86:89]
	v_mfma_f32_16x16x32_bf16 v[82:85], v[180:183], v[204:207], v[82:85]
	v_mfma_f32_16x16x32_bf16 v[70:73], v[172:175], v[212:215], v[70:73]
	v_mfma_f32_16x16x32_bf16 v[66:69], v[180:183], v[212:215], v[66:69]
	s_barrier
	s_setprio 0
	s_mov_b32 m0, s51
	s_mov_b64 s[98:99], s[20:21]
	s_add_u32 s58, s20, 0x2b0000
	ds_read_b128 v[184:187], v154 offset:16384
	ds_read_b128 v[188:191], v154 offset:17408
	ds_read_b128 v[192:195], v154 offset:18432
	ds_read_b128 v[196:199], v154 offset:19456
	ds_read_b128 v[200:203], v154 offset:20480
	ds_read_b128 v[204:207], v154 offset:21504
	ds_read_b128 v[208:211], v154 offset:22528
	global_load_lds_dwordx4 v132, s[20:21]
	s_mov_b32 m0, s52
	s_addc_u32 s59, s21, 0
	global_load_lds_dwordx4 v136, s[20:21]
	s_mov_b32 m0, s46
	s_mov_b64 s[100:101], s[22:23]
	global_load_lds_dwordx4 v132, s[58:59]
	s_mov_b32 m0, s47
	ds_read_b128 v[212:215], v154 offset:23552
	global_load_lds_dwordx4 v136, s[58:59]
	s_waitcnt vmcnt(6) lgkmcnt(0)
	s_setprio 1
	s_barrier
	v_mfma_f32_16x16x32_bf16 v[62:65], v[148:151], v[184:187], v[62:65]
	v_mfma_f32_16x16x32_bf16 v[58:61], v[160:163], v[184:187], v[58:61]
	v_mfma_f32_16x16x32_bf16 v[46:49], v[148:151], v[192:195], v[46:49]
	v_mfma_f32_16x16x32_bf16 v[42:45], v[160:163], v[192:195], v[42:45]
	v_mfma_f32_16x16x32_bf16 v[30:33], v[148:151], v[200:203], v[30:33]
	v_mfma_f32_16x16x32_bf16 v[26:29], v[160:163], v[200:203], v[26:29]
	v_mfma_f32_16x16x32_bf16 v[14:17], v[148:151], v[208:211], v[14:17]
	v_mfma_f32_16x16x32_bf16 v[10:13], v[160:163], v[208:211], v[10:13]
	v_mfma_f32_16x16x32_bf16 v[62:65], v[156:159], v[188:191], v[62:65]
	v_mfma_f32_16x16x32_bf16 v[58:61], v[164:167], v[188:191], v[58:61]
	v_mfma_f32_16x16x32_bf16 v[46:49], v[156:159], v[196:199], v[46:49]
	v_mfma_f32_16x16x32_bf16 v[42:45], v[164:167], v[196:199], v[42:45]
	v_mfma_f32_16x16x32_bf16 v[30:33], v[156:159], v[204:207], v[30:33]
	v_mfma_f32_16x16x32_bf16 v[26:29], v[164:167], v[204:207], v[26:29]
	v_mfma_f32_16x16x32_bf16 v[14:17], v[156:159], v[212:215], v[14:17]
	v_mfma_f32_16x16x32_bf16 v[10:13], v[164:167], v[212:215], v[10:13]
	s_setprio 0
	s_setprio 1
	v_mfma_f32_16x16x32_bf16 v[54:57], v[168:171], v[184:187], v[54:57]
	v_mfma_f32_16x16x32_bf16 v[50:53], v[176:179], v[184:187], v[50:53]
	v_mfma_f32_16x16x32_bf16 v[38:41], v[168:171], v[192:195], v[38:41]
	v_mfma_f32_16x16x32_bf16 v[34:37], v[176:179], v[192:195], v[34:37]
	v_mfma_f32_16x16x32_bf16 v[22:25], v[168:171], v[200:203], v[22:25]
	v_mfma_f32_16x16x32_bf16 v[18:21], v[176:179], v[200:203], v[18:21]
	v_mfma_f32_16x16x32_bf16 v[6:9], v[168:171], v[208:211], v[6:9]
	v_mfma_f32_16x16x32_bf16 v[2:5], v[176:179], v[208:211], v[2:5]
	v_mfma_f32_16x16x32_bf16 v[54:57], v[172:175], v[188:191], v[54:57]
	v_mfma_f32_16x16x32_bf16 v[50:53], v[180:183], v[188:191], v[50:53]
	v_mfma_f32_16x16x32_bf16 v[38:41], v[172:175], v[196:199], v[38:41]
	v_mfma_f32_16x16x32_bf16 v[34:37], v[180:183], v[196:199], v[34:37]
	v_mfma_f32_16x16x32_bf16 v[22:25], v[172:175], v[204:207], v[22:25]
	v_mfma_f32_16x16x32_bf16 v[18:21], v[180:183], v[204:207], v[18:21]
	v_mfma_f32_16x16x32_bf16 v[6:9], v[172:175], v[212:215], v[6:9]
	v_mfma_f32_16x16x32_bf16 v[2:5], v[180:183], v[212:215], v[2:5]
	s_barrier
; #define PG8_BAR __builtin_amdgcn_s_barrier()
;     ...
;         for (int t = 2; t < nt; t += 2) PG8_KITER(t);
;         if constexpr (ALIGN_EPI) { if (wr == 0) PG8_BAR; }
	s_setprio 0
	ds_read_b128 v[148:151], v146
	ds_read_b128 v[156:159], v146 offset:1024
	ds_read_b128 v[160:163], v146 offset:2048
	ds_read_b128 v[164:167], v146 offset:3072
	ds_read_b128 v[168:171], v147
	ds_read_b128 v[172:175], v147 offset:1024
	s_add_u32 s22, s22, 0x2b0000
	s_addc_u32 s23, s23, 0
	s_mov_b32 m0, s28
	ds_read_b128 v[180:183], v147 offset:3072
	global_load_lds_dwordx4 v130, s[100:101]
	s_mov_b32 m0, s29
	ds_read_b128 v[176:179], v147 offset:2048
	global_load_lds_dwordx4 v134, s[100:101]
	s_mov_b32 m0, s30
	ds_read_b128 v[184:187], v154 offset:32768
	ds_read_b128 v[188:191], v154 offset:33792
	ds_read_b128 v[192:195], v154 offset:34816
	ds_read_b128 v[196:199], v154 offset:35840
	ds_read_b128 v[200:203], v154 offset:36864
	ds_read_b128 v[204:207], v154 offset:37888
	ds_read_b128 v[208:211], v154 offset:38912
	global_load_lds_dwordx4 v130, s[22:23]
	s_mov_b32 m0, s31
	ds_read_b128 v[212:215], v154 offset:39936
	global_load_lds_dwordx4 v134, s[22:23]
	s_waitcnt vmcnt(8) lgkmcnt(0)
	s_setprio 1
	s_barrier
	v_mfma_f32_16x16x32_bf16 v[126:129], v[148:151], v[184:187], v[126:129]
	v_mfma_f32_16x16x32_bf16 v[122:125], v[160:163], v[184:187], v[122:125]
	v_mfma_f32_16x16x32_bf16 v[110:113], v[148:151], v[192:195], v[110:113]
	v_mfma_f32_16x16x32_bf16 v[106:109], v[160:163], v[192:195], v[106:109]
	v_mfma_f32_16x16x32_bf16 v[94:97], v[148:151], v[200:203], v[94:97]
	v_mfma_f32_16x16x32_bf16 v[90:93], v[160:163], v[200:203], v[90:93]
	v_mfma_f32_16x16x32_bf16 v[78:81], v[148:151], v[208:211], v[78:81]
	v_mfma_f32_16x16x32_bf16 v[74:77], v[160:163], v[208:211], v[74:77]
	v_mfma_f32_16x16x32_bf16 v[126:129], v[156:159], v[188:191], v[126:129]
	v_mfma_f32_16x16x32_bf16 v[122:125], v[164:167], v[188:191], v[122:125]
	v_mfma_f32_16x16x32_bf16 v[110:113], v[156:159], v[196:199], v[110:113]
	v_mfma_f32_16x16x32_bf16 v[106:109], v[164:167], v[196:199], v[106:109]
	v_mfma_f32_16x16x32_bf16 v[94:97], v[156:159], v[204:207], v[94:97]
	v_mfma_f32_16x16x32_bf16 v[90:93], v[164:167], v[204:207], v[90:93]
	v_mfma_f32_16x16x32_bf16 v[78:81], v[156:159], v[212:215], v[78:81]
	v_mfma_f32_16x16x32_bf16 v[74:77], v[164:167], v[212:215], v[74:77]
	s_setprio 0
	s_setprio 1
	v_mfma_f32_16x16x32_bf16 v[118:121], v[168:171], v[184:187], v[118:121]
	v_mfma_f32_16x16x32_bf16 v[114:117], v[176:179], v[184:187], v[114:117]
	v_mfma_f32_16x16x32_bf16 v[102:105], v[168:171], v[192:195], v[102:105]
	v_mfma_f32_16x16x32_bf16 v[98:101], v[176:179], v[192:195], v[98:101]
	v_mfma_f32_16x16x32_bf16 v[86:89], v[168:171], v[200:203], v[86:89]
	v_mfma_f32_16x16x32_bf16 v[82:85], v[176:179], v[200:203], v[82:85]
	v_mfma_f32_16x16x32_bf16 v[70:73], v[168:171], v[208:211], v[70:73]
	v_mfma_f32_16x16x32_bf16 v[66:69], v[176:179], v[208:211], v[66:69]
	v_mfma_f32_16x16x32_bf16 v[118:121], v[172:175], v[188:191], v[118:121]
	v_mfma_f32_16x16x32_bf16 v[114:117], v[180:183], v[188:191], v[114:117]
	v_mfma_f32_16x16x32_bf16 v[102:105], v[172:175], v[196:199], v[102:105]
	v_mfma_f32_16x16x32_bf16 v[98:101], v[180:183], v[196:199], v[98:101]
	v_mfma_f32_16x16x32_bf16 v[86:89], v[172:175], v[204:207], v[86:89]
	v_mfma_f32_16x16x32_bf16 v[82:85], v[180:183], v[204:207], v[82:85]
	v_mfma_f32_16x16x32_bf16 v[70:73], v[172:175], v[212:215], v[70:73]
	v_mfma_f32_16x16x32_bf16 v[66:69], v[180:183], v[212:215], v[66:69]
	s_barrier
	s_setprio 0
	s_mov_b32 m0, s53
	s_add_u32 s98, s98, 0x80
	s_addc_u32 s99, s99, 0
	s_add_u32 s100, s100, 0x80
	s_addc_u32 s101, s101, 0
	s_add_u32 s20, s20, 0x2b0080
	ds_read_b128 v[184:187], v154 offset:49152
	ds_read_b128 v[188:191], v154 offset:50176
	ds_read_b128 v[192:195], v154 offset:51200
	ds_read_b128 v[196:199], v154 offset:52224
	global_load_lds_dwordx4 v132, s[98:99]
	s_mov_b32 m0, s54
	s_addc_u32 s21, s21, 0
	global_load_lds_dwordx4 v136, s[98:99]
	s_mov_b32 m0, s55
	ds_read_b128 v[212:215], v154 offset:56320
	global_load_lds_dwordx4 v132, s[20:21]
	s_mov_b32 m0, s56
	ds_read_b128 v[208:211], v154 offset:55296
	global_load_lds_dwordx4 v136, s[20:21]
	s_mov_b32 m0, s34
	ds_read_b128 v[204:207], v154 offset:54272
	global_load_lds_dwordx4 v130, s[100:101]
	s_mov_b32 m0, s35
	ds_read_b128 v[200:203], v154 offset:53248
	global_load_lds_dwordx4 v134, s[100:101]
	s_waitcnt vmcnt(8) lgkmcnt(0)
	s_setprio 1
	s_barrier
	v_mfma_f32_16x16x32_bf16 v[62:65], v[148:151], v[184:187], v[62:65]
	v_mfma_f32_16x16x32_bf16 v[58:61], v[160:163], v[184:187], v[58:61]
	v_mfma_f32_16x16x32_bf16 v[46:49], v[148:151], v[192:195], v[46:49]
	v_mfma_f32_16x16x32_bf16 v[42:45], v[160:163], v[192:195], v[42:45]
	v_mfma_f32_16x16x32_bf16 v[30:33], v[148:151], v[200:203], v[30:33]
	v_mfma_f32_16x16x32_bf16 v[26:29], v[160:163], v[200:203], v[26:29]
	v_mfma_f32_16x16x32_bf16 v[14:17], v[148:151], v[208:211], v[14:17]
	v_mfma_f32_16x16x32_bf16 v[10:13], v[160:163], v[208:211], v[10:13]
	v_mfma_f32_16x16x32_bf16 v[62:65], v[156:159], v[188:191], v[62:65]
	v_mfma_f32_16x16x32_bf16 v[58:61], v[164:167], v[188:191], v[58:61]
	v_mfma_f32_16x16x32_bf16 v[46:49], v[156:159], v[196:199], v[46:49]
	v_mfma_f32_16x16x32_bf16 v[42:45], v[164:167], v[196:199], v[42:45]
	v_mfma_f32_16x16x32_bf16 v[30:33], v[156:159], v[204:207], v[30:33]
	v_mfma_f32_16x16x32_bf16 v[26:29], v[164:167], v[204:207], v[26:29]
	v_mfma_f32_16x16x32_bf16 v[14:17], v[156:159], v[212:215], v[14:17]
	v_mfma_f32_16x16x32_bf16 v[10:13], v[164:167], v[212:215], v[10:13]
	s_setprio 0
	s_setprio 1
	v_mfma_f32_16x16x32_bf16 v[54:57], v[168:171], v[184:187], v[54:57]
	v_mfma_f32_16x16x32_bf16 v[50:53], v[176:179], v[184:187], v[50:53]
	v_mfma_f32_16x16x32_bf16 v[38:41], v[168:171], v[192:195], v[38:41]
	v_mfma_f32_16x16x32_bf16 v[34:37], v[176:179], v[192:195], v[34:37]
	v_mfma_f32_16x16x32_bf16 v[22:25], v[168:171], v[200:203], v[22:25]
	v_mfma_f32_16x16x32_bf16 v[18:21], v[176:179], v[200:203], v[18:21]
	v_mfma_f32_16x16x32_bf16 v[6:9], v[168:171], v[208:211], v[6:9]
	v_mfma_f32_16x16x32_bf16 v[2:5], v[176:179], v[208:211], v[2:5]
	v_mfma_f32_16x16x32_bf16 v[54:57], v[172:175], v[188:191], v[54:57]
	v_mfma_f32_16x16x32_bf16 v[50:53], v[180:183], v[188:191], v[50:53]
	v_mfma_f32_16x16x32_bf16 v[38:41], v[172:175], v[196:199], v[38:41]
	v_mfma_f32_16x16x32_bf16 v[34:37], v[180:183], v[196:199], v[34:37]
	v_mfma_f32_16x16x32_bf16 v[22:25], v[172:175], v[204:207], v[22:25]
	v_mfma_f32_16x16x32_bf16 v[18:21], v[180:183], v[204:207], v[18:21]
	v_mfma_f32_16x16x32_bf16 v[6:9], v[172:175], v[212:215], v[6:9]
	v_mfma_f32_16x16x32_bf16 v[2:5], v[180:183], v[212:215], v[2:5]
	s_barrier
	s_setprio 0
	s_add_i32 s57, s57, 2
	s_add_u32 s18, s18, 0x100
	s_addc_u32 s19, s19, 0
	s_add_u32 s26, s26, 0x100
	s_addc_u32 s27, s27, 0
	s_cmpk_gt_u32 s57, 0xa9
	s_cbranch_scc0 .LBB0_1425
	s_and_b64 vcc, exec, s[10:11]
	s_cbranch_vccz .LBB0_1428
	s_barrier
